# all 16-byte global stores made write-through (sc1) so the per-phase L2 write-back at the grid barrier finds little dirty data
# speedup vs baseline: 1.0043x; 1.0043x over previous
.LBB0_22:
	s_waitcnt vmcnt(16)
	s_waitcnt vmcnt(0)
	ds_write2_b32 v31, v27, v44 offset1:66
	ds_write2_b32 v31, v45, v46 offset0:132 offset1:198
	ds_write2_b32 v37, v47, v48 offset0:8 offset1:74
	ds_write2_b32 v37, v49, v50 offset0:140 offset1:206
	ds_write2_b32 v38, v51, v52 offset0:16 offset1:82
	ds_write2_b32 v38, v53, v54 offset0:148 offset1:214
	ds_write2_b32 v39, v55, v56 offset0:24 offset1:90
	ds_write2_b32 v39, v57, v58 offset0:156 offset1:222
	ds_write2_b32 v40, v59, v60 offset0:32 offset1:98
	ds_write2_b32 v40, v61, v62 offset0:164 offset1:230
	ds_write2_b32 v41, v63, v64 offset0:40 offset1:106
	ds_write2_b32 v41, v65, v66 offset0:172 offset1:238
	ds_write2_b32 v42, v67, v68 offset0:48 offset1:114
	ds_write2_b32 v42, v69, v70 offset0:180 offset1:246
	ds_write2_b32 v43, v71, v72 offset0:56 offset1:122
	ds_write2_b32 v43, v73, v74 offset0:188 offset1:254
	s_waitcnt lgkmcnt(0)
	ds_read2_b32 v[48:49], v33 offset1:8
	ds_read2_b32 v[50:51], v33 offset0:33 offset1:41
	ds_read2_b32 v[54:55], v33 offset0:66 offset1:74
	ds_read2_b32 v[56:57], v33 offset0:99 offset1:107
	ds_read2_b32 v[58:59], v33 offset0:132 offset1:140
	ds_read2_b32 v[60:61], v33 offset0:165 offset1:173
	ds_read2_b32 v[62:63], v33 offset0:198 offset1:206
	ds_read2_b32 v[64:65], v33 offset0:231 offset1:239
	s_waitcnt lgkmcnt(7)
	v_mov_b32_e32 v44, v48
	s_waitcnt lgkmcnt(6)
	v_mov_b32_e32 v45, v50
	s_waitcnt lgkmcnt(5)
	v_mov_b32_e32 v46, v54
	s_waitcnt lgkmcnt(4)
	v_mov_b32_e32 v47, v56
	v_pk_mul_f32 v[44:45], v[4:5], v[44:45]
	v_pk_mul_f32 v[46:47], v[6:7], v[46:47]
	v_cvt_pk_bf16_f32 v44, v44, v45
	v_cvt_pk_bf16_f32 v45, v46, v47
	s_waitcnt lgkmcnt(3)
	v_mov_b32_e32 v46, v58
	s_waitcnt lgkmcnt(2)
	v_mov_b32_e32 v47, v60
	s_waitcnt lgkmcnt(1)
	v_mov_b32_e32 v66, v62
	s_waitcnt lgkmcnt(0)
	v_mov_b32_e32 v67, v64
	v_pk_mul_f32 v[46:47], v[0:1], v[46:47]
	v_pk_mul_f32 v[66:67], v[2:3], v[66:67]
	v_cvt_pk_bf16_f32 v46, v46, v47
	v_cvt_pk_bf16_f32 v47, v66, v67
	v_add_u32_e32 v66, s16, v32
	v_ashrrev_i32_e32 v67, 31, v66
	v_lshl_add_u64 v[52:53], s[26:27], 1, v[20:21]
	v_lshlrev_b64 v[68:69], 11, v[66:67]
	v_lshl_add_u64 v[68:69], v[52:53], 0, v[68:69]
	v_mov_b32_e32 v50, v49
	v_mov_b32_e32 v56, v55
	global_store_dwordx4 v[68:69], v[44:47], off sc1
	v_mov_b32_e32 v60, v59
	v_mov_b32_e32 v64, v63
	v_pk_mul_f32 v[44:45], v[4:5], v[50:51]
	v_pk_mul_f32 v[46:47], v[6:7], v[56:57]
	v_cvt_pk_bf16_f32 v44, v44, v45
	v_cvt_pk_bf16_f32 v45, v46, v47
	v_pk_mul_f32 v[46:47], v[0:1], v[60:61]
	v_pk_mul_f32 v[48:49], v[2:3], v[64:65]
	v_cvt_pk_bf16_f32 v46, v46, v47
	v_cvt_pk_bf16_f32 v47, v48, v49
	v_add_u32_e32 v48, 8, v66
	v_ashrrev_i32_e32 v49, 31, v48
	v_lshlrev_b64 v[48:49], 11, v[48:49]
	v_lshl_add_u64 v[48:49], v[52:53], 0, v[48:49]
	ds_read2_b32 v[50:51], v33 offset0:16 offset1:24
	ds_read2_b32 v[54:55], v33 offset0:49 offset1:57
	global_store_dwordx4 v[48:49], v[44:47], off sc1
	ds_read2_b32 v[48:49], v33 offset0:82 offset1:90
	ds_read2_b32 v[56:57], v33 offset0:115 offset1:123
	ds_read2_b32 v[58:59], v33 offset0:148 offset1:156
	ds_read2_b32 v[60:61], v33 offset0:181 offset1:189
	ds_read2_b32 v[62:63], v33 offset0:214 offset1:222
	ds_read2_b32 v[64:65], v33 offset0:247 offset1:255
	s_waitcnt lgkmcnt(7)
	v_mov_b32_e32 v44, v50
	s_waitcnt lgkmcnt(6)
	v_mov_b32_e32 v45, v54
	s_waitcnt lgkmcnt(5)
	v_mov_b32_e32 v46, v48
	s_waitcnt lgkmcnt(4)
	v_mov_b32_e32 v47, v56
	v_pk_mul_f32 v[44:45], v[4:5], v[44:45]
	v_pk_mul_f32 v[46:47], v[6:7], v[46:47]
	v_cvt_pk_bf16_f32 v44, v44, v45
	v_cvt_pk_bf16_f32 v45, v46, v47
	s_waitcnt lgkmcnt(3)
	v_mov_b32_e32 v46, v58
	s_waitcnt lgkmcnt(2)
	v_mov_b32_e32 v47, v60
	v_mov_b32_e32 v54, v51
	v_mov_b32_e32 v56, v49
	v_mov_b32_e32 v60, v59
	v_pk_mul_f32 v[46:47], v[0:1], v[46:47]
	s_waitcnt lgkmcnt(1)
	v_mov_b32_e32 v68, v62
	s_waitcnt lgkmcnt(0)
	v_mov_b32_e32 v69, v64
	v_pk_mul_f32 v[4:5], v[4:5], v[54:55]
	v_pk_mul_f32 v[6:7], v[6:7], v[56:57]
	v_pk_mul_f32 v[0:1], v[0:1], v[60:61]
	v_mov_b32_e32 v64, v63
	v_pk_mul_f32 v[68:69], v[2:3], v[68:69]
	v_cvt_pk_bf16_f32 v4, v4, v5
	v_cvt_pk_bf16_f32 v5, v6, v7
	v_cvt_pk_bf16_f32 v6, v0, v1
	v_pk_mul_f32 v[0:1], v[2:3], v[64:65]
	v_cvt_pk_bf16_f32 v46, v46, v47
	v_cvt_pk_bf16_f32 v47, v68, v69
	v_add_u32_e32 v68, 16, v66
	v_cvt_pk_bf16_f32 v7, v0, v1
	v_add_u32_e32 v0, 24, v66
	v_ashrrev_i32_e32 v69, 31, v68
	v_ashrrev_i32_e32 v1, 31, v0
	v_lshlrev_b64 v[68:69], 11, v[68:69]
	v_lshlrev_b64 v[0:1], 11, v[0:1]
	v_lshl_add_u64 v[68:69], v[52:53], 0, v[68:69]
	v_lshl_add_u64 v[0:1], v[52:53], 0, v[0:1]
	global_store_dwordx4 v[68:69], v[44:47], off sc1
	global_store_dwordx4 v[0:1], v[4:7], off sc1
	s_waitcnt lgkmcnt(0)
	v_readlane_b32 s72, v254, 10

.LBB0_24:
	s_cmpk_gt_i32 s90, 0x11ff
	s_mov_b64 s[16:17], -1
	s_cbranch_scc0 .LBB0_59
	s_cmpk_gt_u32 s90, 0x13ff
	s_cbranch_scc0 .LBB0_56
	s_cmpk_gt_u32 s90, 0x17ff
	s_cbranch_scc0 .LBB0_50
	s_cmpk_gt_u32 s90, 0x19ff
	s_cbranch_scc0 .LBB0_44
	s_cmpk_gt_u32 s90, 0x1bff
	s_cbranch_scc0 .LBB0_41
	s_cmpk_gt_u32 s90, 0x31ff
	s_cbranch_scc0 .LBB0_31
	s_add_i32 s6, s90, 0xffffce00
	s_add_i32 s16, s90, 0xffffc880
	s_cmpk_lt_u32 s6, 0x580
	s_cselect_b32 s16, s6, s16
	s_cmpk_gt_u32 s6, 0x57f
	s_cselect_b32 s6, 0xb00000, 0
	s_cselect_b32 s26, 0x580000, 0
	s_add_u32 s72, s24, s6
	s_addc_u32 s73, s25, 0
	s_lshl_b32 s6, s16, 1
	s_and_b32 s17, s6, 0xfc0
	s_lshl_b32 s6, s16, 5
	s_and_b32 s16, s6, 0x3e0
	v_or_b32_e32 v0, s17, v30
	s_add_u32 s26, s34, s26
	v_lshlrev_b32_e32 v0, 12, v0
	v_mov_b32_e32 v1, v9
	s_addc_u32 s27, s35, 0
	v_lshl_add_u64 v[0:1], s[72:73], 0, v[0:1]
	s_lshl_b32 s6, s16, 2
	v_lshl_add_u64 v[0:1], v[0:1], 0, s[6:7]
	v_lshl_add_u64 v[0:1], v[0:1], 0, v[8:9]
	s_movk_i32 s6, 0x2000
	v_add_co_u32_e32 v2, vcc, s6, v0
	s_movk_i32 s6, 0x4000
	s_nop 0
	v_addc_co_u32_e32 v3, vcc, 0, v1, vcc
	v_add_co_u32_e32 v4, vcc, s6, v0
	s_movk_i32 s6, 0x6000
	s_nop 0
	v_addc_co_u32_e32 v5, vcc, 0, v1, vcc
	v_add_co_u32_e32 v6, vcc, s6, v0
	s_mov_b32 s6, 0x8000
	s_nop 0
	v_addc_co_u32_e32 v7, vcc, 0, v1, vcc
	v_add_co_u32_e32 v44, vcc, s6, v0
	s_mov_b32 s6, 0xa000
	s_nop 0
	v_addc_co_u32_e32 v45, vcc, 0, v1, vcc
	v_add_co_u32_e32 v46, vcc, s6, v0
	s_mov_b32 s6, 0xc000
	s_nop 0
	v_addc_co_u32_e32 v47, vcc, 0, v1, vcc
	v_add_co_u32_e32 v48, vcc, s6, v0
	s_mov_b32 s6, 0xe000
	s_nop 0
	v_addc_co_u32_e32 v49, vcc, 0, v1, vcc
	v_add_co_u32_e32 v50, vcc, s6, v0
	s_mov_b32 s6, 0x10000
	s_nop 0
	v_addc_co_u32_e32 v51, vcc, 0, v1, vcc
	global_load_dword v27, v[0:1], off
	global_load_dword v54, v[2:3], off
	global_load_dword v55, v[4:5], off
	global_load_dword v56, v[6:7], off
	global_load_dword v57, v[44:45], off
	global_load_dword v58, v[46:47], off
	global_load_dword v59, v[48:49], off
	global_load_dword v60, v[50:51], off
	v_add_co_u32_e32 v2, vcc, s6, v0
	s_mov_b32 s6, 0x14000
	s_nop 0
	v_addc_co_u32_e32 v3, vcc, 0, v1, vcc
	v_add_co_u32_e32 v4, vcc, s42, v0
	v_readlane_b32 s72, v254, 10
	s_nop 0
	v_addc_co_u32_e32 v5, vcc, 0, v1, vcc
	v_add_co_u32_e32 v6, vcc, s6, v0
	s_mov_b32 s6, 0x18000
	s_nop 0
	v_addc_co_u32_e32 v7, vcc, 0, v1, vcc
	v_add_co_u32_e32 v44, vcc, s43, v0
	s_nop 1
	v_addc_co_u32_e32 v45, vcc, 0, v1, vcc
	v_add_co_u32_e32 v46, vcc, s6, v0
	s_mov_b32 s6, 0x1a000
	s_nop 0
	v_addc_co_u32_e32 v47, vcc, 0, v1, vcc
	v_add_co_u32_e32 v48, vcc, s6, v0
	s_mov_b32 s6, 0x1c000
	s_nop 0
	v_addc_co_u32_e32 v49, vcc, 0, v1, vcc
	v_add_co_u32_e32 v50, vcc, s6, v0
	s_mov_b32 s6, 0x1e000
	s_nop 0
	v_addc_co_u32_e32 v51, vcc, 0, v1, vcc
	v_add_co_u32_e32 v52, vcc, s6, v0
	s_mov_b32 s6, 0x20000
	s_nop 0
	v_addc_co_u32_e32 v53, vcc, 0, v1, vcc
	global_load_dword v61, v[2:3], off
	global_load_dword v62, v[4:5], off
	global_load_dword v63, v[6:7], off
	global_load_dword v64, v[44:45], off
	global_load_dword v65, v[46:47], off
	global_load_dword v66, v[48:49], off
	global_load_dword v67, v[50:51], off
	global_load_dword v68, v[52:53], off
	v_add_co_u32_e32 v2, vcc, s6, v0
	s_mov_b32 s6, 0x22000
	s_nop 0
	v_addc_co_u32_e32 v3, vcc, 0, v1, vcc
	v_add_co_u32_e32 v4, vcc, s6, v0
	s_mov_b32 s6, 0x26000
	s_nop 0
	v_addc_co_u32_e32 v5, vcc, 0, v1, vcc
	v_add_co_u32_e32 v6, vcc, s44, v0
	s_nop 1
	v_addc_co_u32_e32 v7, vcc, 0, v1, vcc
	v_add_co_u32_e32 v44, vcc, s6, v0
	s_mov_b32 s6, 0x28000
	s_nop 0
	v_addc_co_u32_e32 v45, vcc, 0, v1, vcc
	v_add_co_u32_e32 v46, vcc, s6, v0
	s_mov_b32 s6, 0x2a000
	s_nop 0
	v_addc_co_u32_e32 v47, vcc, 0, v1, vcc
	v_add_co_u32_e32 v48, vcc, s6, v0
	s_mov_b32 s6, 0x2e000
	s_nop 0
	v_addc_co_u32_e32 v49, vcc, 0, v1, vcc
	v_add_co_u32_e32 v50, vcc, s45, v0
	s_nop 1
	v_addc_co_u32_e32 v51, vcc, 0, v1, vcc
	v_add_co_u32_e32 v52, vcc, s6, v0
	s_mov_b32 s6, 0x30000
	s_nop 0
	v_addc_co_u32_e32 v53, vcc, 0, v1, vcc
	global_load_dword v69, v[2:3], off
	global_load_dword v70, v[4:5], off
	global_load_dword v71, v[6:7], off
	global_load_dword v72, v[44:45], off
	global_load_dword v73, v[46:47], off
	global_load_dword v74, v[48:49], off
	global_load_dword v75, v[50:51], off
	s_nop 0
	global_load_dword v52, v[52:53], off
	v_add_co_u32_e32 v2, vcc, s6, v0
	s_mov_b32 s6, 0x32000
	s_nop 0
	v_addc_co_u32_e32 v3, vcc, 0, v1, vcc
	v_add_co_u32_e32 v4, vcc, s6, v0
	s_mov_b32 s6, 0x34000
	s_nop 0
	v_addc_co_u32_e32 v5, vcc, 0, v1, vcc
	v_add_co_u32_e32 v6, vcc, s6, v0
	s_mov_b32 s6, 0x38000
	s_nop 0
	v_addc_co_u32_e32 v7, vcc, 0, v1, vcc
	v_add_co_u32_e32 v44, vcc, s46, v0
	s_nop 1
	v_addc_co_u32_e32 v45, vcc, 0, v1, vcc
	v_add_co_u32_e32 v46, vcc, s6, v0
	s_mov_b32 s6, 0x3a000
	s_nop 0
	v_addc_co_u32_e32 v47, vcc, 0, v1, vcc
	v_add_co_u32_e32 v48, vcc, s6, v0
	s_mov_b32 s6, 0x3c000
	s_nop 0
	v_addc_co_u32_e32 v49, vcc, 0, v1, vcc
	v_add_co_u32_e32 v50, vcc, s6, v0
	s_mov_b32 s6, 0x3e000
	s_nop 0
	v_addc_co_u32_e32 v51, vcc, 0, v1, vcc
	v_add_co_u32_e32 v0, vcc, s6, v0
	s_lshl_b32 s6, s17, 1
	s_nop 0
	v_addc_co_u32_e32 v1, vcc, 0, v1, vcc
	global_load_dword v2, v[2:3], off
	s_nop 0
	global_load_dword v3, v[4:5], off
	s_nop 0
	global_load_dword v4, v[6:7], off
	global_load_dword v5, v[44:45], off
	s_nop 0
	global_load_dword v6, v[46:47], off
	global_load_dword v7, v[48:49], off
	global_load_dword v44, v[50:51], off
	s_nop 0
	global_load_dword v0, v[0:1], off
	s_waitcnt vmcnt(16)
	s_waitcnt vmcnt(0)
	ds_write2_b32 v31, v27, v54 offset1:66
	ds_write2_b32 v31, v55, v56 offset0:132 offset1:198
	ds_write2_b32 v37, v57, v58 offset0:8 offset1:74
	ds_write2_b32 v37, v59, v60 offset0:140 offset1:206
	ds_write2_b32 v38, v61, v62 offset0:16 offset1:82
	ds_write2_b32 v38, v63, v64 offset0:148 offset1:214
	ds_write2_b32 v39, v65, v66 offset0:24 offset1:90
	ds_write2_b32 v39, v67, v68 offset0:156 offset1:222
	ds_write2_b32 v40, v69, v70 offset0:32 offset1:98
	ds_write2_b32 v40, v71, v72 offset0:164 offset1:230
	ds_write2_b32 v41, v73, v74 offset0:40 offset1:106
	ds_write2_b32 v41, v75, v52 offset0:172 offset1:238
	ds_write2_b32 v42, v2, v3 offset0:48 offset1:114
	ds_write2_b32 v42, v4, v5 offset0:180 offset1:246
	ds_write2_b32 v43, v6, v7 offset0:56 offset1:122
	ds_write2_b32 v43, v44, v0 offset0:188 offset1:254
	s_waitcnt lgkmcnt(0)
	ds_read2_b32 v[4:5], v33 offset0:33 offset1:41
	ds_read2_b32 v[6:7], v33 offset1:8
	ds_read2_b32 v[44:45], v33 offset0:66 offset1:74
	ds_read2_b32 v[46:47], v33 offset0:99 offset1:107
	ds_read2_b32 v[48:49], v33 offset0:132 offset1:140
	ds_read2_b32 v[50:51], v33 offset0:165 offset1:173
	ds_read2_b32 v[52:53], v33 offset0:198 offset1:206
	ds_read2_b32 v[54:55], v33 offset0:231 offset1:239
	s_add_u32 s26, s26, s6
	s_waitcnt lgkmcnt(6)
	v_cvt_pk_bf16_f32 v0, v6, v4
	v_or_b32_e32 v4, s16, v32
	s_addc_u32 s27, s27, 0
	v_mov_b32_e32 v27, v9
	v_mul_u32_u24_e32 v4, 0xb00, v4
	v_lshl_add_u64 v[56:57], s[26:27], 0, v[26:27]
	v_lshlrev_b32_e32 v58, 1, v4
	v_mov_b32_e32 v59, v9
	s_waitcnt lgkmcnt(4)
	v_cvt_pk_bf16_f32 v1, v44, v46
	s_waitcnt lgkmcnt(2)
	v_cvt_pk_bf16_f32 v2, v48, v50
	s_waitcnt lgkmcnt(0)
	v_cvt_pk_bf16_f32 v3, v52, v54
	v_lshl_add_u64 v[58:59], v[56:57], 0, v[58:59]
	v_or_b32_e32 v4, s16, v34
	global_store_dwordx4 v[58:59], v[0:3], off sc1
	v_mul_u32_u24_e32 v4, 0xb00, v4
	v_lshlrev_b32_e32 v4, 1, v4
	v_cvt_pk_bf16_f32 v0, v7, v5
	v_cvt_pk_bf16_f32 v1, v45, v47
	v_cvt_pk_bf16_f32 v2, v49, v51
	v_cvt_pk_bf16_f32 v3, v53, v55
	v_mov_b32_e32 v5, v9
	ds_read2_b32 v[6:7], v33 offset0:16 offset1:24
	ds_read2_b32 v[44:45], v33 offset0:49 offset1:57
	ds_read2_b32 v[46:47], v33 offset0:82 offset1:90
	ds_read2_b32 v[48:49], v33 offset0:115 offset1:123
	ds_read2_b32 v[50:51], v33 offset0:148 offset1:156
	ds_read2_b32 v[52:53], v33 offset0:181 offset1:189
	ds_read2_b32 v[54:55], v33 offset0:214 offset1:222
	ds_read2_b32 v[58:59], v33 offset0:247 offset1:255
	v_lshl_add_u64 v[4:5], v[56:57], 0, v[4:5]
	global_store_dwordx4 v[4:5], v[0:3], off sc1
	v_or_b32_e32 v4, s16, v35
	v_mul_u32_u24_e32 v4, 0xb00, v4
	v_lshlrev_b32_e32 v4, 1, v4
	v_mov_b32_e32 v5, v9
	s_waitcnt lgkmcnt(6)
	v_cvt_pk_bf16_f32 v0, v6, v44
	s_waitcnt lgkmcnt(4)
	v_cvt_pk_bf16_f32 v1, v46, v48
	s_waitcnt lgkmcnt(2)
	v_cvt_pk_bf16_f32 v2, v50, v52
	s_waitcnt lgkmcnt(0)
	v_cvt_pk_bf16_f32 v3, v54, v58
	v_lshl_add_u64 v[4:5], v[56:57], 0, v[4:5]
	global_store_dwordx4 v[4:5], v[0:3], off sc1
	v_or_b32_e32 v4, s16, v36
	v_mul_u32_u24_e32 v4, 0xb00, v4
	v_lshlrev_b32_e32 v4, 1, v4
	v_mov_b32_e32 v5, v9
	v_cvt_pk_bf16_f32 v0, v7, v45
	v_cvt_pk_bf16_f32 v1, v47, v49
	v_cvt_pk_bf16_f32 v2, v51, v53
	v_cvt_pk_bf16_f32 v3, v55, v59
	v_lshl_add_u64 v[4:5], v[56:57], 0, v[4:5]
	global_store_dwordx4 v[4:5], v[0:3], off sc1
	s_waitcnt lgkmcnt(0)
	s_mov_b64 s[16:17], 0

.LBB0_39:
	s_waitcnt vmcnt(16)
	s_waitcnt vmcnt(0)
	ds_write2_b32 v31, v27, v44 offset1:66
	ds_write2_b32 v31, v45, v46 offset0:132 offset1:198
	ds_write2_b32 v37, v47, v48 offset0:8 offset1:74
	ds_write2_b32 v37, v49, v50 offset0:140 offset1:206
	ds_write2_b32 v38, v51, v52 offset0:16 offset1:82
	ds_write2_b32 v38, v53, v54 offset0:148 offset1:214
	ds_write2_b32 v39, v55, v56 offset0:24 offset1:90
	ds_write2_b32 v39, v57, v58 offset0:156 offset1:222
	ds_write2_b32 v40, v59, v60 offset0:32 offset1:98
	ds_write2_b32 v40, v61, v62 offset0:164 offset1:230
	ds_write2_b32 v41, v63, v64 offset0:40 offset1:106
	ds_write2_b32 v41, v65, v66 offset0:172 offset1:238
	ds_write2_b32 v42, v67, v68 offset0:48 offset1:114
	ds_write2_b32 v42, v69, v70 offset0:180 offset1:246
	ds_write2_b32 v43, v71, v72 offset0:56 offset1:122
	ds_write2_b32 v43, v73, v74 offset0:188 offset1:254
	s_waitcnt lgkmcnt(0)
	ds_read2_b32 v[48:49], v33 offset1:8
	ds_read2_b32 v[50:51], v33 offset0:33 offset1:41
	ds_read2_b32 v[54:55], v33 offset0:66 offset1:74
	ds_read2_b32 v[56:57], v33 offset0:99 offset1:107
	ds_read2_b32 v[58:59], v33 offset0:132 offset1:140
	ds_read2_b32 v[60:61], v33 offset0:165 offset1:173
	ds_read2_b32 v[62:63], v33 offset0:198 offset1:206
	ds_read2_b32 v[64:65], v33 offset0:231 offset1:239
	s_and_b64 s[16:17], s[16:17], exec
	s_cselect_b32 s16, 0xb00000, 0
	s_waitcnt lgkmcnt(7)
	v_mov_b32_e32 v44, v48
	s_waitcnt lgkmcnt(6)
	v_mov_b32_e32 v45, v50
	s_waitcnt lgkmcnt(5)
	v_mov_b32_e32 v46, v54
	s_waitcnt lgkmcnt(4)
	v_mov_b32_e32 v47, v56
	s_add_u32 s16, s36, s16
	v_pk_mul_f32 v[44:45], v[4:5], v[44:45]
	v_pk_mul_f32 v[46:47], v[6:7], v[46:47]
	s_addc_u32 s17, s37, 0
	s_lshl_b32 s6, s6, 1
	v_cvt_pk_bf16_f32 v44, v44, v45
	v_cvt_pk_bf16_f32 v45, v46, v47
	s_waitcnt lgkmcnt(3)
	v_mov_b32_e32 v46, v58
	s_waitcnt lgkmcnt(2)
	v_mov_b32_e32 v47, v60
	s_waitcnt lgkmcnt(1)
	v_mov_b32_e32 v66, v62
	s_waitcnt lgkmcnt(0)
	v_mov_b32_e32 v67, v64
	s_add_u32 s16, s16, s6
	v_pk_mul_f32 v[46:47], v[0:1], v[46:47]
	v_pk_mul_f32 v[66:67], v[2:3], v[66:67]
	s_addc_u32 s17, s17, 0
	v_mov_b32_e32 v27, v9
	v_cvt_pk_bf16_f32 v46, v46, v47
	v_cvt_pk_bf16_f32 v47, v66, v67
	v_add_u32_e32 v66, s72, v32
	v_mov_b32_e32 v67, v9
	v_lshl_add_u64 v[52:53], s[16:17], 0, v[26:27]
	v_lshlrev_b64 v[66:67], 11, v[66:67]
	v_lshl_add_u64 v[66:67], v[52:53], 0, v[66:67]
	v_mov_b32_e32 v50, v49
	v_mov_b32_e32 v56, v55
	global_store_dwordx4 v[66:67], v[44:47], off sc1
	v_mov_b32_e32 v60, v59
	v_mov_b32_e32 v64, v63
	v_pk_mul_f32 v[44:45], v[4:5], v[50:51]
	v_pk_mul_f32 v[46:47], v[6:7], v[56:57]
	v_cvt_pk_bf16_f32 v44, v44, v45
	v_cvt_pk_bf16_f32 v45, v46, v47
	v_pk_mul_f32 v[46:47], v[0:1], v[60:61]
	v_pk_mul_f32 v[48:49], v[2:3], v[64:65]
	v_cvt_pk_bf16_f32 v46, v46, v47
	v_cvt_pk_bf16_f32 v47, v48, v49
	v_add_u32_e32 v48, s72, v34
	v_mov_b32_e32 v49, v9
	v_lshlrev_b64 v[48:49], 11, v[48:49]
	v_lshl_add_u64 v[48:49], v[52:53], 0, v[48:49]
	ds_read2_b32 v[50:51], v33 offset0:16 offset1:24
	ds_read2_b32 v[54:55], v33 offset0:49 offset1:57
	global_store_dwordx4 v[48:49], v[44:47], off sc1
	ds_read2_b32 v[48:49], v33 offset0:82 offset1:90
	ds_read2_b32 v[56:57], v33 offset0:115 offset1:123
	ds_read2_b32 v[58:59], v33 offset0:148 offset1:156
	ds_read2_b32 v[60:61], v33 offset0:181 offset1:189
	ds_read2_b32 v[62:63], v33 offset0:214 offset1:222
	ds_read2_b32 v[64:65], v33 offset0:247 offset1:255
	s_waitcnt lgkmcnt(7)
	v_mov_b32_e32 v44, v50
	s_waitcnt lgkmcnt(6)
	v_mov_b32_e32 v45, v54
	s_waitcnt lgkmcnt(5)
	v_mov_b32_e32 v46, v48
	s_waitcnt lgkmcnt(4)
	v_mov_b32_e32 v47, v56
	v_pk_mul_f32 v[44:45], v[4:5], v[44:45]
	v_pk_mul_f32 v[46:47], v[6:7], v[46:47]
	v_cvt_pk_bf16_f32 v44, v44, v45
	v_cvt_pk_bf16_f32 v45, v46, v47
	s_waitcnt lgkmcnt(3)
	v_mov_b32_e32 v46, v58
	s_waitcnt lgkmcnt(2)
	v_mov_b32_e32 v47, v60
	v_mov_b32_e32 v54, v51
	v_mov_b32_e32 v56, v49
	v_mov_b32_e32 v60, v59
	v_pk_mul_f32 v[46:47], v[0:1], v[46:47]
	s_waitcnt lgkmcnt(1)
	v_mov_b32_e32 v66, v62
	s_waitcnt lgkmcnt(0)
	v_mov_b32_e32 v67, v64
	v_pk_mul_f32 v[4:5], v[4:5], v[54:55]
	v_pk_mul_f32 v[6:7], v[6:7], v[56:57]
	v_pk_mul_f32 v[0:1], v[0:1], v[60:61]
	v_mov_b32_e32 v64, v63
	v_pk_mul_f32 v[66:67], v[2:3], v[66:67]
	v_cvt_pk_bf16_f32 v4, v4, v5
	v_cvt_pk_bf16_f32 v5, v6, v7
	v_cvt_pk_bf16_f32 v6, v0, v1
	v_pk_mul_f32 v[0:1], v[2:3], v[64:65]
	v_cvt_pk_bf16_f32 v46, v46, v47
	v_cvt_pk_bf16_f32 v47, v66, v67
	v_add_u32_e32 v66, s72, v35
	v_mov_b32_e32 v67, v9
	v_cvt_pk_bf16_f32 v7, v0, v1
	v_add_u32_e32 v0, s72, v36
	v_mov_b32_e32 v1, v9
	v_lshlrev_b64 v[66:67], 11, v[66:67]
	v_lshlrev_b64 v[0:1], 11, v[0:1]
	v_lshl_add_u64 v[66:67], v[52:53], 0, v[66:67]
	v_lshl_add_u64 v[0:1], v[52:53], 0, v[0:1]
	global_store_dwordx4 v[66:67], v[44:47], off sc1
	global_store_dwordx4 v[0:1], v[4:7], off sc1
	s_waitcnt lgkmcnt(0)
	s_mov_b32 s92, s91
	v_readlane_b32 s72, v254, 10

.LBB0_41:
	s_andn2_b64 vcc, exec, s[16:17]
	s_cbranch_vccnz .LBB0_43
	s_and_b32 s6, s40, 0x3fc0
	s_add_i32 s16, s6, 0xffffcc00
	v_or_b32_e32 v0, s16, v30
	v_mov_b32_e32 v1, v9
	s_and_b32 s26, s38, 0x3e0
	v_lshlrev_b64 v[0:1], 12, v[0:1]
	v_lshl_add_u64 v[0:1], s[18:19], 0, v[0:1]
	s_lshl_b32 s6, s26, 2
	v_lshl_add_u64 v[0:1], v[0:1], 0, s[6:7]
	v_lshl_add_u64 v[0:1], v[0:1], 0, v[8:9]
	v_add_co_u32_e32 v2, vcc, 0x2000, v0
	s_mov_b32 s17, s7
	s_nop 0
	v_addc_co_u32_e32 v3, vcc, 0, v1, vcc
	v_add_co_u32_e32 v4, vcc, 0x4000, v0
	s_nop 1
	v_addc_co_u32_e32 v5, vcc, 0, v1, vcc
	v_add_co_u32_e32 v6, vcc, 0x6000, v0
	s_nop 1
	v_addc_co_u32_e32 v7, vcc, 0, v1, vcc
	v_add_co_u32_e32 v44, vcc, 0x8000, v0
	s_nop 1
	v_addc_co_u32_e32 v45, vcc, 0, v1, vcc
	v_add_co_u32_e32 v46, vcc, 0xa000, v0
	s_nop 1
	v_addc_co_u32_e32 v47, vcc, 0, v1, vcc
	v_add_co_u32_e32 v48, vcc, 0xc000, v0
	s_nop 1
	v_addc_co_u32_e32 v49, vcc, 0, v1, vcc
	v_add_co_u32_e32 v50, vcc, 0xe000, v0
	s_nop 1
	v_addc_co_u32_e32 v51, vcc, 0, v1, vcc
	global_load_dword v27, v[0:1], off
	global_load_dword v54, v[2:3], off
	global_load_dword v55, v[4:5], off
	global_load_dword v56, v[6:7], off
	global_load_dword v57, v[44:45], off
	global_load_dword v58, v[46:47], off
	global_load_dword v59, v[48:49], off
	global_load_dword v60, v[50:51], off
	v_add_co_u32_e32 v2, vcc, 0x10000, v0
	s_nop 1
	v_addc_co_u32_e32 v3, vcc, 0, v1, vcc
	v_add_co_u32_e32 v4, vcc, 0x12000, v0
	s_nop 1
	v_addc_co_u32_e32 v5, vcc, 0, v1, vcc
	v_add_co_u32_e32 v6, vcc, 0x14000, v0
	s_nop 1
	v_addc_co_u32_e32 v7, vcc, 0, v1, vcc
	v_add_co_u32_e32 v44, vcc, 0x16000, v0
	s_nop 1
	v_addc_co_u32_e32 v45, vcc, 0, v1, vcc
	v_add_co_u32_e32 v46, vcc, 0x18000, v0
	s_nop 1
	v_addc_co_u32_e32 v47, vcc, 0, v1, vcc
	v_add_co_u32_e32 v48, vcc, 0x1a000, v0
	s_nop 1
	v_addc_co_u32_e32 v49, vcc, 0, v1, vcc
	v_add_co_u32_e32 v50, vcc, 0x1c000, v0
	s_nop 1
	v_addc_co_u32_e32 v51, vcc, 0, v1, vcc
	v_add_co_u32_e32 v52, vcc, 0x1e000, v0
	s_nop 1
	v_addc_co_u32_e32 v53, vcc, 0, v1, vcc
	global_load_dword v61, v[2:3], off
	global_load_dword v62, v[4:5], off
	global_load_dword v63, v[6:7], off
	global_load_dword v64, v[44:45], off
	global_load_dword v65, v[46:47], off
	global_load_dword v66, v[48:49], off
	global_load_dword v67, v[50:51], off
	global_load_dword v68, v[52:53], off
	v_add_co_u32_e32 v2, vcc, 0x20000, v0
	s_nop 1
	v_addc_co_u32_e32 v3, vcc, 0, v1, vcc
	v_add_co_u32_e32 v4, vcc, 0x22000, v0
	s_nop 1
	v_addc_co_u32_e32 v5, vcc, 0, v1, vcc
	v_add_co_u32_e32 v6, vcc, 0x24000, v0
	s_nop 1
	v_addc_co_u32_e32 v7, vcc, 0, v1, vcc
	v_add_co_u32_e32 v44, vcc, 0x26000, v0
	s_nop 1
	v_addc_co_u32_e32 v45, vcc, 0, v1, vcc
	v_add_co_u32_e32 v46, vcc, 0x28000, v0
	s_nop 1
	v_addc_co_u32_e32 v47, vcc, 0, v1, vcc
	v_add_co_u32_e32 v48, vcc, 0x2a000, v0
	s_nop 1
	v_addc_co_u32_e32 v49, vcc, 0, v1, vcc
	v_add_co_u32_e32 v50, vcc, 0x2c000, v0
	s_nop 1
	v_addc_co_u32_e32 v51, vcc, 0, v1, vcc
	v_add_co_u32_e32 v52, vcc, 0x2e000, v0
	s_nop 1
	v_addc_co_u32_e32 v53, vcc, 0, v1, vcc
	global_load_dword v69, v[2:3], off
	global_load_dword v70, v[4:5], off
	global_load_dword v71, v[6:7], off
	global_load_dword v72, v[44:45], off
	global_load_dword v73, v[46:47], off
	global_load_dword v74, v[48:49], off
	global_load_dword v75, v[50:51], off
	s_nop 0
	global_load_dword v52, v[52:53], off
	v_add_co_u32_e32 v2, vcc, 0x30000, v0
	s_nop 1
	v_addc_co_u32_e32 v3, vcc, 0, v1, vcc
	v_add_co_u32_e32 v4, vcc, 0x32000, v0
	s_nop 1
	v_addc_co_u32_e32 v5, vcc, 0, v1, vcc
	v_add_co_u32_e32 v6, vcc, 0x34000, v0
	s_nop 1
	v_addc_co_u32_e32 v7, vcc, 0, v1, vcc
	v_add_co_u32_e32 v44, vcc, 0x36000, v0
	s_nop 1
	v_addc_co_u32_e32 v45, vcc, 0, v1, vcc
	v_add_co_u32_e32 v46, vcc, 0x38000, v0
	s_nop 1
	v_addc_co_u32_e32 v47, vcc, 0, v1, vcc
	v_add_co_u32_e32 v48, vcc, 0x3a000, v0
	s_nop 1
	v_addc_co_u32_e32 v49, vcc, 0, v1, vcc
	v_add_co_u32_e32 v50, vcc, 0x3c000, v0
	s_nop 1
	v_addc_co_u32_e32 v51, vcc, 0, v1, vcc
	v_add_co_u32_e32 v0, vcc, 0x3e000, v0
	s_nop 1
	v_addc_co_u32_e32 v1, vcc, 0, v1, vcc
	global_load_dword v2, v[2:3], off
	s_nop 0
	global_load_dword v3, v[4:5], off
	s_nop 0
	global_load_dword v4, v[6:7], off
	global_load_dword v5, v[44:45], off
	s_nop 0
	global_load_dword v6, v[46:47], off
	global_load_dword v7, v[48:49], off
	global_load_dword v44, v[50:51], off
	s_nop 0
	global_load_dword v0, v[0:1], off
	s_waitcnt vmcnt(16)
	s_waitcnt vmcnt(0)
	ds_write2_b32 v31, v27, v54 offset1:66
	ds_write2_b32 v31, v55, v56 offset0:132 offset1:198
	ds_write2_b32 v37, v57, v58 offset0:8 offset1:74
	ds_write2_b32 v37, v59, v60 offset0:140 offset1:206
	ds_write2_b32 v38, v61, v62 offset0:16 offset1:82
	ds_write2_b32 v38, v63, v64 offset0:148 offset1:214
	ds_write2_b32 v39, v65, v66 offset0:24 offset1:90
	ds_write2_b32 v39, v67, v68 offset0:156 offset1:222
	ds_write2_b32 v40, v69, v70 offset0:32 offset1:98
	ds_write2_b32 v40, v71, v72 offset0:164 offset1:230
	ds_write2_b32 v41, v73, v74 offset0:40 offset1:106
	ds_write2_b32 v41, v75, v52 offset0:172 offset1:238
	ds_write2_b32 v42, v2, v3 offset0:48 offset1:114
	ds_write2_b32 v42, v4, v5 offset0:180 offset1:246
	ds_write2_b32 v43, v6, v7 offset0:56 offset1:122
	ds_write2_b32 v43, v44, v0 offset0:188 offset1:254
	s_waitcnt lgkmcnt(0)
	ds_read2_b32 v[4:5], v33 offset0:33 offset1:41
	ds_read2_b32 v[6:7], v33 offset1:8
	ds_read2_b32 v[44:45], v33 offset0:66 offset1:74
	ds_read2_b32 v[46:47], v33 offset0:99 offset1:107
	ds_read2_b32 v[48:49], v33 offset0:132 offset1:140
	ds_read2_b32 v[50:51], v33 offset0:165 offset1:173
	ds_read2_b32 v[52:53], v33 offset0:198 offset1:206
	ds_read2_b32 v[54:55], v33 offset0:231 offset1:239
	s_waitcnt lgkmcnt(6)
	v_cvt_pk_bf16_f32 v0, v6, v4
	v_or_b32_e32 v4, s26, v32
	v_lshl_add_u64 v[56:57], s[16:17], 1, v[12:13]
	v_lshlrev_b32_e32 v58, 11, v4
	v_mov_b32_e32 v59, v9
	s_waitcnt lgkmcnt(4)
	v_cvt_pk_bf16_f32 v1, v44, v46
	s_waitcnt lgkmcnt(2)
	v_cvt_pk_bf16_f32 v2, v48, v50
	s_waitcnt lgkmcnt(0)
	v_cvt_pk_bf16_f32 v3, v52, v54
	v_lshl_add_u64 v[58:59], v[56:57], 0, v[58:59]
	global_store_dwordx4 v[58:59], v[0:3], off sc1
	v_or_b32_e32 v4, s26, v34
	v_lshlrev_b32_e32 v4, 11, v4
	v_cvt_pk_bf16_f32 v0, v7, v5
	v_cvt_pk_bf16_f32 v1, v45, v47
	v_cvt_pk_bf16_f32 v2, v49, v51
	v_cvt_pk_bf16_f32 v3, v53, v55
	ds_read2_b32 v[6:7], v33 offset0:49 offset1:57
	ds_read2_b32 v[44:45], v33 offset0:16 offset1:24
	ds_read2_b32 v[46:47], v33 offset0:82 offset1:90
	ds_read2_b32 v[48:49], v33 offset0:115 offset1:123
	ds_read2_b32 v[50:51], v33 offset0:148 offset1:156
	ds_read2_b32 v[52:53], v33 offset0:181 offset1:189
	ds_read2_b32 v[54:55], v33 offset0:214 offset1:222
	ds_read2_b32 v[58:59], v33 offset0:247 offset1:255
	v_mov_b32_e32 v5, v9
	v_lshl_add_u64 v[4:5], v[56:57], 0, v[4:5]
	global_store_dwordx4 v[4:5], v[0:3], off sc1
	v_or_b32_e32 v4, s26, v35
	v_lshlrev_b32_e32 v4, 11, v4
	v_mov_b32_e32 v5, v9
	s_waitcnt lgkmcnt(6)
	v_cvt_pk_bf16_f32 v0, v44, v6
	s_waitcnt lgkmcnt(4)
	v_cvt_pk_bf16_f32 v1, v46, v48
	s_waitcnt lgkmcnt(2)
	v_cvt_pk_bf16_f32 v2, v50, v52
	s_waitcnt lgkmcnt(0)
	v_cvt_pk_bf16_f32 v3, v54, v58
	v_lshl_add_u64 v[4:5], v[56:57], 0, v[4:5]
	global_store_dwordx4 v[4:5], v[0:3], off sc1
	v_or_b32_e32 v4, s26, v36
	v_lshlrev_b32_e32 v4, 11, v4
	v_mov_b32_e32 v5, v9
	v_cvt_pk_bf16_f32 v0, v45, v7
	v_cvt_pk_bf16_f32 v1, v47, v49
	v_cvt_pk_bf16_f32 v2, v51, v53
	v_cvt_pk_bf16_f32 v3, v55, v59
	v_lshl_add_u64 v[4:5], v[56:57], 0, v[4:5]
	global_store_dwordx4 v[4:5], v[0:3], off sc1
	s_waitcnt lgkmcnt(0)

.LBB0_48:
	s_waitcnt vmcnt(16)
	s_waitcnt vmcnt(0)
	ds_write2_b32 v31, v27, v44 offset1:66
	ds_write2_b32 v31, v45, v46 offset0:132 offset1:198
	ds_write2_b32 v37, v47, v48 offset0:8 offset1:74
	ds_write2_b32 v37, v49, v50 offset0:140 offset1:206
	ds_write2_b32 v38, v51, v52 offset0:16 offset1:82
	ds_write2_b32 v38, v53, v54 offset0:148 offset1:214
	ds_write2_b32 v39, v55, v56 offset0:24 offset1:90
	ds_write2_b32 v39, v57, v58 offset0:156 offset1:222
	ds_write2_b32 v40, v59, v60 offset0:32 offset1:98
	ds_write2_b32 v40, v61, v62 offset0:164 offset1:230
	ds_write2_b32 v41, v63, v64 offset0:40 offset1:106
	ds_write2_b32 v41, v65, v66 offset0:172 offset1:238
	ds_write2_b32 v42, v67, v68 offset0:48 offset1:114
	ds_write2_b32 v42, v69, v70 offset0:180 offset1:246
	ds_write2_b32 v43, v71, v72 offset0:56 offset1:122
	ds_write2_b32 v43, v73, v74 offset0:188 offset1:254
	s_waitcnt lgkmcnt(0)
	ds_read2_b32 v[48:49], v33 offset1:8
	ds_read2_b32 v[50:51], v33 offset0:33 offset1:41
	ds_read2_b32 v[54:55], v33 offset0:66 offset1:74
	ds_read2_b32 v[56:57], v33 offset0:99 offset1:107
	ds_read2_b32 v[58:59], v33 offset0:132 offset1:140
	ds_read2_b32 v[60:61], v33 offset0:165 offset1:173
	ds_read2_b32 v[62:63], v33 offset0:198 offset1:206
	ds_read2_b32 v[64:65], v33 offset0:231 offset1:239
	s_waitcnt lgkmcnt(7)
	v_mov_b32_e32 v44, v48
	s_waitcnt lgkmcnt(6)
	v_mov_b32_e32 v45, v50
	s_waitcnt lgkmcnt(5)
	v_mov_b32_e32 v46, v54
	s_waitcnt lgkmcnt(4)
	v_mov_b32_e32 v47, v56
	v_pk_mul_f32 v[44:45], v[4:5], v[44:45]
	v_pk_mul_f32 v[46:47], v[6:7], v[46:47]
	v_cvt_pk_bf16_f32 v44, v44, v45
	v_cvt_pk_bf16_f32 v45, v46, v47
	s_waitcnt lgkmcnt(3)
	v_mov_b32_e32 v46, v58
	s_waitcnt lgkmcnt(2)
	v_mov_b32_e32 v47, v60
	s_waitcnt lgkmcnt(1)
	v_mov_b32_e32 v66, v62
	s_waitcnt lgkmcnt(0)
	v_mov_b32_e32 v67, v64
	v_pk_mul_f32 v[46:47], v[0:1], v[46:47]
	v_pk_mul_f32 v[66:67], v[2:3], v[66:67]
	v_or_b32_e32 v27, s16, v32
	v_lshl_add_u64 v[52:53], s[6:7], 1, v[16:17]
	v_cvt_pk_bf16_f32 v46, v46, v47
	v_cvt_pk_bf16_f32 v47, v66, v67
	v_lshlrev_b32_e32 v66, 11, v27
	v_mov_b32_e32 v67, v9
	v_lshl_add_u64 v[66:67], v[52:53], 0, v[66:67]
	v_mov_b32_e32 v50, v49
	v_mov_b32_e32 v56, v55
	global_store_dwordx4 v[66:67], v[44:47], off sc1
	v_mov_b32_e32 v60, v59
	v_mov_b32_e32 v64, v63
	v_pk_mul_f32 v[44:45], v[4:5], v[50:51]
	v_pk_mul_f32 v[46:47], v[6:7], v[56:57]
	v_cvt_pk_bf16_f32 v44, v44, v45
	v_cvt_pk_bf16_f32 v45, v46, v47
	v_pk_mul_f32 v[46:47], v[0:1], v[60:61]
	v_pk_mul_f32 v[48:49], v[2:3], v[64:65]
	v_or_b32_e32 v27, s16, v34
	v_cvt_pk_bf16_f32 v46, v46, v47
	v_cvt_pk_bf16_f32 v47, v48, v49
	v_lshlrev_b32_e32 v48, 11, v27
	v_mov_b32_e32 v49, v9
	v_lshl_add_u64 v[48:49], v[52:53], 0, v[48:49]
	ds_read2_b32 v[50:51], v33 offset0:16 offset1:24
	ds_read2_b32 v[54:55], v33 offset0:49 offset1:57
	global_store_dwordx4 v[48:49], v[44:47], off sc1
	ds_read2_b32 v[48:49], v33 offset0:82 offset1:90
	ds_read2_b32 v[56:57], v33 offset0:115 offset1:123
	ds_read2_b32 v[58:59], v33 offset0:148 offset1:156
	ds_read2_b32 v[60:61], v33 offset0:181 offset1:189
	ds_read2_b32 v[62:63], v33 offset0:214 offset1:222
	ds_read2_b32 v[64:65], v33 offset0:247 offset1:255
	s_waitcnt lgkmcnt(7)
	v_mov_b32_e32 v44, v50
	s_waitcnt lgkmcnt(6)
	v_mov_b32_e32 v45, v54
	s_waitcnt lgkmcnt(5)
	v_mov_b32_e32 v46, v48
	s_waitcnt lgkmcnt(4)
	v_mov_b32_e32 v47, v56
	v_pk_mul_f32 v[44:45], v[4:5], v[44:45]
	v_pk_mul_f32 v[46:47], v[6:7], v[46:47]
	v_cvt_pk_bf16_f32 v44, v44, v45
	v_cvt_pk_bf16_f32 v45, v46, v47
	s_waitcnt lgkmcnt(3)
	v_mov_b32_e32 v46, v58
	s_waitcnt lgkmcnt(2)
	v_mov_b32_e32 v47, v60
	v_mov_b32_e32 v54, v51
	v_mov_b32_e32 v56, v49
	v_mov_b32_e32 v60, v59
	v_pk_mul_f32 v[46:47], v[0:1], v[46:47]
	s_waitcnt lgkmcnt(0)
	v_mov_b32_e32 v67, v64
	v_pk_mul_f32 v[4:5], v[4:5], v[54:55]
	v_pk_mul_f32 v[6:7], v[6:7], v[56:57]
	v_pk_mul_f32 v[0:1], v[0:1], v[60:61]
	v_mov_b32_e32 v64, v63
	v_mov_b32_e32 v66, v62
	v_cvt_pk_bf16_f32 v4, v4, v5
	v_cvt_pk_bf16_f32 v5, v6, v7
	v_cvt_pk_bf16_f32 v6, v0, v1
	v_pk_mul_f32 v[0:1], v[2:3], v[64:65]
	v_pk_mul_f32 v[66:67], v[2:3], v[66:67]
	v_or_b32_e32 v27, s16, v35
	v_cvt_pk_bf16_f32 v7, v0, v1
	v_or_b32_e32 v0, s16, v36
	v_cvt_pk_bf16_f32 v46, v46, v47
	v_cvt_pk_bf16_f32 v47, v66, v67
	v_lshlrev_b32_e32 v66, 11, v27
	v_mov_b32_e32 v67, v9
	v_lshlrev_b32_e32 v0, 11, v0
	v_mov_b32_e32 v1, v9
	v_lshl_add_u64 v[66:67], v[52:53], 0, v[66:67]
	v_lshl_add_u64 v[0:1], v[52:53], 0, v[0:1]
	global_store_dwordx4 v[66:67], v[44:47], off sc1
	global_store_dwordx4 v[0:1], v[4:7], off sc1
	s_waitcnt lgkmcnt(0)

.LBB0_54:
	s_waitcnt vmcnt(16)
	s_waitcnt vmcnt(0)
	ds_write2_b32 v31, v27, v44 offset1:66
	ds_write2_b32 v31, v45, v46 offset0:132 offset1:198
	ds_write2_b32 v37, v47, v48 offset0:8 offset1:74
	ds_write2_b32 v37, v49, v50 offset0:140 offset1:206
	ds_write2_b32 v38, v51, v52 offset0:16 offset1:82
	ds_write2_b32 v38, v53, v54 offset0:148 offset1:214
	ds_write2_b32 v39, v55, v56 offset0:24 offset1:90
	ds_write2_b32 v39, v57, v58 offset0:156 offset1:222
	ds_write2_b32 v40, v59, v60 offset0:32 offset1:98
	ds_write2_b32 v40, v61, v62 offset0:164 offset1:230
	ds_write2_b32 v41, v63, v64 offset0:40 offset1:106
	ds_write2_b32 v41, v65, v66 offset0:172 offset1:238
	ds_write2_b32 v42, v67, v68 offset0:48 offset1:114
	ds_write2_b32 v42, v69, v70 offset0:180 offset1:246
	ds_write2_b32 v43, v71, v72 offset0:56 offset1:122
	ds_write2_b32 v43, v73, v74 offset0:188 offset1:254
	s_waitcnt lgkmcnt(0)
	ds_read2_b32 v[48:49], v33 offset1:8
	ds_read2_b32 v[50:51], v33 offset0:33 offset1:41
	ds_read2_b32 v[54:55], v33 offset0:66 offset1:74
	ds_read2_b32 v[56:57], v33 offset0:99 offset1:107
	ds_read2_b32 v[58:59], v33 offset0:132 offset1:140
	ds_read2_b32 v[60:61], v33 offset0:165 offset1:173
	ds_read2_b32 v[62:63], v33 offset0:198 offset1:206
	ds_read2_b32 v[64:65], v33 offset0:231 offset1:239
	s_waitcnt lgkmcnt(7)
	v_mov_b32_e32 v44, v48
	s_waitcnt lgkmcnt(6)
	v_mov_b32_e32 v45, v50
	s_waitcnt lgkmcnt(5)
	v_mov_b32_e32 v46, v54
	s_waitcnt lgkmcnt(4)
	v_mov_b32_e32 v47, v56
	v_pk_mul_f32 v[44:45], v[4:5], v[44:45]
	v_pk_mul_f32 v[46:47], v[6:7], v[46:47]
	v_cvt_pk_bf16_f32 v44, v44, v45
	v_cvt_pk_bf16_f32 v45, v46, v47
	s_waitcnt lgkmcnt(3)
	v_mov_b32_e32 v46, v58
	s_waitcnt lgkmcnt(2)
	v_mov_b32_e32 v47, v60
	s_waitcnt lgkmcnt(1)
	v_mov_b32_e32 v66, v62
	s_waitcnt lgkmcnt(0)
	v_mov_b32_e32 v67, v64
	v_pk_mul_f32 v[46:47], v[0:1], v[46:47]
	v_pk_mul_f32 v[66:67], v[2:3], v[66:67]
	v_or_b32_e32 v27, s16, v32
	v_lshl_add_u64 v[52:53], s[6:7], 1, v[18:19]
	v_cvt_pk_bf16_f32 v46, v46, v47
	v_cvt_pk_bf16_f32 v47, v66, v67
	v_lshlrev_b32_e32 v66, 11, v27
	v_mov_b32_e32 v67, v9
	v_lshl_add_u64 v[66:67], v[52:53], 0, v[66:67]
	v_mov_b32_e32 v50, v49
	v_mov_b32_e32 v56, v55
	global_store_dwordx4 v[66:67], v[44:47], off sc1
	v_mov_b32_e32 v60, v59
	v_mov_b32_e32 v64, v63
	v_pk_mul_f32 v[44:45], v[4:5], v[50:51]
	v_pk_mul_f32 v[46:47], v[6:7], v[56:57]
	v_cvt_pk_bf16_f32 v44, v44, v45
	v_cvt_pk_bf16_f32 v45, v46, v47
	v_pk_mul_f32 v[46:47], v[0:1], v[60:61]
	v_pk_mul_f32 v[48:49], v[2:3], v[64:65]
	v_or_b32_e32 v27, s16, v34
	v_cvt_pk_bf16_f32 v46, v46, v47
	v_cvt_pk_bf16_f32 v47, v48, v49
	v_lshlrev_b32_e32 v48, 11, v27
	v_mov_b32_e32 v49, v9
	v_lshl_add_u64 v[48:49], v[52:53], 0, v[48:49]
	ds_read2_b32 v[50:51], v33 offset0:16 offset1:24
	ds_read2_b32 v[54:55], v33 offset0:49 offset1:57
	global_store_dwordx4 v[48:49], v[44:47], off sc1
	ds_read2_b32 v[48:49], v33 offset0:82 offset1:90
	ds_read2_b32 v[56:57], v33 offset0:115 offset1:123
	ds_read2_b32 v[58:59], v33 offset0:148 offset1:156
	ds_read2_b32 v[60:61], v33 offset0:181 offset1:189
	ds_read2_b32 v[62:63], v33 offset0:214 offset1:222
	ds_read2_b32 v[64:65], v33 offset0:247 offset1:255
	s_waitcnt lgkmcnt(7)
	v_mov_b32_e32 v44, v50
	s_waitcnt lgkmcnt(6)
	v_mov_b32_e32 v45, v54
	s_waitcnt lgkmcnt(5)
	v_mov_b32_e32 v46, v48
	s_waitcnt lgkmcnt(4)
	v_mov_b32_e32 v47, v56
	v_pk_mul_f32 v[44:45], v[4:5], v[44:45]
	v_pk_mul_f32 v[46:47], v[6:7], v[46:47]
	v_cvt_pk_bf16_f32 v44, v44, v45
	v_cvt_pk_bf16_f32 v45, v46, v47
	s_waitcnt lgkmcnt(3)
	v_mov_b32_e32 v46, v58
	s_waitcnt lgkmcnt(2)
	v_mov_b32_e32 v47, v60
	v_mov_b32_e32 v54, v51
	v_mov_b32_e32 v56, v49
	v_mov_b32_e32 v60, v59
	v_pk_mul_f32 v[46:47], v[0:1], v[46:47]
	s_waitcnt lgkmcnt(0)
	v_mov_b32_e32 v67, v64
	v_pk_mul_f32 v[4:5], v[4:5], v[54:55]
	v_pk_mul_f32 v[6:7], v[6:7], v[56:57]
	v_pk_mul_f32 v[0:1], v[0:1], v[60:61]
	v_mov_b32_e32 v64, v63
	v_mov_b32_e32 v66, v62
	v_cvt_pk_bf16_f32 v4, v4, v5
	v_cvt_pk_bf16_f32 v5, v6, v7
	v_cvt_pk_bf16_f32 v6, v0, v1
	v_pk_mul_f32 v[0:1], v[2:3], v[64:65]
	v_pk_mul_f32 v[66:67], v[2:3], v[66:67]
	v_or_b32_e32 v27, s16, v35
	v_cvt_pk_bf16_f32 v7, v0, v1
	v_or_b32_e32 v0, s16, v36
	v_cvt_pk_bf16_f32 v46, v46, v47
	v_cvt_pk_bf16_f32 v47, v66, v67
	v_lshlrev_b32_e32 v66, 11, v27
	v_mov_b32_e32 v67, v9
	v_lshlrev_b32_e32 v0, 11, v0
	v_mov_b32_e32 v1, v9
	v_lshl_add_u64 v[66:67], v[52:53], 0, v[66:67]
	v_lshl_add_u64 v[0:1], v[52:53], 0, v[0:1]
	global_store_dwordx4 v[66:67], v[44:47], off sc1
	global_store_dwordx4 v[0:1], v[4:7], off sc1
	s_waitcnt lgkmcnt(0)

.LBB0_56:
	s_andn2_b64 vcc, exec, s[16:17]
	s_cbranch_vccnz .LBB0_58
	s_and_b32 s6, s40, 0x3fc0
	s_add_i32 s16, s6, 0xffffdc00
	v_or_b32_e32 v0, s16, v30
	v_mov_b32_e32 v1, v9
	s_and_b32 s26, s38, 0x3e0
	v_lshlrev_b64 v[0:1], 12, v[0:1]
	v_lshl_add_u64 v[0:1], s[10:11], 0, v[0:1]
	s_lshl_b32 s6, s26, 2
	v_lshl_add_u64 v[0:1], v[0:1], 0, s[6:7]
	v_lshl_add_u64 v[0:1], v[0:1], 0, v[8:9]
	v_add_co_u32_e32 v2, vcc, 0x2000, v0
	s_mov_b32 s17, s7
	s_nop 0
	v_addc_co_u32_e32 v3, vcc, 0, v1, vcc
	v_add_co_u32_e32 v4, vcc, 0x4000, v0
	s_nop 1
	v_addc_co_u32_e32 v5, vcc, 0, v1, vcc
	v_add_co_u32_e32 v6, vcc, 0x6000, v0
	s_nop 1
	v_addc_co_u32_e32 v7, vcc, 0, v1, vcc
	v_add_co_u32_e32 v44, vcc, 0x8000, v0
	s_nop 1
	v_addc_co_u32_e32 v45, vcc, 0, v1, vcc
	v_add_co_u32_e32 v46, vcc, 0xa000, v0
	s_nop 1
	v_addc_co_u32_e32 v47, vcc, 0, v1, vcc
	v_add_co_u32_e32 v48, vcc, 0xc000, v0
	s_nop 1
	v_addc_co_u32_e32 v49, vcc, 0, v1, vcc
	v_add_co_u32_e32 v50, vcc, 0xe000, v0
	s_nop 1
	v_addc_co_u32_e32 v51, vcc, 0, v1, vcc
	global_load_dword v27, v[0:1], off
	global_load_dword v54, v[2:3], off
	global_load_dword v55, v[4:5], off
	global_load_dword v56, v[6:7], off
	global_load_dword v57, v[44:45], off
	global_load_dword v58, v[46:47], off
	global_load_dword v59, v[48:49], off
	global_load_dword v60, v[50:51], off
	v_add_co_u32_e32 v2, vcc, 0x10000, v0
	s_nop 1
	v_addc_co_u32_e32 v3, vcc, 0, v1, vcc
	v_add_co_u32_e32 v4, vcc, 0x12000, v0
	s_nop 1
	v_addc_co_u32_e32 v5, vcc, 0, v1, vcc
	v_add_co_u32_e32 v6, vcc, 0x14000, v0
	s_nop 1
	v_addc_co_u32_e32 v7, vcc, 0, v1, vcc
	v_add_co_u32_e32 v44, vcc, 0x16000, v0
	s_nop 1
	v_addc_co_u32_e32 v45, vcc, 0, v1, vcc
	v_add_co_u32_e32 v46, vcc, 0x18000, v0
	s_nop 1
	v_addc_co_u32_e32 v47, vcc, 0, v1, vcc
	v_add_co_u32_e32 v48, vcc, 0x1a000, v0
	s_nop 1
	v_addc_co_u32_e32 v49, vcc, 0, v1, vcc
	v_add_co_u32_e32 v50, vcc, 0x1c000, v0
	s_nop 1
	v_addc_co_u32_e32 v51, vcc, 0, v1, vcc
	v_add_co_u32_e32 v52, vcc, 0x1e000, v0
	s_nop 1
	v_addc_co_u32_e32 v53, vcc, 0, v1, vcc
	global_load_dword v61, v[2:3], off
	global_load_dword v62, v[4:5], off
	global_load_dword v63, v[6:7], off
	global_load_dword v64, v[44:45], off
	global_load_dword v65, v[46:47], off
	global_load_dword v66, v[48:49], off
	global_load_dword v67, v[50:51], off
	global_load_dword v68, v[52:53], off
	v_add_co_u32_e32 v2, vcc, 0x20000, v0
	s_nop 1
	v_addc_co_u32_e32 v3, vcc, 0, v1, vcc
	v_add_co_u32_e32 v4, vcc, 0x22000, v0
	s_nop 1
	v_addc_co_u32_e32 v5, vcc, 0, v1, vcc
	v_add_co_u32_e32 v6, vcc, 0x24000, v0
	s_nop 1
	v_addc_co_u32_e32 v7, vcc, 0, v1, vcc
	v_add_co_u32_e32 v44, vcc, 0x26000, v0
	s_nop 1
	v_addc_co_u32_e32 v45, vcc, 0, v1, vcc
	v_add_co_u32_e32 v46, vcc, 0x28000, v0
	s_nop 1
	v_addc_co_u32_e32 v47, vcc, 0, v1, vcc
	v_add_co_u32_e32 v48, vcc, 0x2a000, v0
	s_nop 1
	v_addc_co_u32_e32 v49, vcc, 0, v1, vcc
	v_add_co_u32_e32 v50, vcc, 0x2c000, v0
	s_nop 1
	v_addc_co_u32_e32 v51, vcc, 0, v1, vcc
	v_add_co_u32_e32 v52, vcc, 0x2e000, v0
	s_nop 1
	v_addc_co_u32_e32 v53, vcc, 0, v1, vcc
	global_load_dword v69, v[2:3], off
	global_load_dword v70, v[4:5], off
	global_load_dword v71, v[6:7], off
	global_load_dword v72, v[44:45], off
	global_load_dword v73, v[46:47], off
	global_load_dword v74, v[48:49], off
	global_load_dword v75, v[50:51], off
	s_nop 0
	global_load_dword v52, v[52:53], off
	v_add_co_u32_e32 v2, vcc, 0x30000, v0
	s_nop 1
	v_addc_co_u32_e32 v3, vcc, 0, v1, vcc
	v_add_co_u32_e32 v4, vcc, 0x32000, v0
	s_nop 1
	v_addc_co_u32_e32 v5, vcc, 0, v1, vcc
	v_add_co_u32_e32 v6, vcc, 0x34000, v0
	s_nop 1
	v_addc_co_u32_e32 v7, vcc, 0, v1, vcc
	v_add_co_u32_e32 v44, vcc, 0x36000, v0
	s_nop 1
	v_addc_co_u32_e32 v45, vcc, 0, v1, vcc
	v_add_co_u32_e32 v46, vcc, 0x38000, v0
	s_nop 1
	v_addc_co_u32_e32 v47, vcc, 0, v1, vcc
	v_add_co_u32_e32 v48, vcc, 0x3a000, v0
	s_nop 1
	v_addc_co_u32_e32 v49, vcc, 0, v1, vcc
	v_add_co_u32_e32 v50, vcc, 0x3c000, v0
	s_nop 1
	v_addc_co_u32_e32 v51, vcc, 0, v1, vcc
	v_add_co_u32_e32 v0, vcc, 0x3e000, v0
	s_nop 1
	v_addc_co_u32_e32 v1, vcc, 0, v1, vcc
	global_load_dword v2, v[2:3], off
	s_nop 0
	global_load_dword v3, v[4:5], off
	s_nop 0
	global_load_dword v4, v[6:7], off
	global_load_dword v5, v[44:45], off
	s_nop 0
	global_load_dword v6, v[46:47], off
	global_load_dword v7, v[48:49], off
	global_load_dword v44, v[50:51], off
	s_nop 0
	global_load_dword v0, v[0:1], off
	s_waitcnt vmcnt(16)
	s_waitcnt vmcnt(0)
	ds_write2_b32 v31, v27, v54 offset1:66
	ds_write2_b32 v31, v55, v56 offset0:132 offset1:198
	ds_write2_b32 v37, v57, v58 offset0:8 offset1:74
	ds_write2_b32 v37, v59, v60 offset0:140 offset1:206
	ds_write2_b32 v38, v61, v62 offset0:16 offset1:82
	ds_write2_b32 v38, v63, v64 offset0:148 offset1:214
	ds_write2_b32 v39, v65, v66 offset0:24 offset1:90
	ds_write2_b32 v39, v67, v68 offset0:156 offset1:222
	ds_write2_b32 v40, v69, v70 offset0:32 offset1:98
	ds_write2_b32 v40, v71, v72 offset0:164 offset1:230
	ds_write2_b32 v41, v73, v74 offset0:40 offset1:106
	ds_write2_b32 v41, v75, v52 offset0:172 offset1:238
	ds_write2_b32 v42, v2, v3 offset0:48 offset1:114
	ds_write2_b32 v42, v4, v5 offset0:180 offset1:246
	ds_write2_b32 v43, v6, v7 offset0:56 offset1:122
	ds_write2_b32 v43, v44, v0 offset0:188 offset1:254
	s_waitcnt lgkmcnt(0)
	ds_read2_b32 v[4:5], v33 offset0:33 offset1:41
	ds_read2_b32 v[6:7], v33 offset1:8
	ds_read2_b32 v[44:45], v33 offset0:66 offset1:74
	ds_read2_b32 v[46:47], v33 offset0:99 offset1:107
	ds_read2_b32 v[48:49], v33 offset0:132 offset1:140
	ds_read2_b32 v[50:51], v33 offset0:165 offset1:173
	ds_read2_b32 v[52:53], v33 offset0:198 offset1:206
	ds_read2_b32 v[54:55], v33 offset0:231 offset1:239
	s_waitcnt lgkmcnt(6)
	v_cvt_pk_bf16_f32 v0, v6, v4
	v_or_b32_e32 v4, s26, v32
	v_lshl_add_u64 v[56:57], s[16:17], 1, v[14:15]
	v_lshlrev_b32_e32 v58, 11, v4
	v_mov_b32_e32 v59, v9
	s_waitcnt lgkmcnt(4)
	v_cvt_pk_bf16_f32 v1, v44, v46
	s_waitcnt lgkmcnt(2)
	v_cvt_pk_bf16_f32 v2, v48, v50
	s_waitcnt lgkmcnt(0)
	v_cvt_pk_bf16_f32 v3, v52, v54
	v_lshl_add_u64 v[58:59], v[56:57], 0, v[58:59]
	global_store_dwordx4 v[58:59], v[0:3], off sc1
	v_or_b32_e32 v4, s26, v34
	v_lshlrev_b32_e32 v4, 11, v4
	v_cvt_pk_bf16_f32 v0, v7, v5
	v_cvt_pk_bf16_f32 v1, v45, v47
	v_cvt_pk_bf16_f32 v2, v49, v51
	v_cvt_pk_bf16_f32 v3, v53, v55
	ds_read2_b32 v[6:7], v33 offset0:49 offset1:57
	ds_read2_b32 v[44:45], v33 offset0:16 offset1:24
	ds_read2_b32 v[46:47], v33 offset0:82 offset1:90
	ds_read2_b32 v[48:49], v33 offset0:115 offset1:123
	ds_read2_b32 v[50:51], v33 offset0:148 offset1:156
	ds_read2_b32 v[52:53], v33 offset0:181 offset1:189
	ds_read2_b32 v[54:55], v33 offset0:214 offset1:222
	ds_read2_b32 v[58:59], v33 offset0:247 offset1:255
	v_mov_b32_e32 v5, v9
	v_lshl_add_u64 v[4:5], v[56:57], 0, v[4:5]
	global_store_dwordx4 v[4:5], v[0:3], off sc1
	v_or_b32_e32 v4, s26, v35
	v_lshlrev_b32_e32 v4, 11, v4
	v_mov_b32_e32 v5, v9
	s_waitcnt lgkmcnt(6)
	v_cvt_pk_bf16_f32 v0, v44, v6
	s_waitcnt lgkmcnt(4)
	v_cvt_pk_bf16_f32 v1, v46, v48
	s_waitcnt lgkmcnt(2)
	v_cvt_pk_bf16_f32 v2, v50, v52
	s_waitcnt lgkmcnt(0)
	v_cvt_pk_bf16_f32 v3, v54, v58
	v_lshl_add_u64 v[4:5], v[56:57], 0, v[4:5]
	global_store_dwordx4 v[4:5], v[0:3], off sc1
	v_or_b32_e32 v4, s26, v36
	v_lshlrev_b32_e32 v4, 11, v4
	v_mov_b32_e32 v5, v9
	v_cvt_pk_bf16_f32 v0, v45, v7
	v_cvt_pk_bf16_f32 v1, v47, v49
	v_cvt_pk_bf16_f32 v2, v51, v53
	v_cvt_pk_bf16_f32 v3, v55, v59
	v_lshl_add_u64 v[4:5], v[56:57], 0, v[4:5]
	global_store_dwordx4 v[4:5], v[0:3], off sc1
	s_waitcnt lgkmcnt(0)

.LBB0_74:
	v_add_u32_e32 v5, s0, v5
	v_cmp_lt_i32_e32 vcc, s1, v5
	global_store_dwordx4 v[6:7], v[0:3], off sc1
	s_or_b64 s[8:9], vcc, s[8:9]
	v_lshl_add_u64 v[6:7], v[6:7], 0, s[6:7]
	s_andn2_b64 exec, exec, s[8:9]
	s_cbranch_execnz .LBB0_74

.LBB0_155:
	v_lshl_add_u64 v[26:27], s[0:1], 0, v[24:25]
	v_add_co_u32_e32 v28, vcc, 0x5000000, v26
	s_add_u32 s12, s0, s10
	s_nop 0
	v_addc_co_u32_e32 v29, vcc, 0, v27, vcc
	s_mov_b32 s2, 0x5001000
	s_addc_u32 s13, s1, s11
	v_add_co_u32_e32 v26, vcc, s2, v26
	s_add_u32 s2, s12, 0x700000
	s_nop 0
	v_addc_co_u32_e32 v27, vcc, 0, v27, vcc
	s_addc_u32 s3, s13, 0
	global_load_dwordx2 v[60:61], v[28:29], off
	global_load_dwordx2 v[56:57], v[28:29], off offset:512
	global_load_dwordx2 v[20:21], v[28:29], off offset:1024
	global_load_dwordx2 v[18:19], v[28:29], off offset:1536
	global_load_dwordx2 v[48:49], v[28:29], off offset:2048
	global_load_dwordx2 v[46:47], v[28:29], off offset:2560
	global_load_dwordx2 v[44:45], v[28:29], off offset:3072
	global_load_dwordx2 v[40:41], v[28:29], off offset:3584
	global_load_dwordx2 v[42:43], v[26:27], off
	global_load_dwordx2 v[38:39], v[26:27], off offset:512
	global_load_dwordx2 v[36:37], v[26:27], off offset:1024
	global_load_dwordx2 v[34:35], v[26:27], off offset:1536
	global_load_dwordx2 v[32:33], v[26:27], off offset:2048
	global_load_dwordx2 v[30:31], v[26:27], off offset:2560
	global_load_dwordx2 v[28:29], v[26:27], off offset:3072
	s_nop 0
	global_load_dwordx2 v[26:27], v[26:27], off offset:3584
	s_nop 0
	global_load_dwordx4 v[50:53], v0, s[2:3] offset:48
	global_load_dwordx4 v[62:65], v0, s[2:3] offset:32
	global_load_dwordx4 v[66:69], v0, s[2:3] offset:16
	global_load_dwordx4 v[70:73], v78, s[12:13]
	v_lshl_add_u64 v[24:25], v[24:25], 0, s[26:27]
	s_waitcnt vmcnt(2)
	v_add_f32_e32 v62, v62, v63
	s_waitcnt vmcnt(1)
	v_mov_b32_e32 v58, v67
	s_waitcnt vmcnt(0)
	v_mov_b32_e32 v54, v71
	v_mov_b32_e32 v55, v72
	v_mov_b32_e32 v71, v73
	v_mov_b32_e32 v59, v68
	v_mov_b32_e32 v67, v69
	v_pk_add_f32 v[54:55], v[54:55], v[70:71]
	v_pk_add_f32 v[58:59], v[58:59], v[66:67]
	v_pk_add_f32 v[54:55], v[54:55], v[54:55] op_sel:[0,1] op_sel_hi:[1,0]
	v_pk_add_f32 v[58:59], v[58:59], v[58:59] op_sel:[0,1] op_sel_hi:[1,0]
	v_add_f32_e32 v64, v64, v65
	v_mov_b32_e32 v55, v50
	v_mov_b32_e32 v59, v51
	v_mov_b32_e32 v63, v52
	v_mov_b32_e32 v65, v53
	v_pk_add_f32 v[50:51], v[54:55], v[58:59]
	v_pk_add_f32 v[52:53], v[62:63], v[64:65]
	s_nop 0
	v_pk_add_f32 v[50:51], v[50:51], v[52:53]
	s_nop 0
	v_add_f32_e32 v1, v50, v51
	v_fmamk_f32 v1, v1, 0x3a800000, v235
	v_cmp_gt_f32_e32 vcc, s64, v1
	v_mul_f32_e32 v50, 0x4f800000, v1
	s_nop 0
	v_cndmask_b32_e32 v1, v1, v50, vcc
	v_sqrt_f32_e32 v50, v1
	s_nop 0
	v_add_u32_e32 v51, -1, v50
	v_fma_f32 v52, -v51, v50, v1
	v_cmp_ge_f32_e64 s[2:3], 0, v52
	v_add_u32_e32 v52, 1, v50
	s_nop 0
	v_cndmask_b32_e64 v51, v50, v51, s[2:3]
	v_fma_f32 v50, -v52, v50, v1
	v_cmp_lt_f32_e64 s[2:3], 0, v50
	s_nop 1
	v_cndmask_b32_e64 v50, v51, v52, s[2:3]
	v_mul_f32_e32 v51, 0x37800000, v50
	v_cndmask_b32_e32 v50, v50, v51, vcc
	v_cmp_class_f32_e32 vcc, v1, v79
	s_nop 1
	v_cndmask_b32_e32 v1, v50, v1, vcc
	v_div_scale_f32 v50, s[2:3], v1, v1, 1.0
	v_rcp_f32_e32 v51, v50
	s_add_u32 s2, s12, 0x700040
	s_addc_u32 s3, s13, 0
	v_fma_f32 v52, -v50, v51, 1.0
	v_fmac_f32_e32 v51, v52, v51
	v_div_scale_f32 v52, vcc, 1.0, v1, 1.0
	v_mul_f32_e32 v53, v52, v51
	v_fma_f32 v54, -v50, v53, v52
	v_fmac_f32_e32 v53, v54, v51
	v_fma_f32 v50, -v50, v53, v52
	v_div_fmas_f32 v50, v50, v51, v53
	v_div_fixup_f32 v58, v50, v1, 1.0
	global_load_dwordx4 v[50:53], v0, s[2:3] offset:48
	global_load_dwordx4 v[62:65], v0, s[2:3] offset:32
	global_load_dwordx4 v[66:69], v0, s[2:3] offset:16
	global_load_dwordx4 v[70:73], v78, s[12:13] offset:64
	s_waitcnt vmcnt(2)
	v_add_f32_e32 v62, v62, v63
	v_add_f32_e32 v64, v64, v65
	s_waitcnt vmcnt(0)
	v_mov_b32_e32 v54, v71
	v_mov_b32_e32 v55, v72
	v_mov_b32_e32 v71, v73
	v_pk_add_f32 v[54:55], v[54:55], v[70:71]
	v_mov_b32_e32 v70, v67
	v_mov_b32_e32 v71, v68
	v_mov_b32_e32 v67, v69
	v_pk_add_f32 v[66:67], v[70:71], v[66:67]
	v_pk_add_f32 v[54:55], v[54:55], v[54:55] op_sel:[0,1] op_sel_hi:[1,0]
	v_pk_add_f32 v[66:67], v[66:67], v[66:67] op_sel:[0,1] op_sel_hi:[1,0]
	v_mov_b32_e32 v55, v50
	v_mov_b32_e32 v67, v51
	v_mov_b32_e32 v63, v52
	v_mov_b32_e32 v65, v53
	v_pk_add_f32 v[50:51], v[54:55], v[66:67]
	v_pk_add_f32 v[52:53], v[62:63], v[64:65]
	s_nop 0
	v_pk_add_f32 v[50:51], v[50:51], v[52:53]
	s_nop 0
	v_add_f32_e32 v1, v50, v51
	v_fmamk_f32 v1, v1, 0x3a800000, v235
	v_cmp_gt_f32_e32 vcc, s64, v1
	v_mul_f32_e32 v50, 0x4f800000, v1
	s_nop 0
	v_cndmask_b32_e32 v1, v1, v50, vcc
	v_sqrt_f32_e32 v50, v1
	s_nop 0
	v_add_u32_e32 v51, -1, v50
	v_fma_f32 v52, -v51, v50, v1
	v_cmp_ge_f32_e64 s[2:3], 0, v52
	v_add_u32_e32 v52, 1, v50
	s_nop 0
	v_cndmask_b32_e64 v51, v50, v51, s[2:3]
	v_fma_f32 v50, -v52, v50, v1
	v_cmp_lt_f32_e64 s[2:3], 0, v50
	s_nop 1
	v_cndmask_b32_e64 v50, v51, v52, s[2:3]
	v_mul_f32_e32 v51, 0x37800000, v50
	v_cndmask_b32_e32 v50, v50, v51, vcc
	v_cmp_class_f32_e32 vcc, v1, v79
	s_nop 1
	v_cndmask_b32_e32 v1, v50, v1, vcc
	v_div_scale_f32 v50, s[2:3], v1, v1, 1.0
	v_rcp_f32_e32 v51, v50
	s_add_u32 s2, s12, 0x700080
	s_addc_u32 s3, s13, 0
	v_fma_f32 v52, -v50, v51, 1.0
	v_fmac_f32_e32 v51, v52, v51
	v_div_scale_f32 v52, vcc, 1.0, v1, 1.0
	v_mul_f32_e32 v53, v52, v51
	v_fma_f32 v54, -v50, v53, v52
	v_fmac_f32_e32 v53, v54, v51
	v_fma_f32 v50, -v50, v53, v52
	v_div_fmas_f32 v50, v50, v51, v53
	v_div_fixup_f32 v54, v50, v1, 1.0
	global_load_dwordx4 v[50:53], v0, s[2:3] offset:48
	global_load_dwordx4 v[62:65], v0, s[2:3] offset:32
	global_load_dwordx4 v[66:69], v0, s[2:3] offset:16
	global_load_dwordx4 v[70:73], v78, s[12:13] offset:128
	s_waitcnt vmcnt(2)
	v_add_f32_e32 v62, v62, v63
	v_add_f32_e32 v64, v64, v65
	s_waitcnt vmcnt(0)
	v_mov_b32_e32 v74, v71
	v_mov_b32_e32 v75, v72
	v_mov_b32_e32 v71, v73
	v_mov_b32_e32 v72, v67
	v_mov_b32_e32 v73, v68
	v_mov_b32_e32 v67, v69
	v_pk_add_f32 v[70:71], v[74:75], v[70:71]
	v_pk_add_f32 v[66:67], v[72:73], v[66:67]
	v_pk_add_f32 v[70:71], v[70:71], v[70:71] op_sel:[0,1] op_sel_hi:[1,0]
	v_pk_add_f32 v[66:67], v[66:67], v[66:67] op_sel:[0,1] op_sel_hi:[1,0]
	v_mov_b32_e32 v71, v50
	v_mov_b32_e32 v67, v51
	v_mov_b32_e32 v63, v52
	v_mov_b32_e32 v65, v53
	v_pk_add_f32 v[50:51], v[70:71], v[66:67]
	v_pk_add_f32 v[52:53], v[62:63], v[64:65]
	s_nop 0
	v_pk_add_f32 v[50:51], v[50:51], v[52:53]
	s_nop 0
	v_add_f32_e32 v1, v50, v51
	v_fmamk_f32 v1, v1, 0x3a800000, v235
	v_cmp_gt_f32_e32 vcc, s64, v1
	v_mul_f32_e32 v50, 0x4f800000, v1
	s_nop 0
	v_cndmask_b32_e32 v1, v1, v50, vcc
	v_sqrt_f32_e32 v50, v1
	s_nop 0
	v_add_u32_e32 v51, -1, v50
	v_fma_f32 v52, -v51, v50, v1
	v_cmp_ge_f32_e64 s[2:3], 0, v52
	v_add_u32_e32 v52, 1, v50
	s_nop 0
	v_cndmask_b32_e64 v51, v50, v51, s[2:3]
	v_fma_f32 v50, -v52, v50, v1
	v_cmp_lt_f32_e64 s[2:3], 0, v50
	s_nop 1
	v_cndmask_b32_e64 v50, v51, v52, s[2:3]
	v_mul_f32_e32 v51, 0x37800000, v50
	v_cndmask_b32_e32 v50, v50, v51, vcc
	v_cmp_class_f32_e32 vcc, v1, v79
	s_nop 1
	v_cndmask_b32_e32 v1, v50, v1, vcc
	v_div_scale_f32 v50, s[2:3], v1, v1, 1.0
	s_add_u32 s2, s12, 0x7000c0
	s_addc_u32 s3, s13, 0
	s_nop 2
	global_load_dwordx4 v[62:65], v0, s[2:3] offset:48
	global_load_dwordx4 v[66:69], v0, s[2:3] offset:32
	global_load_dwordx4 v[70:73], v0, s[2:3] offset:16
	global_load_dwordx4 v[74:77], v78, s[12:13] offset:192
	v_rcp_f32_e32 v51, v50
	s_add_i32 s6, s6, s14
	s_add_u32 s10, s10, s20
	s_addc_u32 s11, s11, s21
	v_fma_f32 v52, -v50, v51, 1.0
	v_fmac_f32_e32 v51, v52, v51
	v_div_scale_f32 v52, vcc, 1.0, v1, 1.0
	v_mul_f32_e32 v53, v52, v51
	v_fma_f32 v55, -v50, v53, v52
	v_fmac_f32_e32 v53, v55, v51
	v_fma_f32 v50, -v50, v53, v52
	v_div_fmas_f32 v50, v50, v51, v53
	v_div_fixup_f32 v50, v50, v1, 1.0
	s_cmp_lt_i32 s6, 0x8000
	s_waitcnt vmcnt(2)
	v_add_f32_e32 v66, v66, v67
	v_add_f32_e32 v68, v68, v69
	s_waitcnt vmcnt(0)
	v_mov_b32_e32 v52, v75
	v_mov_b32_e32 v53, v76
	v_mov_b32_e32 v75, v77
	v_pk_add_f32 v[52:53], v[52:53], v[74:75]
	v_mov_b32_e32 v74, v71
	v_mov_b32_e32 v75, v72
	v_mov_b32_e32 v71, v73
	v_pk_add_f32 v[70:71], v[74:75], v[70:71]
	v_pk_add_f32 v[52:53], v[52:53], v[52:53] op_sel:[0,1] op_sel_hi:[1,0]
	v_pk_add_f32 v[70:71], v[70:71], v[70:71] op_sel:[0,1] op_sel_hi:[1,0]
	v_mov_b32_e32 v53, v62
	v_mov_b32_e32 v71, v63
	v_mov_b32_e32 v67, v64
	v_mov_b32_e32 v69, v65
	v_pk_add_f32 v[52:53], v[52:53], v[70:71]
	v_pk_add_f32 v[62:63], v[66:67], v[68:69]
	s_nop 0
	v_pk_add_f32 v[52:53], v[52:53], v[62:63]
	v_lshlrev_b32_e32 v62, 16, v60
	v_add_f32_e32 v1, v52, v53
	v_fmamk_f32 v1, v1, 0x3a800000, v235
	v_cmp_gt_f32_e32 vcc, s64, v1
	v_mul_f32_e32 v51, 0x4f800000, v1
	v_and_b32_e32 v63, 0xffff0000, v60
	v_cndmask_b32_e32 v1, v1, v51, vcc
	v_sqrt_f32_e32 v51, v1
	v_lshlrev_b32_e32 v60, 16, v61
	v_and_b32_e32 v61, 0xffff0000, v61
	v_add_u32_e32 v52, -1, v51
	v_fma_f32 v53, -v52, v51, v1
	v_cmp_ge_f32_e64 s[2:3], 0, v53
	v_add_u32_e32 v53, 1, v51
	s_nop 0
	v_cndmask_b32_e64 v52, v51, v52, s[2:3]
	v_fma_f32 v51, -v53, v51, v1
	v_cmp_lt_f32_e64 s[2:3], 0, v51
	s_nop 1
	v_cndmask_b32_e64 v51, v52, v53, s[2:3]
	v_mul_f32_e32 v52, 0x37800000, v51
	v_cndmask_b32_e32 v51, v51, v52, vcc
	v_cmp_class_f32_e32 vcc, v1, v79
	s_nop 1
	v_cndmask_b32_e32 v1, v51, v1, vcc
	v_div_scale_f32 v51, s[2:3], v1, v1, 1.0
	v_rcp_f32_e32 v52, v51
	s_movk_i32 s2, 0xd000
	v_fma_f32 v53, -v51, v52, 1.0
	v_fmac_f32_e32 v52, v53, v52
	v_div_scale_f32 v53, vcc, 1.0, v1, 1.0
	v_mul_f32_e32 v55, v53, v52
	v_fma_f32 v59, -v51, v55, v53
	v_fmac_f32_e32 v55, v59, v52
	v_fma_f32 v51, -v51, v55, v53
	v_pk_mul_f32 v[64:65], v[58:59], v[62:63] op_sel_hi:[0,1]
	v_pk_mul_f32 v[60:61], v[58:59], v[60:61] op_sel_hi:[0,1]
	v_div_fmas_f32 v51, v51, v52, v55
	v_pk_mul_f32 v[62:63], v[4:5], v[60:61]
	v_pk_mul_f32 v[60:61], v[2:3], v[64:65]
	v_add_co_u32_e32 v64, vcc, s2, v22
	s_movk_i32 s2, 0xe000
	s_nop 0
	v_addc_co_u32_e32 v65, vcc, -1, v23, vcc
	global_store_dwordx4 v[64:65], v[60:63], off offset:-3072 sc1
	v_div_fixup_f32 v52, v51, v1, 1.0
	s_nop 0
	v_lshlrev_b32_e32 v60, 16, v56
	v_and_b32_e32 v61, 0xffff0000, v56
	v_lshlrev_b32_e32 v56, 16, v57
	v_and_b32_e32 v57, 0xffff0000, v57
	v_pk_mul_f32 v[56:57], v[58:59], v[56:57] op_sel_hi:[0,1]
	v_pk_mul_f32 v[60:61], v[58:59], v[60:61] op_sel_hi:[0,1]
	v_pk_mul_f32 v[62:63], v[8:9], v[56:57]
	v_lshlrev_b32_e32 v56, 16, v20
	v_and_b32_e32 v57, 0xffff0000, v20
	v_lshlrev_b32_e32 v20, 16, v21
	v_and_b32_e32 v21, 0xffff0000, v21
	v_pk_mul_f32 v[60:61], v[6:7], v[60:61]
	v_pk_mul_f32 v[20:21], v[58:59], v[20:21] op_sel_hi:[0,1]
	global_store_dwordx4 v[64:65], v[60:63], off offset:-2048 sc1
	v_pk_mul_f32 v[56:57], v[58:59], v[56:57] op_sel_hi:[0,1]
	s_nop 0
	v_pk_mul_f32 v[62:63], v[12:13], v[20:21]
	v_lshlrev_b32_e32 v20, 16, v18
	v_and_b32_e32 v21, 0xffff0000, v18
	v_lshlrev_b32_e32 v18, 16, v19
	v_and_b32_e32 v19, 0xffff0000, v19
	v_pk_mul_f32 v[60:61], v[10:11], v[56:57]
	v_pk_mul_f32 v[56:57], v[58:59], v[20:21] op_sel_hi:[0,1]
	v_pk_mul_f32 v[18:19], v[58:59], v[18:19] op_sel_hi:[0,1]
	v_pk_mul_f32 v[20:21], v[16:17], v[18:19]
	v_pk_mul_f32 v[18:19], v[14:15], v[56:57]
	v_add_co_u32_e32 v56, vcc, s2, v22
	s_movk_i32 s2, 0xf000
	s_nop 0
	v_addc_co_u32_e32 v57, vcc, -1, v23, vcc
	global_store_dwordx4 v[56:57], v[18:21], off offset:-4096 sc1
	global_store_dwordx4 v[64:65], v[60:63], off offset:-1024 sc1
	s_nop 0
	v_lshlrev_b32_e32 v18, 16, v48
	v_and_b32_e32 v19, 0xffff0000, v48
	v_lshlrev_b32_e32 v20, 16, v49
	v_and_b32_e32 v21, 0xffff0000, v49
	v_pk_mul_f32 v[18:19], v[54:55], v[18:19] op_sel_hi:[0,1]
	v_pk_mul_f32 v[20:21], v[54:55], v[20:21] op_sel_hi:[0,1]
	v_pk_mul_f32 v[20:21], v[4:5], v[20:21]
	v_pk_mul_f32 v[18:19], v[2:3], v[18:19]
	global_store_dwordx4 v[56:57], v[18:21], off offset:-3072 sc1
	s_nop 1
	v_lshlrev_b32_e32 v18, 16, v46
	v_and_b32_e32 v19, 0xffff0000, v46
	v_lshlrev_b32_e32 v20, 16, v47
	v_and_b32_e32 v21, 0xffff0000, v47
	v_pk_mul_f32 v[18:19], v[54:55], v[18:19] op_sel_hi:[0,1]
	v_pk_mul_f32 v[20:21], v[54:55], v[20:21] op_sel_hi:[0,1]
	v_pk_mul_f32 v[20:21], v[8:9], v[20:21]
	v_pk_mul_f32 v[18:19], v[6:7], v[18:19]
	global_store_dwordx4 v[56:57], v[18:21], off offset:-2048 sc1
	s_nop 1
	v_lshlrev_b32_e32 v18, 16, v44
	v_and_b32_e32 v19, 0xffff0000, v44
	v_lshlrev_b32_e32 v20, 16, v45
	v_and_b32_e32 v21, 0xffff0000, v45
	v_pk_mul_f32 v[18:19], v[54:55], v[18:19] op_sel_hi:[0,1]
	v_pk_mul_f32 v[20:21], v[54:55], v[20:21] op_sel_hi:[0,1]
	v_pk_mul_f32 v[20:21], v[12:13], v[20:21]
	v_pk_mul_f32 v[18:19], v[10:11], v[18:19]
	global_store_dwordx4 v[56:57], v[18:21], off offset:-1024 sc1
	s_nop 1
	v_lshlrev_b32_e32 v18, 16, v40
	v_and_b32_e32 v19, 0xffff0000, v40
	v_lshlrev_b32_e32 v20, 16, v41
	v_and_b32_e32 v21, 0xffff0000, v41
	v_pk_mul_f32 v[18:19], v[54:55], v[18:19] op_sel_hi:[0,1]
	v_pk_mul_f32 v[20:21], v[54:55], v[20:21] op_sel_hi:[0,1]
	v_pk_mul_f32 v[20:21], v[16:17], v[20:21]
	v_pk_mul_f32 v[18:19], v[14:15], v[18:19]
	global_store_dwordx4 v[56:57], v[18:21], off sc1
	v_add_co_u32_e32 v40, vcc, s2, v22
	s_nop 0
	v_lshlrev_b32_e32 v18, 16, v42
	v_and_b32_e32 v19, 0xffff0000, v42
	v_lshlrev_b32_e32 v20, 16, v43
	v_and_b32_e32 v21, 0xffff0000, v43
	v_pk_mul_f32 v[18:19], v[50:51], v[18:19] op_sel_hi:[0,1]
	v_pk_mul_f32 v[20:21], v[50:51], v[20:21] op_sel_hi:[0,1]
	v_pk_mul_f32 v[20:21], v[4:5], v[20:21]
	v_pk_mul_f32 v[18:19], v[2:3], v[18:19]
	v_addc_co_u32_e32 v41, vcc, -1, v23, vcc
	global_store_dwordx4 v[40:41], v[18:21], off offset:-3072 sc1
	s_nop 1
	v_lshlrev_b32_e32 v18, 16, v38
	v_and_b32_e32 v19, 0xffff0000, v38
	v_lshlrev_b32_e32 v20, 16, v39
	v_and_b32_e32 v21, 0xffff0000, v39
	v_pk_mul_f32 v[18:19], v[50:51], v[18:19] op_sel_hi:[0,1]
	v_pk_mul_f32 v[20:21], v[50:51], v[20:21] op_sel_hi:[0,1]
	v_pk_mul_f32 v[20:21], v[8:9], v[20:21]
	v_pk_mul_f32 v[18:19], v[6:7], v[18:19]
	global_store_dwordx4 v[40:41], v[18:21], off offset:-2048 sc1
	s_nop 1
	v_lshlrev_b32_e32 v18, 16, v36
	v_and_b32_e32 v19, 0xffff0000, v36
	v_lshlrev_b32_e32 v20, 16, v37
	v_and_b32_e32 v21, 0xffff0000, v37
	v_pk_mul_f32 v[18:19], v[50:51], v[18:19] op_sel_hi:[0,1]
	v_pk_mul_f32 v[20:21], v[50:51], v[20:21] op_sel_hi:[0,1]
	v_pk_mul_f32 v[20:21], v[12:13], v[20:21]
	v_pk_mul_f32 v[18:19], v[10:11], v[18:19]
	global_store_dwordx4 v[40:41], v[18:21], off offset:-1024 sc1
	s_nop 1
	v_lshlrev_b32_e32 v18, 16, v34
	v_and_b32_e32 v19, 0xffff0000, v34
	v_lshlrev_b32_e32 v20, 16, v35
	v_and_b32_e32 v21, 0xffff0000, v35
	v_pk_mul_f32 v[18:19], v[50:51], v[18:19] op_sel_hi:[0,1]
	v_pk_mul_f32 v[20:21], v[50:51], v[20:21] op_sel_hi:[0,1]
	v_pk_mul_f32 v[20:21], v[16:17], v[20:21]
	v_pk_mul_f32 v[18:19], v[14:15], v[18:19]
	global_store_dwordx4 v[22:23], v[18:21], off offset:-4096 sc1
	s_nop 1
	v_lshlrev_b32_e32 v18, 16, v32
	v_and_b32_e32 v19, 0xffff0000, v32
	v_lshlrev_b32_e32 v20, 16, v33
	v_and_b32_e32 v21, 0xffff0000, v33
	v_pk_mul_f32 v[18:19], v[52:53], v[18:19] op_sel_hi:[0,1]
	v_pk_mul_f32 v[20:21], v[52:53], v[20:21] op_sel_hi:[0,1]
	v_pk_mul_f32 v[20:21], v[4:5], v[20:21]
	v_pk_mul_f32 v[18:19], v[2:3], v[18:19]
	global_store_dwordx4 v[22:23], v[18:21], off offset:-3072 sc1
	s_nop 1
	v_lshlrev_b32_e32 v18, 16, v30
	v_and_b32_e32 v19, 0xffff0000, v30
	v_lshlrev_b32_e32 v20, 16, v31
	v_and_b32_e32 v21, 0xffff0000, v31
	v_pk_mul_f32 v[18:19], v[52:53], v[18:19] op_sel_hi:[0,1]
	v_pk_mul_f32 v[20:21], v[52:53], v[20:21] op_sel_hi:[0,1]
	v_pk_mul_f32 v[20:21], v[8:9], v[20:21]
	v_pk_mul_f32 v[18:19], v[6:7], v[18:19]
	global_store_dwordx4 v[22:23], v[18:21], off offset:-2048 sc1
	s_nop 1
	v_lshlrev_b32_e32 v18, 16, v28
	v_and_b32_e32 v19, 0xffff0000, v28
	v_lshlrev_b32_e32 v20, 16, v29
	v_and_b32_e32 v21, 0xffff0000, v29
	v_pk_mul_f32 v[18:19], v[52:53], v[18:19] op_sel_hi:[0,1]
	v_pk_mul_f32 v[20:21], v[52:53], v[20:21] op_sel_hi:[0,1]
	v_pk_mul_f32 v[20:21], v[12:13], v[20:21]
	v_pk_mul_f32 v[18:19], v[10:11], v[18:19]
	global_store_dwordx4 v[22:23], v[18:21], off offset:-1024 sc1
	s_nop 1
	v_lshlrev_b32_e32 v18, 16, v26
	v_and_b32_e32 v19, 0xffff0000, v26
	v_lshlrev_b32_e32 v20, 16, v27
	v_and_b32_e32 v21, 0xffff0000, v27
	v_pk_mul_f32 v[18:19], v[52:53], v[18:19] op_sel_hi:[0,1]
	v_pk_mul_f32 v[20:21], v[52:53], v[20:21] op_sel_hi:[0,1]
	v_pk_mul_f32 v[20:21], v[16:17], v[20:21]
	v_pk_mul_f32 v[18:19], v[14:15], v[18:19]
	global_store_dwordx4 v[22:23], v[18:21], off sc1
	v_lshl_add_u64 v[22:23], v[22:23], 0, s[16:17]
	s_cbranch_scc1 .LBB0_155

.LBB0_198:
	global_load_dwordx4 v[12:15], v[4:5], off
	v_ashrrev_i32_e32 v11, 31, v10
	v_lshlrev_b64 v[16:17], 11, v[10:11]
	s_waitcnt vmcnt(11)
	v_lshl_add_u64 v[128:129], v[2:3], 0, v[16:17]
	global_load_dwordx4 v[16:19], v[128:129], off
	global_load_dwordx4 v[20:23], v[4:5], off offset:64
	global_load_dwordx4 v[24:27], v[128:129], off offset:64
	global_load_dwordx4 v[28:31], v[4:5], off offset:128
	global_load_dwordx4 v[32:35], v[4:5], off offset:192
	global_load_dwordx4 v[36:39], v[128:129], off offset:128
	global_load_dwordx4 v[40:43], v[128:129], off offset:192
	global_load_dwordx4 v[44:47], v[4:5], off offset:256
	global_load_dwordx4 v[48:51], v[4:5], off offset:320
	global_load_dwordx4 v[52:55], v[4:5], off offset:960
	global_load_dwordx4 v[56:59], v[128:129], off offset:960
	global_load_dwordx4 v[60:63], v[128:129], off offset:256
	global_load_dwordx4 v[64:67], v[128:129], off offset:320
	global_load_dwordx4 v[68:71], v[4:5], off offset:384
	global_load_dwordx4 v[72:75], v[4:5], off offset:448
	global_load_dwordx4 v[76:79], v[128:129], off offset:384
	global_load_dwordx4 v[80:83], v[128:129], off offset:448
	global_load_dwordx4 v[84:87], v[4:5], off offset:512
	global_load_dwordx4 v[88:91], v[4:5], off offset:576
	global_load_dwordx4 v[92:95], v[128:129], off offset:512
	global_load_dwordx4 v[96:99], v[128:129], off offset:576
	global_load_dwordx4 v[100:103], v[4:5], off offset:640
	global_load_dwordx4 v[104:107], v[4:5], off offset:704
	global_load_dwordx4 v[108:111], v[128:129], off offset:640
	global_load_dwordx4 v[112:115], v[4:5], off offset:768
	global_load_dwordx4 v[116:119], v[128:129], off offset:704
	v_lshlrev_b64 v[130:131], 6, v[10:11]
	v_lshl_add_u64 v[132:133], s[6:7], 0, v[130:131]
	s_add_i32 s4, s4, s72
	s_cmpk_lt_i32 s4, 0x800
	v_add_u32_e32 v10, s2, v10
	s_waitcnt vmcnt(25)
	v_mfma_f32_16x16x32_bf16 v[12:15], v[12:15], v[16:19], 0
	global_load_dwordx4 v[16:19], v[128:129], off offset:768
	global_load_dwordx4 v[120:123], v[4:5], off offset:896
	global_load_dwordx4 v[124:127], v[4:5], off offset:832
	s_waitcnt vmcnt(26)
	v_mfma_f32_16x16x32_bf16 v[12:15], v[20:23], v[24:27], v[12:15]
	global_load_dwordx4 v[20:23], v[128:129], off offset:896
	s_waitcnt vmcnt(24)
	v_mfma_f32_16x16x32_bf16 v[12:15], v[28:31], v[36:39], v[12:15]
	global_load_dwordx4 v[24:27], v[128:129], off offset:832
	global_load_dwordx4 v[28:31], v[132:133], off offset:48
	global_load_dwordx4 v[36:39], v[132:133], off offset:32
	s_waitcnt vmcnt(26)
	v_mfma_f32_16x16x32_bf16 v[12:15], v[32:35], v[40:43], v[12:15]
	global_load_dwordx4 v[32:35], v[132:133], off offset:16
	global_load_dwordx4 v[40:43], v[132:133], off
	s_waitcnt vmcnt(24)
	s_waitcnt vmcnt(23)
	v_mfma_f32_16x16x32_bf16 v[12:15], v[44:47], v[60:63], v[12:15]
	global_load_dwordx4 v[44:47], v[4:5], off offset:1024
	global_load_dwordx4 v[60:63], v[4:5], off offset:1088
	s_waitcnt vmcnt(24)
	v_mfma_f32_16x16x32_bf16 v[12:15], v[48:51], v[64:67], v[12:15]
	global_load_dwordx4 v[48:51], v[128:129], off offset:1024
	global_load_dwordx4 v[64:67], v[128:129], off offset:1088
	s_waitcnt vmcnt(23)
	v_mfma_f32_16x16x32_bf16 v[12:15], v[68:71], v[76:79], v[12:15]
	global_load_dwordx4 v[68:71], v[4:5], off offset:1152
	global_load_dwordx4 v[76:79], v[4:5], off offset:1216
	s_waitcnt vmcnt(24)
	v_mfma_f32_16x16x32_bf16 v[12:15], v[72:75], v[80:83], v[12:15]
	global_load_dwordx4 v[72:75], v[128:129], off offset:1152
	global_load_dwordx4 v[80:83], v[128:129], off offset:1216
	s_waitcnt vmcnt(23)
	v_mfma_f32_16x16x32_bf16 v[12:15], v[84:87], v[92:95], v[12:15]
	global_load_dwordx4 v[84:87], v[4:5], off offset:1280
	global_load_dwordx4 v[92:95], v[128:129], off offset:1280
	s_waitcnt vmcnt(24)
	v_mfma_f32_16x16x32_bf16 v[12:15], v[88:91], v[96:99], v[12:15]
	global_load_dwordx4 v[88:91], v[4:5], off offset:1344
	global_load_dwordx4 v[96:99], v[128:129], off offset:1344
	s_waitcnt vmcnt(23)
	v_mfma_f32_16x16x32_bf16 v[12:15], v[100:103], v[108:111], v[12:15]
	s_waitcnt vmcnt(21)
	v_mfma_f32_16x16x32_bf16 v[12:15], v[104:107], v[116:119], v[12:15]
	global_load_dwordx4 v[100:103], v[4:5], off offset:1408
	global_load_dwordx4 v[104:107], v[128:129], off offset:1984
	global_load_dwordx4 v[108:111], v[4:5], off offset:1984
	s_waitcnt vmcnt(23)
	v_mfma_f32_16x16x32_bf16 v[12:15], v[112:115], v[16:19], v[12:15]
	global_load_dwordx4 v[16:19], v[128:129], off offset:1408
	s_waitcnt vmcnt(20)
	v_mfma_f32_16x16x32_bf16 v[12:15], v[124:127], v[24:27], v[12:15]
	global_load_dwordx4 v[24:27], v[4:5], off offset:1472
	global_load_dwordx4 v[112:115], v[128:129], off offset:1472
	v_mfma_f32_16x16x32_bf16 v[12:15], v[120:123], v[20:23], v[12:15]
	global_load_dwordx4 v[20:23], v[4:5], off offset:1536
	global_load_dwordx4 v[116:119], v[4:5], off offset:1600
	v_mfma_f32_16x16x32_bf16 v[12:15], v[52:55], v[56:59], v[12:15]
	global_load_dwordx4 v[52:55], v[128:129], off offset:1536
	global_load_dwordx4 v[56:59], v[128:129], off offset:1600
	s_waitcnt vmcnt(19)
	v_mfma_f32_16x16x32_bf16 v[12:15], v[44:47], v[48:51], v[12:15]
	global_load_dwordx4 v[44:47], v[4:5], off offset:1664
	global_load_dwordx4 v[48:51], v[4:5], off offset:1728
	s_waitcnt vmcnt(20)
	v_mfma_f32_16x16x32_bf16 v[12:15], v[60:63], v[64:67], v[12:15]
	global_load_dwordx4 v[60:63], v[128:129], off offset:1664
	global_load_dwordx4 v[64:67], v[128:129], off offset:1728
	s_waitcnt vmcnt(19)
	v_mfma_f32_16x16x32_bf16 v[12:15], v[68:71], v[72:75], v[12:15]
	global_load_dwordx4 v[68:71], v[4:5], off offset:1792
	global_load_dwordx4 v[72:75], v[128:129], off offset:1792
	s_waitcnt vmcnt(20)
	v_mfma_f32_16x16x32_bf16 v[12:15], v[76:79], v[80:83], v[12:15]
	global_load_dwordx4 v[76:79], v[4:5], off offset:1856
	global_load_dwordx4 v[80:83], v[4:5], off offset:1920
	s_waitcnt vmcnt(20)
	v_mfma_f32_16x16x32_bf16 v[12:15], v[84:87], v[92:95], v[12:15]
	global_load_dwordx4 v[84:87], v[128:129], off offset:1856
	s_waitcnt vmcnt(19)
	v_mfma_f32_16x16x32_bf16 v[12:15], v[88:91], v[96:99], v[12:15]
	global_load_dwordx4 v[88:91], v[128:129], off offset:1920
	s_waitcnt vmcnt(17)
	s_waitcnt vmcnt(16)
	v_mfma_f32_16x16x32_bf16 v[12:15], v[100:103], v[16:19], v[12:15]
	global_load_dwordx4 v[16:19], v[6:7], off
	s_waitcnt vmcnt(15)
	v_mfma_f32_16x16x32_bf16 v[12:15], v[24:27], v[112:115], v[12:15]
	v_mov_b32_e32 v26, v41
	v_mov_b32_e32 v27, v42
	v_mov_b32_e32 v41, v43
	v_pk_add_f32 v[26:27], v[26:27], v[40:41]
	s_waitcnt vmcnt(12)
	v_mfma_f32_16x16x32_bf16 v[12:15], v[20:23], v[52:55], v[12:15]
	v_mov_b32_e32 v20, v33
	v_mov_b32_e32 v21, v34
	v_mov_b32_e32 v33, v35
	s_waitcnt vmcnt(11)
	v_mfma_f32_16x16x32_bf16 v[12:15], v[116:119], v[56:59], v[12:15]
	v_add_f32_e64 v20, v20, v32
	v_add_f32_e64 v21, v21, v33
	v_pk_add_f32 v[26:27], v[26:27], v[26:27] op_sel:[0,1] op_sel_hi:[1,0]
	v_pk_add_f32 v[20:21], v[20:21], v[20:21] op_sel:[0,1] op_sel_hi:[1,0]
	s_waitcnt vmcnt(8)
	v_mfma_f32_16x16x32_bf16 v[12:15], v[44:47], v[60:63], v[12:15]
	v_add_f32_e32 v22, v36, v37
	v_add_f32_e32 v34, v38, v39
	v_mov_b32_e32 v23, v30
	s_waitcnt vmcnt(7)
	v_mfma_f32_16x16x32_bf16 v[12:15], v[48:51], v[64:67], v[12:15]
	v_mov_b32_e32 v35, v31
	v_mov_b32_e32 v27, v28
	v_mov_b32_e32 v21, v29
	s_waitcnt vmcnt(5)
	v_mfma_f32_16x16x32_bf16 v[12:15], v[68:71], v[72:75], v[12:15]
	v_add_f32_e64 v22, v22, v34
	v_add_f32_e64 v23, v23, v35
	v_pk_add_f32 v[20:21], v[26:27], v[20:21]
	v_lshl_add_u64 v[24:25], v[8:9], 0, v[130:131]
	s_waitcnt vmcnt(2)
	v_mfma_f32_16x16x32_bf16 v[12:15], v[76:79], v[84:87], v[12:15]
	v_add_f32_e64 v20, v20, v22
	v_add_f32_e64 v21, v21, v23
	v_add_f32_e32 v11, v20, v21
	s_waitcnt vmcnt(1)
	v_mfma_f32_16x16x32_bf16 v[12:15], v[80:83], v[88:91], v[12:15]
	v_fmamk_f32 v11, v11, 0x3a800000, v235
	v_rsq_f32_e32 v11, v11
	v_mfma_f32_16x16x32_bf16 v[12:15], v[108:111], v[104:107], v[12:15]
	s_waitcnt vmcnt(0)
	s_nop 6
	v_fma_f32 v12, v11, v12, v16
	v_fma_f32 v13, v11, v13, v17
	v_fma_f32 v14, v11, v14, v18
	v_fmac_f32_e32 v19, v11, v15
	v_mul_f32_e64 v11, |v12|, s66
	v_mul_f32_e64 v16, |v13|, s66
	v_mul_f32_e64 v17, |v14|, s66
	v_mul_f32_e64 v18, |v19|, s66
	v_exp_f32_e32 v11, v11
	v_exp_f32_e32 v16, v16
	v_exp_f32_e32 v17, v17
	v_exp_f32_e32 v18, v18
	v_add_f32_e32 v11, 1.0, v11
	v_add_f32_e32 v16, 1.0, v16
	v_add_f32_e32 v17, 1.0, v17
	v_add_f32_e32 v18, 1.0, v18
	v_min_f32_e32 v15, 0, v19
	v_log_f32_e32 v18, v18
	v_log_f32_e32 v19, v17
	v_log_f32_e32 v20, v16
	v_log_f32_e32 v11, v11
	v_min_f32_e32 v12, 0, v12
	v_min_f32_e32 v13, 0, v13
	v_min_f32_e32 v14, 0, v14
	v_xor_b32_e32 v17, 0x80000000, v18
	v_xor_b32_e32 v16, 0x80000000, v19
	v_xor_b32_e32 v19, 0x80000000, v20
	v_xor_b32_e32 v18, 0x80000000, v11
	v_pk_fma_f32 v[14:15], v[14:15], s[10:11], v[16:17] op_sel_hi:[1,0,1]
	v_pk_fma_f32 v[12:13], v[12:13], s[10:11], v[18:19] op_sel_hi:[1,0,1]
	global_store_dwordx4 v[24:25], v[12:15], off sc1
	s_cbranch_scc1 .LBB0_198
	v_readlane_b32 s2, v255, 6
	s_nop 1
	v_mov_b32_e32 v2, s2
	ds_read_b64 v[2:3], v2

.LBB0_222:
	v_lshl_add_u32 v186, s43, 8, v207
	v_or_b32_e32 v182, 16, v186
	v_or_b32_e32 v178, 32, v186
	v_ashrrev_i32_e32 v187, 31, v186
	v_ashrrev_i32_e32 v183, 31, v182
	v_ashrrev_i32_e32 v179, 31, v178
	v_or_b32_e32 v174, 48, v186
	v_add_u32_e32 v170, 0x80, v186
	v_lshlrev_b64 v[188:189], 6, v[186:187]
	v_lshlrev_b64 v[184:185], 6, v[182:183]
	v_lshlrev_b64 v[180:181], 6, v[178:179]
	v_ashrrev_i32_e32 v175, 31, v174
	v_ashrrev_i32_e32 v171, 31, v170
	v_add_u32_e32 v166, 0x90, v186
	v_lshl_add_u64 v[130:131], v[150:151], 0, v[188:189]
	v_lshl_add_u64 v[134:135], v[150:151], 0, v[184:185]
	v_lshl_add_u64 v[158:159], v[150:151], 0, v[180:181]
	v_lshlrev_b64 v[176:177], 6, v[174:175]
	v_lshlrev_b64 v[172:173], 6, v[170:171]
	v_ashrrev_i32_e32 v167, 31, v166
	global_load_dwordx4 v[130:133], v[130:131], off
	s_nop 0
	global_load_dwordx4 v[134:137], v[134:135], off
	v_lshl_add_u64 v[160:161], v[150:151], 0, v[176:177]
	global_load_dwordx4 v[194:197], v[158:159], off
	global_load_dwordx4 v[198:201], v[160:161], off
	v_lshl_add_u64 v[158:159], v[150:151], 0, v[172:173]
	v_lshlrev_b64 v[168:169], 6, v[166:167]
	v_add_u32_e32 v162, 0xa0, v186
	v_lshl_add_u64 v[160:161], v[150:151], 0, v[168:169]
	global_load_dwordx4 v[210:213], v[158:159], off
	global_load_dwordx4 v[226:229], v[160:161], off
	v_ashrrev_i32_e32 v163, 31, v162
	v_add_u32_e32 v158, 0xb0, v186
	v_lshlrev_b64 v[164:165], 6, v[162:163]
	v_ashrrev_i32_e32 v159, 31, v158
	v_lshl_add_u64 v[214:215], v[150:151], 0, v[164:165]
	v_lshlrev_b64 v[160:161], 6, v[158:159]
	v_lshl_add_u64 v[216:217], v[150:151], 0, v[160:161]
	global_load_dwordx4 v[244:247], v[214:215], off
	global_load_dwordx4 v[248:251], v[216:217], off
	s_cmp_lt_i32 s33, 4
	s_cselect_b64 s[4:5], -1, 0
	s_cmp_gt_i32 s33, 7
	s_cselect_b64 s[24:25], -1, 0
	s_mov_b64 s[26:27], -1
	s_and_b64 vcc, exec, s[24:25]
	s_waitcnt vmcnt(0)
	v_add_f32_e32 v214, v130, v131
	v_add_f32_e32 v215, v132, v133
	v_add_f32_e32 v130, v214, v215
	v_add_f32_e32 v133, v194, v195
	v_mov_b32_e32 v195, v130
	s_nop 1
	v_permlane16_swap_b32_e32 v130, v195
	v_add_f32_e32 v130, v130, v195
	v_add_f32_e32 v131, v134, v135
	v_add_f32_e32 v132, v136, v137
	v_mov_b32_e32 v195, v130
	v_add_f32_e32 v134, v196, v197
	v_add_f32_e32 v135, v198, v199
	v_add_f32_e32 v136, v200, v201
	v_add_f32_e32 v131, v131, v132
	v_permlane32_swap_b32_e32 v130, v195
	v_add_f32_e32 v132, v133, v134
	v_add_f32_e32 v133, v135, v136
	v_mov_b32_e32 v135, v131
	v_add_f32_e32 v130, v130, v195
	s_nop 0
	v_permlane16_swap_b32_e32 v131, v135
	v_fmamk_f32 v130, v130, 0x3a800000, v235
	v_add_f32_e32 v222, v131, v135
	v_rsq_f32_e32 v224, v130
	v_add_f32_e32 v130, v226, v227
	v_add_f32_e32 v131, v228, v229
	v_add_f32_e32 v130, v130, v131
	v_mov_b32_e32 v131, v130
	s_nop 1
	v_permlane16_swap_b32_e32 v130, v131
	v_add_f32_e32 v214, v130, v131
	v_add_f32_e32 v130, v244, v245
	v_add_f32_e32 v131, v246, v247
	v_add_f32_e32 v130, v130, v131
	v_mov_b32_e32 v131, v130
	s_nop 1
	v_permlane16_swap_b32_e32 v130, v131
	v_add_f32_e32 v137, v210, v211
	v_add_f32_e32 v194, v212, v213
	v_add_f32_e32 v212, v130, v131
	v_add_f32_e32 v130, v248, v249
	v_add_f32_e32 v131, v250, v251
	v_add_f32_e32 v134, v137, v194
	v_add_f32_e32 v130, v130, v131
	v_mov_b32_e32 v136, v132
	v_mov_b32_e32 v137, v133
	v_mov_b32_e32 v194, v134
	v_mov_b32_e32 v131, v130
	v_permlane16_swap_b32_e32 v132, v136
	v_permlane16_swap_b32_e32 v133, v137
	v_permlane16_swap_b32_e32 v134, v194
	v_permlane16_swap_b32_e32 v130, v131
	v_add_f32_e32 v220, v132, v136
	v_add_f32_e32 v218, v133, v137
	v_add_f32_e32 v216, v134, v194
	v_add_f32_e32 v210, v130, v131
	v_mov_b32_e32 v223, v222
	v_mov_b32_e32 v221, v220
	v_mov_b32_e32 v219, v218
	v_mov_b32_e32 v217, v216
	v_mov_b32_e32 v215, v214
	v_mov_b32_e32 v213, v212
	v_mov_b32_e32 v211, v210
	v_permlane32_swap_b32_e32 v222, v223
	v_permlane32_swap_b32_e32 v220, v221
	v_permlane32_swap_b32_e32 v218, v219
	v_permlane32_swap_b32_e32 v216, v217
	v_permlane32_swap_b32_e32 v214, v215
	v_permlane32_swap_b32_e32 v212, v213
	v_permlane32_swap_b32_e32 v210, v211
	s_cbranch_vccz .LBB0_226
	s_and_saveexec_b64 s[26:27], s[14:15]
	s_cbranch_execz .LBB0_225
	global_load_dwordx4 v[132:135], v[152:153], off offset:16
	global_load_dwordx4 v[194:197], v[152:153], off
	s_mov_b32 s44, 0x3fb8aa3b
	v_lshl_add_u64 v[188:189], v[148:149], 0, v[188:189]
	s_waitcnt vmcnt(1)
	v_fma_f32 v132, v122, v224, v132
	s_waitcnt vmcnt(0)
	v_fma_f32 v130, v126, v224, v194
	v_mul_f32_e64 v131, |v130|, s66
	v_exp_f32_e32 v131, v131
	v_fmac_f32_e32 v197, v129, v224
	v_min_f32_e32 v130, 0, v130
	v_fmac_f32_e32 v135, v125, v224
	v_add_f32_e32 v131, 1.0, v131
	v_log_f32_e32 v198, v131
	v_fma_f32 v131, v127, v224, v195
	v_mul_f32_e64 v136, |v131|, s66
	v_exp_f32_e32 v136, v136
	v_min_f32_e32 v131, 0, v131
	v_add_f32_e32 v136, 1.0, v136
	v_log_f32_e32 v199, v136
	v_fma_f32 v136, v128, v224, v196
	v_mul_f32_e64 v137, |v136|, s66
	v_exp_f32_e32 v137, v137
	v_min_f32_e32 v136, 0, v136
	v_add_f32_e32 v137, 1.0, v137
	v_log_f32_e32 v196, v137
	v_mul_f32_e64 v137, |v197|, s66
	v_exp_f32_e32 v194, v137
	v_min_f32_e32 v137, 0, v197
	v_add_f32_e32 v194, 1.0, v194
	v_log_f32_e32 v197, v194
	v_mul_f32_e64 v194, |v132|, s66
	v_exp_f32_e32 v195, v194
	v_min_f32_e32 v194, 0, v132
	v_add_f32_e32 v132, 1.0, v195
	v_log_f32_e32 v200, v132
	v_fma_f32 v132, v123, v224, v133
	v_mul_f32_e64 v133, |v132|, s66
	v_exp_f32_e32 v133, v133
	v_min_f32_e32 v195, 0, v132
	v_add_f32_e32 v132, 1.0, v133
	v_log_f32_e32 v201, v132
	v_fma_f32 v132, v124, v224, v134
	v_mul_f32_e64 v133, |v132|, s66
	v_exp_f32_e32 v133, v133
	v_min_f32_e32 v134, 0, v132
	v_add_f32_e32 v132, 1.0, v133
	v_log_f32_e32 v225, v132
	v_xor_b32_e32 v133, 0x80000000, v197
	v_xor_b32_e32 v132, 0x80000000, v196
	v_pk_fma_f32 v[132:133], v[136:137], s[44:45], v[132:133] op_sel_hi:[1,0,1]
	v_xor_b32_e32 v137, 0x80000000, v199
	v_xor_b32_e32 v136, 0x80000000, v198
	v_pk_fma_f32 v[130:131], v[130:131], s[44:45], v[136:137] op_sel_hi:[1,0,1]
	v_mul_f32_e64 v136, |v135|, s66
	v_exp_f32_e32 v136, v136
	v_min_f32_e32 v135, 0, v135
	v_add_f32_e32 v136, 1.0, v136
	v_log_f32_e32 v136, v136
	s_nop 0
	v_xor_b32_e32 v137, 0x80000000, v136
	v_xor_b32_e32 v136, 0x80000000, v225
	v_pk_fma_f32 v[136:137], v[134:135], s[44:45], v[136:137] op_sel_hi:[1,0,1]
	v_xor_b32_e32 v135, 0x80000000, v201
	v_xor_b32_e32 v134, 0x80000000, v200
	v_pk_fma_f32 v[134:135], v[194:195], s[44:45], v[134:135] op_sel_hi:[1,0,1]
	global_store_dwordx4 v[188:189], v[130:133], off sc1
	global_store_dwordx4 v[188:189], v[134:137], off offset:16 sc1

.LBB0_226:
	s_lshr_b32 s98, s33, 2
	s_lshl_b32 s98, s98, 26
	s_lshr_b32 s99, s43, 4
	s_lshl_b32 s99, s99, 4
	s_and_b32 s100, s33, 3
	s_lshl_b32 s100, s100, 2
	s_add_i32 s99, s99, s100
	s_and_b32 s100, s71, 3
	s_lshr_b32 s100, s100, 1
	s_add_i32 s99, s99, s100
	s_lshl_b32 s99, s99, 19
	s_add_u32 s98, s98, s99
	s_add_u32 s98, s96, s98
	s_addc_u32 s99, s97, 0
	s_and_b32 s100, s43, 15
	s_lshl_b32 s100, s100, 15
	s_lshr_b32 s101, s71, 2
	s_lshl_b32 s101, s101, 13
	s_add_i32 s100, s100, s101
	s_and_b32 s101, s71, 1
	s_lshl_b32 s101, s101, 11
	s_add_i32 s100, s100, s101
	v_and_b32_e32 v130, 15, v207
	v_and_b32_e32 v136, 3, v130
	v_and_b32_e32 v137, 4, v130
	v_lshl_or_b32 v136, v137, 1, v136
	v_and_b32_e32 v137, 8, v130
	v_lshrrev_b32_e32 v137, 1, v137
	v_or_b32_e32 v136, v136, v137
	v_cndmask_b32_e64 v130, v136, v130, s[4:5]
	v_lshlrev_b32_e32 v130, 4, v130
	v_and_b32_e32 v136, 31, v147
	v_lshl_add_u32 v130, v136, 6, v130
	v_add_u32_e32 v130, s100, v130
	v_lshrrev_b32_e32 v130, 1, v130
	s_mov_b32 s100, 0x100000
	s_mov_b32 s101, 0
	v_cndmask_b32_e64 v132, 1.0, v240, s[4:5]
	s_andn2_b64 vcc, exec, s[26:27]
	v_ashrrev_i32_e32 v131, 31, v130
	s_cbranch_vccnz .LBB0_228
	v_mul_f32_e32 v134, v132, v224
	v_mov_b64_e32 v[136:137], 0
	v_pk_mul_f32 v[126:127], v[126:127], v[134:135] op_sel_hi:[1,0]
	v_pk_mul_f32 v[128:129], v[128:129], v[134:135] op_sel_hi:[1,0]
	v_pk_mul_f32 v[186:187], v[124:125], v[134:135] op_sel_hi:[1,0]
	v_pk_mul_f32 v[124:125], v[122:123], v[134:135] op_sel_hi:[1,0]
	v_cvt_pk_bf16_f32 v122, v126, v127
	v_lshl_add_u64 v[126:127], s[98:99], 0, v[136:137]
	v_cvt_pk_bf16_f32 v123, v128, v129
	v_cvt_pk_bf16_f32 v124, v124, v125
	v_cvt_pk_bf16_f32 v125, v186, v187
	v_lshl_add_u64 v[126:127], v[130:131], 1, v[126:127]
	global_store_dwordx4 v[126:127], v[122:125], off sc1
	v_pk_mul_f32 v[120:121], v[120:121], v[134:135] op_sel_hi:[1,0]
	v_pk_mul_f32 v[118:119], v[118:119], v[134:135] op_sel_hi:[1,0]
	v_pk_mul_f32 v[122:123], v[116:117], v[134:135] op_sel_hi:[1,0]
	v_pk_mul_f32 v[116:117], v[114:115], v[134:135] op_sel_hi:[1,0]
	v_cvt_pk_bf16_f32 v114, v118, v119
	v_cvt_pk_bf16_f32 v115, v120, v121
	v_cvt_pk_bf16_f32 v116, v116, v117
	v_cvt_pk_bf16_f32 v117, v122, v123
	v_lshl_add_u64 v[126:127], v[126:127], 0, s[100:101]
	global_store_dwordx4 v[126:127], v[114:117], off sc1
.LBB0_228:
	s_nop 1
	v_add_f32_e32 v114, v222, v223
	v_fmamk_f32 v114, v114, 0x3a800000, v235
	v_rsq_f32_e32 v122, v114
	v_cndmask_b32_e64 v114, 0, 1, s[24:25]
	v_cmp_ne_u32_e64 s[4:5], 1, v114
	s_andn2_b64 vcc, exec, s[24:25]
	s_mov_b64 s[24:25], -1
	s_cbranch_vccnz .LBB0_232
	s_and_saveexec_b64 s[24:25], s[14:15]
	s_cbranch_execz .LBB0_231
	global_load_dwordx4 v[118:121], v[152:153], off offset:16
	global_load_dwordx4 v[114:117], v[152:153], off
	s_mov_b32 s26, 0x3fb8aa3b
	s_waitcnt vmcnt(1)
	v_fma_f32 v119, v107, v122, v119
	s_waitcnt vmcnt(0)
	v_fma_f32 v115, v111, v122, v115
	v_mul_f32_e64 v124, |v115|, s66
	v_exp_f32_e32 v124, v124
	v_fma_f32 v116, v112, v122, v116
	v_fmac_f32_e32 v117, v113, v122
	v_fma_f32 v114, v110, v122, v114
	v_add_f32_e32 v124, 1.0, v124
	v_log_f32_e32 v126, v124
	v_mul_f32_e64 v124, |v116|, s66
	v_mul_f32_e64 v125, |v117|, s66
	v_mul_f32_e64 v123, |v114|, s66
	v_exp_f32_e32 v124, v124
	v_exp_f32_e32 v125, v125
	v_exp_f32_e32 v123, v123
	v_min_f32_e32 v116, 0, v116
	v_add_f32_e32 v124, 1.0, v124
	v_add_f32_e32 v125, 1.0, v125
	v_add_f32_e32 v123, 1.0, v123
	v_log_f32_e32 v124, v124
	v_log_f32_e32 v125, v125
	v_log_f32_e32 v123, v123
	v_min_f32_e32 v117, 0, v117
	v_xor_b32_e32 v124, 0x80000000, v124
	v_xor_b32_e32 v125, 0x80000000, v125
	v_min_f32_e32 v114, 0, v114
	v_min_f32_e32 v115, 0, v115
	v_pk_fma_f32 v[116:117], v[116:117], s[26:27], v[124:125] op_sel_hi:[1,0,1]
	v_xor_b32_e32 v125, 0x80000000, v126
	v_xor_b32_e32 v124, 0x80000000, v123
	v_pk_fma_f32 v[114:115], v[114:115], s[26:27], v[124:125] op_sel_hi:[1,0,1]
	v_mul_f32_e64 v124, |v119|, s66
	v_exp_f32_e32 v124, v124
	v_fma_f32 v120, v108, v122, v120
	v_fmac_f32_e32 v121, v109, v122
	v_fma_f32 v118, v106, v122, v118
	v_add_f32_e32 v124, 1.0, v124
	v_log_f32_e32 v126, v124
	v_mul_f32_e64 v124, |v120|, s66
	v_mul_f32_e64 v125, |v121|, s66
	v_mul_f32_e64 v123, |v118|, s66
	v_exp_f32_e32 v124, v124
	v_exp_f32_e32 v125, v125
	v_exp_f32_e32 v123, v123
	v_min_f32_e32 v120, 0, v120
	v_add_f32_e32 v124, 1.0, v124
	v_add_f32_e32 v125, 1.0, v125
	v_add_f32_e32 v123, 1.0, v123
	v_log_f32_e32 v124, v124
	v_log_f32_e32 v125, v125
	v_log_f32_e32 v123, v123
	v_min_f32_e32 v121, 0, v121
	v_xor_b32_e32 v124, 0x80000000, v124
	v_xor_b32_e32 v125, 0x80000000, v125
	v_min_f32_e32 v118, 0, v118
	v_min_f32_e32 v119, 0, v119
	v_pk_fma_f32 v[120:121], v[120:121], s[26:27], v[124:125] op_sel_hi:[1,0,1]
	v_xor_b32_e32 v125, 0x80000000, v126
	v_xor_b32_e32 v124, 0x80000000, v123
	v_pk_fma_f32 v[118:119], v[118:119], s[26:27], v[124:125] op_sel_hi:[1,0,1]
	v_lshl_add_u64 v[124:125], v[148:149], 0, v[184:185]
	global_store_dwordx4 v[124:125], v[114:117], off sc1
	global_store_dwordx4 v[124:125], v[118:121], off offset:16 sc1

.LBB0_232:
	s_andn2_b64 vcc, exec, s[24:25]
	s_cbranch_vccnz .LBB0_234
	v_mul_f32_e32 v114, v132, v122
	v_mov_b64_e32 v[116:117], 0x100
	v_pk_mul_f32 v[110:111], v[110:111], v[114:115] op_sel_hi:[1,0]
	v_pk_mul_f32 v[112:113], v[112:113], v[114:115] op_sel_hi:[1,0]
	v_pk_mul_f32 v[118:119], v[108:109], v[114:115] op_sel_hi:[1,0]
	v_pk_mul_f32 v[108:109], v[106:107], v[114:115] op_sel_hi:[1,0]
	v_cvt_pk_bf16_f32 v106, v110, v111
	v_lshl_add_u64 v[110:111], s[98:99], 0, v[116:117]
	v_cvt_pk_bf16_f32 v107, v112, v113
	v_cvt_pk_bf16_f32 v108, v108, v109
	v_cvt_pk_bf16_f32 v109, v118, v119
	v_lshl_add_u64 v[110:111], v[130:131], 1, v[110:111]
	global_store_dwordx4 v[110:111], v[106:109], off sc1
	v_pk_mul_f32 v[104:105], v[104:105], v[114:115] op_sel_hi:[1,0]
	v_pk_mul_f32 v[102:103], v[102:103], v[114:115] op_sel_hi:[1,0]
	v_pk_mul_f32 v[106:107], v[100:101], v[114:115] op_sel_hi:[1,0]
	v_pk_mul_f32 v[100:101], v[98:99], v[114:115] op_sel_hi:[1,0]
	v_cvt_pk_bf16_f32 v98, v102, v103
	v_cvt_pk_bf16_f32 v99, v104, v105
	v_cvt_pk_bf16_f32 v100, v100, v101
	v_cvt_pk_bf16_f32 v101, v106, v107
	v_lshl_add_u64 v[110:111], v[110:111], 0, s[100:101]
	global_store_dwordx4 v[110:111], v[98:101], off sc1
.LBB0_234:
	s_nop 1
	v_add_f32_e32 v98, v220, v221
	v_fmamk_f32 v98, v98, 0x3a800000, v235
	v_rsq_f32_e32 v106, v98
	s_and_b64 vcc, exec, s[4:5]
	s_mov_b64 s[24:25], -1
	s_cbranch_vccnz .LBB0_238
	s_and_saveexec_b64 s[24:25], s[14:15]
	s_cbranch_execz .LBB0_237
	global_load_dwordx4 v[102:105], v[152:153], off offset:16
	global_load_dwordx4 v[98:101], v[152:153], off
	s_mov_b32 s26, 0x3fb8aa3b
	s_waitcnt vmcnt(1)
	v_fma_f32 v103, v91, v106, v103
	s_waitcnt vmcnt(0)
	v_fma_f32 v99, v95, v106, v99
	v_mul_f32_e64 v108, |v99|, s66
	v_exp_f32_e32 v108, v108
	v_fma_f32 v100, v96, v106, v100
	v_fmac_f32_e32 v101, v97, v106
	v_fma_f32 v98, v94, v106, v98
	v_add_f32_e32 v108, 1.0, v108
	v_log_f32_e32 v110, v108
	v_mul_f32_e64 v108, |v100|, s66
	v_mul_f32_e64 v109, |v101|, s66
	v_mul_f32_e64 v107, |v98|, s66
	v_exp_f32_e32 v108, v108
	v_exp_f32_e32 v109, v109
	v_exp_f32_e32 v107, v107
	v_min_f32_e32 v100, 0, v100
	v_add_f32_e32 v108, 1.0, v108
	v_add_f32_e32 v109, 1.0, v109
	v_add_f32_e32 v107, 1.0, v107
	v_log_f32_e32 v108, v108
	v_log_f32_e32 v109, v109
	v_log_f32_e32 v107, v107
	v_min_f32_e32 v101, 0, v101
	v_xor_b32_e32 v108, 0x80000000, v108
	v_xor_b32_e32 v109, 0x80000000, v109
	v_min_f32_e32 v98, 0, v98
	v_min_f32_e32 v99, 0, v99
	v_pk_fma_f32 v[100:101], v[100:101], s[26:27], v[108:109] op_sel_hi:[1,0,1]
	v_xor_b32_e32 v109, 0x80000000, v110
	v_xor_b32_e32 v108, 0x80000000, v107
	v_pk_fma_f32 v[98:99], v[98:99], s[26:27], v[108:109] op_sel_hi:[1,0,1]
	v_mul_f32_e64 v108, |v103|, s66
	v_exp_f32_e32 v108, v108
	v_fma_f32 v104, v92, v106, v104
	v_fmac_f32_e32 v105, v93, v106
	v_fma_f32 v102, v90, v106, v102
	v_add_f32_e32 v108, 1.0, v108
	v_log_f32_e32 v110, v108
	v_mul_f32_e64 v108, |v104|, s66
	v_mul_f32_e64 v109, |v105|, s66
	v_mul_f32_e64 v107, |v102|, s66
	v_exp_f32_e32 v108, v108
	v_exp_f32_e32 v109, v109
	v_exp_f32_e32 v107, v107
	v_min_f32_e32 v104, 0, v104
	v_add_f32_e32 v108, 1.0, v108
	v_add_f32_e32 v109, 1.0, v109
	v_add_f32_e32 v107, 1.0, v107
	v_log_f32_e32 v108, v108
	v_log_f32_e32 v109, v109
	v_log_f32_e32 v107, v107
	v_min_f32_e32 v105, 0, v105
	v_xor_b32_e32 v108, 0x80000000, v108
	v_xor_b32_e32 v109, 0x80000000, v109
	v_min_f32_e32 v102, 0, v102
	v_min_f32_e32 v103, 0, v103
	v_pk_fma_f32 v[104:105], v[104:105], s[26:27], v[108:109] op_sel_hi:[1,0,1]
	v_xor_b32_e32 v109, 0x80000000, v110
	v_xor_b32_e32 v108, 0x80000000, v107
	v_pk_fma_f32 v[102:103], v[102:103], s[26:27], v[108:109] op_sel_hi:[1,0,1]
	v_lshl_add_u64 v[108:109], v[148:149], 0, v[180:181]
	global_store_dwordx4 v[108:109], v[98:101], off sc1
	global_store_dwordx4 v[108:109], v[102:105], off offset:16 sc1

.LBB0_238:
	s_andn2_b64 vcc, exec, s[24:25]
	s_cbranch_vccnz .LBB0_240
	v_mul_f32_e32 v98, v132, v106
	v_mov_b64_e32 v[100:101], 0x1000
	v_pk_mul_f32 v[94:95], v[94:95], v[98:99] op_sel_hi:[1,0]
	v_pk_mul_f32 v[96:97], v[96:97], v[98:99] op_sel_hi:[1,0]
	v_pk_mul_f32 v[102:103], v[92:93], v[98:99] op_sel_hi:[1,0]
	v_pk_mul_f32 v[92:93], v[90:91], v[98:99] op_sel_hi:[1,0]
	v_cvt_pk_bf16_f32 v90, v94, v95
	v_lshl_add_u64 v[94:95], s[98:99], 0, v[100:101]
	v_cvt_pk_bf16_f32 v91, v96, v97
	v_cvt_pk_bf16_f32 v92, v92, v93
	v_cvt_pk_bf16_f32 v93, v102, v103
	v_lshl_add_u64 v[94:95], v[130:131], 1, v[94:95]
	global_store_dwordx4 v[94:95], v[90:93], off sc1
	v_pk_mul_f32 v[88:89], v[88:89], v[98:99] op_sel_hi:[1,0]
	v_pk_mul_f32 v[86:87], v[86:87], v[98:99] op_sel_hi:[1,0]
	v_pk_mul_f32 v[90:91], v[84:85], v[98:99] op_sel_hi:[1,0]
	v_pk_mul_f32 v[84:85], v[82:83], v[98:99] op_sel_hi:[1,0]
	v_cvt_pk_bf16_f32 v82, v86, v87
	v_cvt_pk_bf16_f32 v83, v88, v89
	v_cvt_pk_bf16_f32 v84, v84, v85
	v_cvt_pk_bf16_f32 v85, v90, v91
	v_lshl_add_u64 v[94:95], v[94:95], 0, s[100:101]
	global_store_dwordx4 v[94:95], v[82:85], off sc1
.LBB0_240:
	s_nop 1
	v_add_f32_e32 v82, v218, v219
	v_fmamk_f32 v82, v82, 0x3a800000, v235
	v_rsq_f32_e32 v90, v82
	s_and_b64 vcc, exec, s[4:5]
	s_mov_b64 s[24:25], -1
	s_cbranch_vccnz .LBB0_244
	s_and_saveexec_b64 s[24:25], s[14:15]
	s_cbranch_execz .LBB0_243
	global_load_dwordx4 v[86:89], v[152:153], off offset:16
	global_load_dwordx4 v[82:85], v[152:153], off
	s_mov_b32 s26, 0x3fb8aa3b
	s_waitcnt vmcnt(1)
	v_fma_f32 v87, v75, v90, v87
	s_waitcnt vmcnt(0)
	v_fma_f32 v83, v79, v90, v83
	v_mul_f32_e64 v92, |v83|, s66
	v_exp_f32_e32 v92, v92
	v_fma_f32 v84, v80, v90, v84
	v_fmac_f32_e32 v85, v81, v90
	v_fma_f32 v82, v78, v90, v82
	v_add_f32_e32 v92, 1.0, v92
	v_log_f32_e32 v94, v92
	v_mul_f32_e64 v92, |v84|, s66
	v_mul_f32_e64 v93, |v85|, s66
	v_mul_f32_e64 v91, |v82|, s66
	v_exp_f32_e32 v92, v92
	v_exp_f32_e32 v93, v93
	v_exp_f32_e32 v91, v91
	v_min_f32_e32 v84, 0, v84
	v_add_f32_e32 v92, 1.0, v92
	v_add_f32_e32 v93, 1.0, v93
	v_add_f32_e32 v91, 1.0, v91
	v_log_f32_e32 v92, v92
	v_log_f32_e32 v93, v93
	v_log_f32_e32 v91, v91
	v_min_f32_e32 v85, 0, v85
	v_xor_b32_e32 v92, 0x80000000, v92
	v_xor_b32_e32 v93, 0x80000000, v93
	v_min_f32_e32 v82, 0, v82
	v_min_f32_e32 v83, 0, v83
	v_pk_fma_f32 v[84:85], v[84:85], s[26:27], v[92:93] op_sel_hi:[1,0,1]
	v_xor_b32_e32 v93, 0x80000000, v94
	v_xor_b32_e32 v92, 0x80000000, v91
	v_pk_fma_f32 v[82:83], v[82:83], s[26:27], v[92:93] op_sel_hi:[1,0,1]
	v_mul_f32_e64 v92, |v87|, s66
	v_exp_f32_e32 v92, v92
	v_fma_f32 v88, v76, v90, v88
	v_fmac_f32_e32 v89, v77, v90
	v_fma_f32 v86, v74, v90, v86
	v_add_f32_e32 v92, 1.0, v92
	v_log_f32_e32 v94, v92
	v_mul_f32_e64 v92, |v88|, s66
	v_mul_f32_e64 v93, |v89|, s66
	v_mul_f32_e64 v91, |v86|, s66
	v_exp_f32_e32 v92, v92
	v_exp_f32_e32 v93, v93
	v_exp_f32_e32 v91, v91
	v_min_f32_e32 v88, 0, v88
	v_add_f32_e32 v92, 1.0, v92
	v_add_f32_e32 v93, 1.0, v93
	v_add_f32_e32 v91, 1.0, v91
	v_log_f32_e32 v92, v92
	v_log_f32_e32 v93, v93
	v_log_f32_e32 v91, v91
	v_min_f32_e32 v89, 0, v89
	v_xor_b32_e32 v92, 0x80000000, v92
	v_xor_b32_e32 v93, 0x80000000, v93
	v_min_f32_e32 v86, 0, v86
	v_min_f32_e32 v87, 0, v87
	v_pk_fma_f32 v[88:89], v[88:89], s[26:27], v[92:93] op_sel_hi:[1,0,1]
	v_xor_b32_e32 v93, 0x80000000, v94
	v_xor_b32_e32 v92, 0x80000000, v91
	v_pk_fma_f32 v[86:87], v[86:87], s[26:27], v[92:93] op_sel_hi:[1,0,1]
	v_lshl_add_u64 v[92:93], v[148:149], 0, v[176:177]
	global_store_dwordx4 v[92:93], v[82:85], off sc1
	global_store_dwordx4 v[92:93], v[86:89], off offset:16 sc1

.LBB0_244:
	s_andn2_b64 vcc, exec, s[24:25]
	s_cbranch_vccnz .LBB0_246
	v_mul_f32_e32 v82, v132, v90
	v_mov_b64_e32 v[84:85], 0x1100
	v_pk_mul_f32 v[78:79], v[78:79], v[82:83] op_sel_hi:[1,0]
	v_pk_mul_f32 v[80:81], v[80:81], v[82:83] op_sel_hi:[1,0]
	v_pk_mul_f32 v[86:87], v[76:77], v[82:83] op_sel_hi:[1,0]
	v_pk_mul_f32 v[76:77], v[74:75], v[82:83] op_sel_hi:[1,0]
	v_cvt_pk_bf16_f32 v74, v78, v79
	v_lshl_add_u64 v[78:79], s[98:99], 0, v[84:85]
	v_cvt_pk_bf16_f32 v75, v80, v81
	v_cvt_pk_bf16_f32 v76, v76, v77
	v_cvt_pk_bf16_f32 v77, v86, v87
	v_lshl_add_u64 v[78:79], v[130:131], 1, v[78:79]
	global_store_dwordx4 v[78:79], v[74:77], off sc1
	v_pk_mul_f32 v[72:73], v[72:73], v[82:83] op_sel_hi:[1,0]
	v_pk_mul_f32 v[70:71], v[70:71], v[82:83] op_sel_hi:[1,0]
	v_pk_mul_f32 v[74:75], v[68:69], v[82:83] op_sel_hi:[1,0]
	v_pk_mul_f32 v[68:69], v[66:67], v[82:83] op_sel_hi:[1,0]
	v_cvt_pk_bf16_f32 v66, v70, v71
	v_cvt_pk_bf16_f32 v67, v72, v73
	v_cvt_pk_bf16_f32 v68, v68, v69
	v_cvt_pk_bf16_f32 v69, v74, v75
	v_lshl_add_u64 v[78:79], v[78:79], 0, s[100:101]
	global_store_dwordx4 v[78:79], v[66:69], off sc1
.LBB0_246:
	s_nop 1
	v_add_f32_e32 v66, v216, v217
	v_fmamk_f32 v66, v66, 0x3a800000, v235
	v_rsq_f32_e32 v74, v66
	s_and_b64 vcc, exec, s[4:5]
	s_mov_b64 s[24:25], -1
	s_cbranch_vccnz .LBB0_250
	s_and_saveexec_b64 s[24:25], s[14:15]
	s_cbranch_execz .LBB0_249
	global_load_dwordx4 v[70:73], v[152:153], off offset:16
	global_load_dwordx4 v[66:69], v[152:153], off
	s_mov_b32 s26, 0x3fb8aa3b
	s_waitcnt vmcnt(1)
	v_fma_f32 v71, v59, v74, v71
	s_waitcnt vmcnt(0)
	v_fma_f32 v67, v63, v74, v67
	v_mul_f32_e64 v76, |v67|, s66
	v_exp_f32_e32 v76, v76
	v_fma_f32 v68, v64, v74, v68
	v_fmac_f32_e32 v69, v65, v74
	v_fma_f32 v66, v62, v74, v66
	v_add_f32_e32 v76, 1.0, v76
	v_log_f32_e32 v78, v76
	v_mul_f32_e64 v76, |v68|, s66
	v_mul_f32_e64 v77, |v69|, s66
	v_mul_f32_e64 v75, |v66|, s66
	v_exp_f32_e32 v76, v76
	v_exp_f32_e32 v77, v77
	v_exp_f32_e32 v75, v75
	v_min_f32_e32 v68, 0, v68
	v_add_f32_e32 v76, 1.0, v76
	v_add_f32_e32 v77, 1.0, v77
	v_add_f32_e32 v75, 1.0, v75
	v_log_f32_e32 v76, v76
	v_log_f32_e32 v77, v77
	v_log_f32_e32 v75, v75
	v_min_f32_e32 v69, 0, v69
	v_xor_b32_e32 v76, 0x80000000, v76
	v_xor_b32_e32 v77, 0x80000000, v77
	v_min_f32_e32 v66, 0, v66
	v_min_f32_e32 v67, 0, v67
	v_pk_fma_f32 v[68:69], v[68:69], s[26:27], v[76:77] op_sel_hi:[1,0,1]
	v_xor_b32_e32 v77, 0x80000000, v78
	v_xor_b32_e32 v76, 0x80000000, v75
	v_pk_fma_f32 v[66:67], v[66:67], s[26:27], v[76:77] op_sel_hi:[1,0,1]
	v_mul_f32_e64 v76, |v71|, s66
	v_exp_f32_e32 v76, v76
	v_fma_f32 v72, v60, v74, v72
	v_fmac_f32_e32 v73, v61, v74
	v_fma_f32 v70, v58, v74, v70
	v_add_f32_e32 v76, 1.0, v76
	v_log_f32_e32 v78, v76
	v_mul_f32_e64 v76, |v72|, s66
	v_mul_f32_e64 v77, |v73|, s66
	v_mul_f32_e64 v75, |v70|, s66
	v_exp_f32_e32 v76, v76
	v_exp_f32_e32 v77, v77
	v_exp_f32_e32 v75, v75
	v_min_f32_e32 v72, 0, v72
	v_add_f32_e32 v76, 1.0, v76
	v_add_f32_e32 v77, 1.0, v77
	v_add_f32_e32 v75, 1.0, v75
	v_log_f32_e32 v76, v76
	v_log_f32_e32 v77, v77
	v_log_f32_e32 v75, v75
	v_min_f32_e32 v73, 0, v73
	v_xor_b32_e32 v76, 0x80000000, v76
	v_xor_b32_e32 v77, 0x80000000, v77
	v_min_f32_e32 v70, 0, v70
	v_min_f32_e32 v71, 0, v71
	v_pk_fma_f32 v[72:73], v[72:73], s[26:27], v[76:77] op_sel_hi:[1,0,1]
	v_xor_b32_e32 v77, 0x80000000, v78
	v_xor_b32_e32 v76, 0x80000000, v75
	v_pk_fma_f32 v[70:71], v[70:71], s[26:27], v[76:77] op_sel_hi:[1,0,1]
	v_lshl_add_u64 v[76:77], v[148:149], 0, v[172:173]
	global_store_dwordx4 v[76:77], v[66:69], off sc1
	global_store_dwordx4 v[76:77], v[70:73], off offset:16 sc1

.LBB0_250:
	s_andn2_b64 vcc, exec, s[24:25]
	s_cbranch_vccnz .LBB0_252
	v_mul_f32_e32 v66, v132, v74
	v_mov_b64_e32 v[68:69], 0x4000
	v_pk_mul_f32 v[62:63], v[62:63], v[66:67] op_sel_hi:[1,0]
	v_pk_mul_f32 v[64:65], v[64:65], v[66:67] op_sel_hi:[1,0]
	v_pk_mul_f32 v[70:71], v[60:61], v[66:67] op_sel_hi:[1,0]
	v_pk_mul_f32 v[60:61], v[58:59], v[66:67] op_sel_hi:[1,0]
	v_cvt_pk_bf16_f32 v58, v62, v63
	v_lshl_add_u64 v[62:63], s[98:99], 0, v[68:69]
	v_cvt_pk_bf16_f32 v59, v64, v65
	v_cvt_pk_bf16_f32 v60, v60, v61
	v_cvt_pk_bf16_f32 v61, v70, v71
	v_lshl_add_u64 v[62:63], v[130:131], 1, v[62:63]
	global_store_dwordx4 v[62:63], v[58:61], off sc1
	v_pk_mul_f32 v[56:57], v[56:57], v[66:67] op_sel_hi:[1,0]
	v_pk_mul_f32 v[54:55], v[54:55], v[66:67] op_sel_hi:[1,0]
	v_pk_mul_f32 v[58:59], v[52:53], v[66:67] op_sel_hi:[1,0]
	v_pk_mul_f32 v[52:53], v[50:51], v[66:67] op_sel_hi:[1,0]
	v_cvt_pk_bf16_f32 v50, v54, v55
	v_cvt_pk_bf16_f32 v51, v56, v57
	v_cvt_pk_bf16_f32 v52, v52, v53
	v_cvt_pk_bf16_f32 v53, v58, v59
	v_lshl_add_u64 v[62:63], v[62:63], 0, s[100:101]
	global_store_dwordx4 v[62:63], v[50:53], off sc1
.LBB0_252:
	s_nop 1
	v_add_f32_e32 v50, v214, v215
	v_fmamk_f32 v50, v50, 0x3a800000, v235
	v_rsq_f32_e32 v58, v50
	s_and_b64 vcc, exec, s[4:5]
	s_mov_b64 s[24:25], -1
	s_cbranch_vccnz .LBB0_256
	s_and_saveexec_b64 s[24:25], s[14:15]
	s_cbranch_execz .LBB0_255
	global_load_dwordx4 v[54:57], v[152:153], off offset:16
	global_load_dwordx4 v[50:53], v[152:153], off
	s_mov_b32 s26, 0x3fb8aa3b
	s_waitcnt vmcnt(1)
	v_fma_f32 v55, v43, v58, v55
	s_waitcnt vmcnt(0)
	v_fma_f32 v51, v47, v58, v51
	v_mul_f32_e64 v60, |v51|, s66
	v_exp_f32_e32 v60, v60
	v_fma_f32 v52, v48, v58, v52
	v_fmac_f32_e32 v53, v49, v58
	v_fma_f32 v50, v46, v58, v50
	v_add_f32_e32 v60, 1.0, v60
	v_log_f32_e32 v62, v60
	v_mul_f32_e64 v60, |v52|, s66
	v_mul_f32_e64 v61, |v53|, s66
	v_mul_f32_e64 v59, |v50|, s66
	v_exp_f32_e32 v60, v60
	v_exp_f32_e32 v61, v61
	v_exp_f32_e32 v59, v59
	v_min_f32_e32 v52, 0, v52
	v_add_f32_e32 v60, 1.0, v60
	v_add_f32_e32 v61, 1.0, v61
	v_add_f32_e32 v59, 1.0, v59
	v_log_f32_e32 v60, v60
	v_log_f32_e32 v61, v61
	v_log_f32_e32 v59, v59
	v_min_f32_e32 v53, 0, v53
	v_xor_b32_e32 v60, 0x80000000, v60
	v_xor_b32_e32 v61, 0x80000000, v61
	v_min_f32_e32 v50, 0, v50
	v_min_f32_e32 v51, 0, v51
	v_pk_fma_f32 v[52:53], v[52:53], s[26:27], v[60:61] op_sel_hi:[1,0,1]
	v_xor_b32_e32 v61, 0x80000000, v62
	v_xor_b32_e32 v60, 0x80000000, v59
	v_pk_fma_f32 v[50:51], v[50:51], s[26:27], v[60:61] op_sel_hi:[1,0,1]
	v_mul_f32_e64 v60, |v55|, s66
	v_exp_f32_e32 v60, v60
	v_fma_f32 v56, v44, v58, v56
	v_fmac_f32_e32 v57, v45, v58
	v_fma_f32 v54, v42, v58, v54
	v_add_f32_e32 v60, 1.0, v60
	v_log_f32_e32 v62, v60
	v_mul_f32_e64 v60, |v56|, s66
	v_mul_f32_e64 v61, |v57|, s66
	v_mul_f32_e64 v59, |v54|, s66
	v_exp_f32_e32 v60, v60
	v_exp_f32_e32 v61, v61
	v_exp_f32_e32 v59, v59
	v_min_f32_e32 v56, 0, v56
	v_add_f32_e32 v60, 1.0, v60
	v_add_f32_e32 v61, 1.0, v61
	v_add_f32_e32 v59, 1.0, v59
	v_log_f32_e32 v60, v60
	v_log_f32_e32 v61, v61
	v_log_f32_e32 v59, v59
	v_min_f32_e32 v57, 0, v57
	v_xor_b32_e32 v60, 0x80000000, v60
	v_xor_b32_e32 v61, 0x80000000, v61
	v_min_f32_e32 v54, 0, v54
	v_min_f32_e32 v55, 0, v55
	v_pk_fma_f32 v[56:57], v[56:57], s[26:27], v[60:61] op_sel_hi:[1,0,1]
	v_xor_b32_e32 v61, 0x80000000, v62
	v_xor_b32_e32 v60, 0x80000000, v59
	v_pk_fma_f32 v[54:55], v[54:55], s[26:27], v[60:61] op_sel_hi:[1,0,1]
	v_lshl_add_u64 v[60:61], v[148:149], 0, v[168:169]
	global_store_dwordx4 v[60:61], v[50:53], off sc1
	global_store_dwordx4 v[60:61], v[54:57], off offset:16 sc1

.LBB0_256:
	s_andn2_b64 vcc, exec, s[24:25]
	s_cbranch_vccnz .LBB0_258
	v_mul_f32_e32 v50, v132, v58
	v_mov_b64_e32 v[52:53], 0x4100
	v_pk_mul_f32 v[46:47], v[46:47], v[50:51] op_sel_hi:[1,0]
	v_pk_mul_f32 v[48:49], v[48:49], v[50:51] op_sel_hi:[1,0]
	v_pk_mul_f32 v[54:55], v[44:45], v[50:51] op_sel_hi:[1,0]
	v_pk_mul_f32 v[44:45], v[42:43], v[50:51] op_sel_hi:[1,0]
	v_cvt_pk_bf16_f32 v42, v46, v47
	v_lshl_add_u64 v[46:47], s[98:99], 0, v[52:53]
	v_cvt_pk_bf16_f32 v43, v48, v49
	v_cvt_pk_bf16_f32 v44, v44, v45
	v_cvt_pk_bf16_f32 v45, v54, v55
	v_lshl_add_u64 v[46:47], v[130:131], 1, v[46:47]
	global_store_dwordx4 v[46:47], v[42:45], off sc1
	v_pk_mul_f32 v[40:41], v[40:41], v[50:51] op_sel_hi:[1,0]
	v_pk_mul_f32 v[38:39], v[38:39], v[50:51] op_sel_hi:[1,0]
	v_pk_mul_f32 v[42:43], v[36:37], v[50:51] op_sel_hi:[1,0]
	v_pk_mul_f32 v[36:37], v[34:35], v[50:51] op_sel_hi:[1,0]
	v_cvt_pk_bf16_f32 v34, v38, v39
	v_cvt_pk_bf16_f32 v35, v40, v41
	v_cvt_pk_bf16_f32 v36, v36, v37
	v_cvt_pk_bf16_f32 v37, v42, v43
	v_lshl_add_u64 v[46:47], v[46:47], 0, s[100:101]
	global_store_dwordx4 v[46:47], v[34:37], off sc1
.LBB0_258:
	s_nop 1
	v_add_f32_e32 v34, v212, v213
	v_fmamk_f32 v34, v34, 0x3a800000, v235
	v_rsq_f32_e32 v42, v34
	s_and_b64 vcc, exec, s[4:5]
	s_mov_b64 s[24:25], -1
	s_cbranch_vccnz .LBB0_262
	s_and_saveexec_b64 s[24:25], s[14:15]
	s_cbranch_execz .LBB0_261
	global_load_dwordx4 v[38:41], v[152:153], off offset:16
	global_load_dwordx4 v[34:37], v[152:153], off
	s_mov_b32 s26, 0x3fb8aa3b
	s_waitcnt vmcnt(1)
	v_fma_f32 v39, v27, v42, v39
	s_waitcnt vmcnt(0)
	v_fma_f32 v35, v31, v42, v35
	v_mul_f32_e64 v44, |v35|, s66
	v_exp_f32_e32 v44, v44
	v_fma_f32 v36, v32, v42, v36
	v_fmac_f32_e32 v37, v33, v42
	v_fma_f32 v34, v30, v42, v34
	v_add_f32_e32 v44, 1.0, v44
	v_log_f32_e32 v46, v44
	v_mul_f32_e64 v44, |v36|, s66
	v_mul_f32_e64 v45, |v37|, s66
	v_mul_f32_e64 v43, |v34|, s66
	v_exp_f32_e32 v44, v44
	v_exp_f32_e32 v45, v45
	v_exp_f32_e32 v43, v43
	v_min_f32_e32 v36, 0, v36
	v_add_f32_e32 v44, 1.0, v44
	v_add_f32_e32 v45, 1.0, v45
	v_add_f32_e32 v43, 1.0, v43
	v_log_f32_e32 v44, v44
	v_log_f32_e32 v45, v45
	v_log_f32_e32 v43, v43
	v_min_f32_e32 v37, 0, v37
	v_xor_b32_e32 v44, 0x80000000, v44
	v_xor_b32_e32 v45, 0x80000000, v45
	v_min_f32_e32 v34, 0, v34
	v_min_f32_e32 v35, 0, v35
	v_pk_fma_f32 v[36:37], v[36:37], s[26:27], v[44:45] op_sel_hi:[1,0,1]
	v_xor_b32_e32 v45, 0x80000000, v46
	v_xor_b32_e32 v44, 0x80000000, v43
	v_pk_fma_f32 v[34:35], v[34:35], s[26:27], v[44:45] op_sel_hi:[1,0,1]
	v_mul_f32_e64 v44, |v39|, s66
	v_exp_f32_e32 v44, v44
	v_fma_f32 v40, v28, v42, v40
	v_fmac_f32_e32 v41, v29, v42
	v_fma_f32 v38, v26, v42, v38
	v_add_f32_e32 v44, 1.0, v44
	v_log_f32_e32 v46, v44
	v_mul_f32_e64 v44, |v40|, s66
	v_mul_f32_e64 v45, |v41|, s66
	v_mul_f32_e64 v43, |v38|, s66
	v_exp_f32_e32 v44, v44
	v_exp_f32_e32 v45, v45
	v_exp_f32_e32 v43, v43
	v_min_f32_e32 v40, 0, v40
	v_add_f32_e32 v44, 1.0, v44
	v_add_f32_e32 v45, 1.0, v45
	v_add_f32_e32 v43, 1.0, v43
	v_log_f32_e32 v44, v44
	v_log_f32_e32 v45, v45
	v_log_f32_e32 v43, v43
	v_min_f32_e32 v41, 0, v41
	v_xor_b32_e32 v44, 0x80000000, v44
	v_xor_b32_e32 v45, 0x80000000, v45
	v_min_f32_e32 v38, 0, v38
	v_min_f32_e32 v39, 0, v39
	v_pk_fma_f32 v[40:41], v[40:41], s[26:27], v[44:45] op_sel_hi:[1,0,1]
	v_xor_b32_e32 v45, 0x80000000, v46
	v_xor_b32_e32 v44, 0x80000000, v43
	v_pk_fma_f32 v[38:39], v[38:39], s[26:27], v[44:45] op_sel_hi:[1,0,1]
	v_lshl_add_u64 v[44:45], v[148:149], 0, v[164:165]
	global_store_dwordx4 v[44:45], v[34:37], off sc1
	global_store_dwordx4 v[44:45], v[38:41], off offset:16 sc1

.LBB0_262:
	s_andn2_b64 vcc, exec, s[24:25]
	s_cbranch_vccnz .LBB0_264
	v_mul_f32_e32 v34, v132, v42
	v_mov_b64_e32 v[36:37], 0x5000
	v_pk_mul_f32 v[30:31], v[30:31], v[34:35] op_sel_hi:[1,0]
	v_pk_mul_f32 v[32:33], v[32:33], v[34:35] op_sel_hi:[1,0]
	v_pk_mul_f32 v[38:39], v[28:29], v[34:35] op_sel_hi:[1,0]
	v_pk_mul_f32 v[28:29], v[26:27], v[34:35] op_sel_hi:[1,0]
	v_cvt_pk_bf16_f32 v26, v30, v31
	v_lshl_add_u64 v[30:31], s[98:99], 0, v[36:37]
	v_cvt_pk_bf16_f32 v27, v32, v33
	v_cvt_pk_bf16_f32 v28, v28, v29
	v_cvt_pk_bf16_f32 v29, v38, v39
	v_lshl_add_u64 v[30:31], v[130:131], 1, v[30:31]
	global_store_dwordx4 v[30:31], v[26:29], off sc1
	v_pk_mul_f32 v[24:25], v[24:25], v[34:35] op_sel_hi:[1,0]
	v_pk_mul_f32 v[22:23], v[22:23], v[34:35] op_sel_hi:[1,0]
	v_pk_mul_f32 v[26:27], v[20:21], v[34:35] op_sel_hi:[1,0]
	v_pk_mul_f32 v[20:21], v[18:19], v[34:35] op_sel_hi:[1,0]
	v_cvt_pk_bf16_f32 v18, v22, v23
	v_cvt_pk_bf16_f32 v19, v24, v25
	v_cvt_pk_bf16_f32 v20, v20, v21
	v_cvt_pk_bf16_f32 v21, v26, v27
	v_lshl_add_u64 v[30:31], v[30:31], 0, s[100:101]
	global_store_dwordx4 v[30:31], v[18:21], off sc1

.LBB0_267:
	s_and_saveexec_b64 s[4:5], s[14:15]
	s_cbranch_execz .LBB0_269
	global_load_dwordx4 v[22:25], v[152:153], off offset:16
	global_load_dwordx4 v[18:21], v[152:153], off
	s_mov_b32 s24, 0x3fb8aa3b
	s_waitcnt vmcnt(1)
	v_fma_f32 v23, v11, v26, v23
	s_waitcnt vmcnt(0)
	v_fma_f32 v19, v15, v26, v19
	v_mul_f32_e64 v28, |v19|, s66
	v_exp_f32_e32 v28, v28
	v_fma_f32 v20, v16, v26, v20
	v_fmac_f32_e32 v21, v17, v26
	v_fma_f32 v18, v14, v26, v18
	v_add_f32_e32 v28, 1.0, v28
	v_log_f32_e32 v30, v28
	v_mul_f32_e64 v28, |v20|, s66
	v_mul_f32_e64 v29, |v21|, s66
	v_mul_f32_e64 v27, |v18|, s66
	v_exp_f32_e32 v28, v28
	v_exp_f32_e32 v29, v29
	v_exp_f32_e32 v27, v27
	v_min_f32_e32 v20, 0, v20
	v_add_f32_e32 v28, 1.0, v28
	v_add_f32_e32 v29, 1.0, v29
	v_add_f32_e32 v27, 1.0, v27
	v_log_f32_e32 v28, v28
	v_log_f32_e32 v29, v29
	v_log_f32_e32 v27, v27
	v_min_f32_e32 v21, 0, v21
	v_xor_b32_e32 v28, 0x80000000, v28
	v_xor_b32_e32 v29, 0x80000000, v29
	v_min_f32_e32 v18, 0, v18
	v_min_f32_e32 v19, 0, v19
	v_pk_fma_f32 v[20:21], v[20:21], s[24:25], v[28:29] op_sel_hi:[1,0,1]
	v_xor_b32_e32 v29, 0x80000000, v30
	v_xor_b32_e32 v28, 0x80000000, v27
	v_pk_fma_f32 v[18:19], v[18:19], s[24:25], v[28:29] op_sel_hi:[1,0,1]
	v_mul_f32_e64 v28, |v23|, s66
	v_exp_f32_e32 v28, v28
	v_fma_f32 v24, v12, v26, v24
	v_fmac_f32_e32 v25, v13, v26
	v_fma_f32 v22, v10, v26, v22
	v_add_f32_e32 v28, 1.0, v28
	v_log_f32_e32 v30, v28
	v_mul_f32_e64 v28, |v24|, s66
	v_mul_f32_e64 v29, |v25|, s66
	v_mul_f32_e64 v27, |v22|, s66
	v_exp_f32_e32 v28, v28
	v_exp_f32_e32 v29, v29
	v_exp_f32_e32 v27, v27
	v_min_f32_e32 v24, 0, v24
	v_add_f32_e32 v28, 1.0, v28
	v_add_f32_e32 v29, 1.0, v29
	v_add_f32_e32 v27, 1.0, v27
	v_log_f32_e32 v28, v28
	v_log_f32_e32 v29, v29
	v_log_f32_e32 v27, v27
	v_min_f32_e32 v25, 0, v25
	v_xor_b32_e32 v28, 0x80000000, v28
	v_xor_b32_e32 v29, 0x80000000, v29
	v_min_f32_e32 v22, 0, v22
	v_min_f32_e32 v23, 0, v23
	v_pk_fma_f32 v[24:25], v[24:25], s[24:25], v[28:29] op_sel_hi:[1,0,1]
	v_xor_b32_e32 v29, 0x80000000, v30
	v_xor_b32_e32 v28, 0x80000000, v27
	v_pk_fma_f32 v[22:23], v[22:23], s[24:25], v[28:29] op_sel_hi:[1,0,1]
	v_lshl_add_u64 v[28:29], v[148:149], 0, v[160:161]
	global_store_dwordx4 v[28:29], v[18:21], off sc1
	global_store_dwordx4 v[28:29], v[22:25], off offset:16 sc1

.LBB0_270:
	v_mul_f32_e32 v18, v132, v26
	v_mov_b64_e32 v[20:21], 0x5100
	v_pk_mul_f32 v[14:15], v[14:15], v[18:19] op_sel_hi:[1,0]
	v_pk_mul_f32 v[16:17], v[16:17], v[18:19] op_sel_hi:[1,0]
	v_pk_mul_f32 v[22:23], v[12:13], v[18:19] op_sel_hi:[1,0]
	v_pk_mul_f32 v[12:13], v[10:11], v[18:19] op_sel_hi:[1,0]
	v_cvt_pk_bf16_f32 v10, v14, v15
	v_lshl_add_u64 v[14:15], s[98:99], 0, v[20:21]
	v_cvt_pk_bf16_f32 v11, v16, v17
	v_cvt_pk_bf16_f32 v12, v12, v13
	v_cvt_pk_bf16_f32 v13, v22, v23
	v_lshl_add_u64 v[14:15], v[130:131], 1, v[14:15]
	global_store_dwordx4 v[14:15], v[10:13], off sc1
	v_pk_mul_f32 v[8:9], v[8:9], v[18:19] op_sel_hi:[1,0]
	v_pk_mul_f32 v[6:7], v[6:7], v[18:19] op_sel_hi:[1,0]
	v_pk_mul_f32 v[10:11], v[4:5], v[18:19] op_sel_hi:[1,0]
	v_pk_mul_f32 v[4:5], v[2:3], v[18:19] op_sel_hi:[1,0]
	v_cvt_pk_bf16_f32 v2, v6, v7
	v_cvt_pk_bf16_f32 v3, v8, v9
	v_cvt_pk_bf16_f32 v4, v4, v5
	v_cvt_pk_bf16_f32 v5, v10, v11
	v_lshl_add_u64 v[14:15], v[14:15], 0, s[100:101]
	global_store_dwordx4 v[14:15], v[2:5], off sc1
	s_andn2_b64 vcc, exec, s[2:3]
	s_mov_b64 s[2:3], -1
	s_cbranch_vccnz .LBB0_211

.LBB0_294:
	s_lshr_b32 s98, s40, 4
	s_lshl_b32 s98, s98, 4
	s_lshl_b32 s99, s41, 2
	s_add_i32 s98, s98, s99
	s_lshr_b32 s99, s71, 2
	s_add_i32 s98, s98, s99
	s_lshl_b32 s98, s98, 19
	s_and_b32 s99, s40, 15
	s_lshl_b32 s99, s99, 15
	s_add_i32 s98, s98, s99
	s_add_u32 s98, s82, s98
	s_addc_u32 s99, s83, 0
	s_mov_b32 s100, 0x4000
	s_mov_b32 s101, 0
	s_lshl_b32 s16, s40, 8
	v_or_b32_e32 v134, s16, v155
	v_or_b32_e32 v134, v1, v134
	v_ashrrev_i32_e32 v135, 31, v134
	v_lshlrev_b64 v[134:135], 6, v[134:135]
	v_lshl_add_u64 v[152:153], s[6:7], 0, v[134:135]
	global_load_dwordx4 v[134:137], v[152:153], off offset:48
	global_load_dwordx4 v[148:151], v[152:153], off offset:32
	global_load_dwordx4 v[158:161], v[152:153], off offset:16
	global_load_dwordx4 v[162:165], v[152:153], off
	s_lshl_b32 s17, s40, 6
	s_and_b32 s17, s17, 0xfffffc00
	s_andn2_b64 vcc, exec, s[2:3]
	s_waitcnt vmcnt(0)
	v_add_f32_e32 v148, v148, v149
	v_add_f32_e32 v150, v150, v151
	v_mov_b32_e32 v152, v163
	v_mov_b32_e32 v153, v164
	v_mov_b32_e32 v163, v165
	v_pk_add_f32 v[152:153], v[152:153], v[162:163]
	v_mov_b32_e32 v162, v159
	v_mov_b32_e32 v163, v160
	v_mov_b32_e32 v159, v161
	v_pk_add_f32 v[158:159], v[162:163], v[158:159]
	v_pk_add_f32 v[152:153], v[152:153], v[152:153] op_sel:[0,1] op_sel_hi:[1,0]
	v_pk_add_f32 v[158:159], v[158:159], v[158:159] op_sel:[0,1] op_sel_hi:[1,0]
	v_mov_b32_e32 v153, v134
	v_mov_b32_e32 v159, v135
	v_mov_b32_e32 v149, v136
	v_mov_b32_e32 v151, v137
	v_pk_add_f32 v[134:135], v[152:153], v[158:159]
	v_pk_add_f32 v[136:137], v[148:149], v[150:151]
	v_bitop3_b32 v159, s16, v241, v155 bitop3:0xc8
	v_pk_add_f32 v[134:135], v[134:135], v[136:137]
	s_lshl_b32 s16, s41, 8
	v_add_f32_e32 v134, v134, v135
	v_fmamk_f32 v134, v134, 0x3a800000, v235
	v_rsq_f32_e32 v157, v134
	v_mbcnt_hi_u32_b32 v135, -1, v233
	v_and_or_b32 v135, v135, 64, v146
	v_lshlrev_b32_e32 v158, 2, v135
	ds_bpermute_b32 v150, v158, v157
	ds_bpermute_b32 v151, v158, v157 offset:4
	ds_bpermute_b32 v136, v158, v157 offset:8
	ds_bpermute_b32 v137, v158, v157 offset:12
	ds_bpermute_b32 v152, v158, v157 offset:16
	ds_bpermute_b32 v153, v158, v157 offset:20
	ds_bpermute_b32 v148, v158, v157 offset:24
	ds_bpermute_b32 v149, v158, v157 offset:28
	s_add_i32 s17, s17, s16
	v_add_u32_e32 v134, s17, v147
	v_ashrrev_i32_e32 v135, 31, v134
	v_mov_b64_e32 v[160:161], 0
	v_lshl_add_u64 v[160:161], s[98:99], 0, v[160:161]
	s_waitcnt lgkmcnt(6)
	v_pk_mul_f32 v[126:127], v[126:127], v[150:151]
	s_waitcnt lgkmcnt(2)
	v_pk_mul_f32 v[162:163], v[122:123], v[152:153]
	v_pk_mul_f32 v[128:129], v[128:129], v[136:137]
	s_waitcnt lgkmcnt(0)
	v_pk_mul_f32 v[164:165], v[124:125], v[148:149]
	v_and_b32_e32 v122, 0xffffffe0, v155
	v_lshlrev_b32_e32 v122, 7, v122
	v_and_b32_e32 v123, 31, v155
	v_lshl_add_u32 v122, v123, 6, v122
	v_and_b32_e32 v123, 15, v147
	v_lshl_add_u32 v122, v123, 4, v122
	v_mov_b32_e32 v123, v0
	v_lshl_add_u64 v[124:125], v[160:161], 0, v[122:123]
	v_cvt_pk_bf16_f32 v126, v126, v127
	v_cvt_pk_bf16_f32 v127, v128, v129
	v_cvt_pk_bf16_f32 v128, v162, v163
	v_cvt_pk_bf16_f32 v129, v164, v165
	global_store_dwordx4 v[124:125], v[126:129], off sc1
	v_pk_mul_f32 v[118:119], v[118:119], v[150:151]
	v_pk_mul_f32 v[120:121], v[120:121], v[136:137]
	v_or_b32_e32 v126, 16, v134
	v_ashrrev_i32_e32 v127, 31, v126
	v_mov_b64_e32 v[126:127], 0x100
	v_lshl_add_u64 v[126:127], s[98:99], 0, v[126:127]
	v_pk_mul_f32 v[128:129], v[114:115], v[152:153]
	v_pk_mul_f32 v[160:161], v[116:117], v[148:149]
	v_lshl_add_u64 v[114:115], v[126:127], 0, v[122:123]
	v_cvt_pk_bf16_f32 v116, v118, v119
	v_cvt_pk_bf16_f32 v117, v120, v121
	v_cvt_pk_bf16_f32 v118, v128, v129
	v_cvt_pk_bf16_f32 v119, v160, v161
	global_store_dwordx4 v[114:115], v[116:119], off sc1
	v_pk_mul_f32 v[110:111], v[110:111], v[150:151]
	v_pk_mul_f32 v[112:113], v[112:113], v[136:137]
	v_or_b32_e32 v116, 32, v134
	v_ashrrev_i32_e32 v117, 31, v116
	v_mov_b64_e32 v[116:117], 0x800
	v_lshl_add_u64 v[116:117], s[98:99], 0, v[116:117]
	v_pk_mul_f32 v[118:119], v[106:107], v[152:153]
	v_pk_mul_f32 v[120:121], v[108:109], v[148:149]
	v_lshl_add_u64 v[106:107], v[116:117], 0, v[122:123]
	v_cvt_pk_bf16_f32 v108, v110, v111
	v_cvt_pk_bf16_f32 v109, v112, v113
	v_cvt_pk_bf16_f32 v110, v118, v119
	v_cvt_pk_bf16_f32 v111, v120, v121
	global_store_dwordx4 v[106:107], v[108:111], off sc1
	v_pk_mul_f32 v[102:103], v[102:103], v[150:151]
	v_pk_mul_f32 v[104:105], v[104:105], v[136:137]
	v_or_b32_e32 v108, 48, v134
	v_ashrrev_i32_e32 v109, 31, v108
	v_mov_b64_e32 v[108:109], 0x900
	v_lshl_add_u64 v[108:109], s[98:99], 0, v[108:109]
	v_pk_mul_f32 v[110:111], v[98:99], v[152:153]
	v_pk_mul_f32 v[112:113], v[100:101], v[148:149]
	v_lshl_add_u64 v[98:99], v[108:109], 0, v[122:123]
	v_cvt_pk_bf16_f32 v100, v102, v103
	v_cvt_pk_bf16_f32 v101, v104, v105
	v_cvt_pk_bf16_f32 v102, v110, v111
	v_cvt_pk_bf16_f32 v103, v112, v113
	global_store_dwordx4 v[98:99], v[100:103], off sc1
	v_pk_mul_f32 v[94:95], v[94:95], v[150:151]
	v_pk_mul_f32 v[96:97], v[96:97], v[136:137]
	v_add_u32_e32 v100, 0x80, v134
	v_ashrrev_i32_e32 v101, 31, v100
	v_mov_b64_e32 v[100:101], 0x100000
	v_lshl_add_u64 v[100:101], s[98:99], 0, v[100:101]
	v_pk_mul_f32 v[102:103], v[90:91], v[152:153]
	v_pk_mul_f32 v[104:105], v[92:93], v[148:149]
	v_lshl_add_u64 v[100:101], v[100:101], 0, v[122:123]
	v_cvt_pk_bf16_f32 v90, v94, v95
	v_cvt_pk_bf16_f32 v91, v96, v97
	v_cvt_pk_bf16_f32 v92, v102, v103
	v_cvt_pk_bf16_f32 v93, v104, v105
	global_store_dwordx4 v[100:101], v[90:93], off sc1
	v_pk_mul_f32 v[86:87], v[86:87], v[150:151]
	v_pk_mul_f32 v[88:89], v[88:89], v[136:137]
	v_add_u32_e32 v90, 0x90, v134
	v_ashrrev_i32_e32 v91, 31, v90
	v_mov_b64_e32 v[90:91], 0x100100
	v_lshl_add_u64 v[90:91], s[98:99], 0, v[90:91]
	v_pk_mul_f32 v[92:93], v[82:83], v[152:153]
	v_pk_mul_f32 v[94:95], v[84:85], v[148:149]
	v_lshl_add_u64 v[90:91], v[90:91], 0, v[122:123]
	v_cvt_pk_bf16_f32 v82, v86, v87
	v_cvt_pk_bf16_f32 v83, v88, v89
	v_cvt_pk_bf16_f32 v84, v92, v93
	v_cvt_pk_bf16_f32 v85, v94, v95
	global_store_dwordx4 v[90:91], v[82:85], off sc1
	v_pk_mul_f32 v[78:79], v[78:79], v[150:151]
	v_pk_mul_f32 v[80:81], v[80:81], v[136:137]
	v_add_u32_e32 v82, 0xa0, v134
	v_ashrrev_i32_e32 v83, 31, v82
	v_mov_b64_e32 v[82:83], 0x100800
	v_lshl_add_u64 v[82:83], s[98:99], 0, v[82:83]
	v_pk_mul_f32 v[84:85], v[74:75], v[152:153]
	v_pk_mul_f32 v[86:87], v[76:77], v[148:149]
	v_lshl_add_u64 v[82:83], v[82:83], 0, v[122:123]
	v_cvt_pk_bf16_f32 v74, v78, v79
	v_cvt_pk_bf16_f32 v75, v80, v81
	v_cvt_pk_bf16_f32 v76, v84, v85
	v_cvt_pk_bf16_f32 v77, v86, v87
	global_store_dwordx4 v[82:83], v[74:77], off sc1
	v_pk_mul_f32 v[62:63], v[62:63], v[150:151]
	v_pk_mul_f32 v[64:65], v[64:65], v[136:137]
	v_add_u32_e32 v74, 0xb0, v134
	v_ashrrev_i32_e32 v75, 31, v74
	v_mov_b64_e32 v[74:75], 0x100900
	v_lshl_add_u64 v[74:75], s[98:99], 0, v[74:75]
	v_pk_mul_f32 v[76:77], v[58:59], v[152:153]
	v_pk_mul_f32 v[78:79], v[60:61], v[148:149]
	v_lshl_add_u64 v[74:75], v[74:75], 0, v[122:123]
	v_cvt_pk_bf16_f32 v58, v62, v63
	v_cvt_pk_bf16_f32 v59, v64, v65
	v_cvt_pk_bf16_f32 v60, v76, v77
	v_cvt_pk_bf16_f32 v61, v78, v79
	global_store_dwordx4 v[74:75], v[58:61], off sc1
	ds_bpermute_b32 v62, v158, v157 offset:32
	ds_bpermute_b32 v63, v158, v157 offset:36
	v_or_b32_e32 v58, 60, v158
	ds_bpermute_b32 v64, v158, v157 offset:40
	ds_bpermute_b32 v65, v158, v157 offset:44
	ds_bpermute_b32 v76, v158, v157 offset:48
	ds_bpermute_b32 v77, v158, v157 offset:52
	ds_bpermute_b32 v78, v158, v157 offset:56
	ds_bpermute_b32 v79, v58, v157
	s_waitcnt lgkmcnt(6)
	v_pk_mul_f32 v[58:59], v[70:71], v[62:63]
	v_pk_mul_f32 v[54:55], v[54:55], v[62:63]
	s_waitcnt lgkmcnt(2)
	v_pk_mul_f32 v[60:61], v[66:67], v[76:77]
	v_pk_mul_f32 v[66:67], v[72:73], v[64:65]
	s_waitcnt lgkmcnt(0)
	v_pk_mul_f32 v[68:69], v[68:69], v[78:79]
	v_cvt_pk_bf16_f32 v58, v58, v59
	v_cvt_pk_bf16_f32 v59, v66, v67
	v_cvt_pk_bf16_f32 v60, v60, v61
	v_cvt_pk_bf16_f32 v61, v68, v69
	v_lshl_add_u64 v[124:125], v[124:125], 0, s[100:101]
	global_store_dwordx4 v[124:125], v[58:61], off sc1
	v_pk_mul_f32 v[56:57], v[56:57], v[64:65]
	v_pk_mul_f32 v[46:47], v[46:47], v[62:63]
	v_pk_mul_f32 v[58:59], v[50:51], v[76:77]
	v_pk_mul_f32 v[60:61], v[52:53], v[78:79]
	v_cvt_pk_bf16_f32 v50, v54, v55
	v_cvt_pk_bf16_f32 v51, v56, v57
	v_cvt_pk_bf16_f32 v52, v58, v59
	v_cvt_pk_bf16_f32 v53, v60, v61
	v_lshl_add_u64 v[114:115], v[114:115], 0, s[100:101]
	global_store_dwordx4 v[114:115], v[50:53], off sc1
	v_pk_mul_f32 v[48:49], v[48:49], v[64:65]
	v_pk_mul_f32 v[38:39], v[38:39], v[62:63]
	v_pk_mul_f32 v[50:51], v[42:43], v[76:77]
	v_pk_mul_f32 v[52:53], v[44:45], v[78:79]
	v_cvt_pk_bf16_f32 v42, v46, v47
	v_cvt_pk_bf16_f32 v43, v48, v49
	v_cvt_pk_bf16_f32 v44, v50, v51
	v_cvt_pk_bf16_f32 v45, v52, v53
	v_lshl_add_u64 v[106:107], v[106:107], 0, s[100:101]
	global_store_dwordx4 v[106:107], v[42:45], off sc1
	v_pk_mul_f32 v[40:41], v[40:41], v[64:65]
	v_pk_mul_f32 v[30:31], v[30:31], v[62:63]
	v_pk_mul_f32 v[42:43], v[34:35], v[76:77]
	v_pk_mul_f32 v[44:45], v[36:37], v[78:79]
	v_cvt_pk_bf16_f32 v34, v38, v39
	v_cvt_pk_bf16_f32 v35, v40, v41
	v_cvt_pk_bf16_f32 v36, v42, v43
	v_cvt_pk_bf16_f32 v37, v44, v45
	v_lshl_add_u64 v[98:99], v[98:99], 0, s[100:101]
	global_store_dwordx4 v[98:99], v[34:37], off sc1
	v_pk_mul_f32 v[32:33], v[32:33], v[64:65]
	v_pk_mul_f32 v[22:23], v[22:23], v[62:63]
	v_pk_mul_f32 v[34:35], v[26:27], v[76:77]
	v_pk_mul_f32 v[36:37], v[28:29], v[78:79]
	v_cvt_pk_bf16_f32 v26, v30, v31
	v_cvt_pk_bf16_f32 v27, v32, v33
	v_cvt_pk_bf16_f32 v28, v34, v35
	v_cvt_pk_bf16_f32 v29, v36, v37
	v_lshl_add_u64 v[100:101], v[100:101], 0, s[100:101]
	global_store_dwordx4 v[100:101], v[26:29], off sc1
	v_pk_mul_f32 v[24:25], v[24:25], v[64:65]
	v_pk_mul_f32 v[14:15], v[14:15], v[62:63]
	v_pk_mul_f32 v[26:27], v[18:19], v[76:77]
	v_pk_mul_f32 v[28:29], v[20:21], v[78:79]
	v_cvt_pk_bf16_f32 v18, v22, v23
	v_cvt_pk_bf16_f32 v19, v24, v25
	v_cvt_pk_bf16_f32 v20, v26, v27
	v_cvt_pk_bf16_f32 v21, v28, v29
	v_lshl_add_u64 v[90:91], v[90:91], 0, s[100:101]
	global_store_dwordx4 v[90:91], v[18:21], off sc1
	v_pk_mul_f32 v[16:17], v[16:17], v[64:65]
	v_pk_mul_f32 v[6:7], v[6:7], v[62:63]
	v_pk_mul_f32 v[18:19], v[10:11], v[76:77]
	v_pk_mul_f32 v[20:21], v[12:13], v[78:79]
	v_cvt_pk_bf16_f32 v10, v14, v15
	v_cvt_pk_bf16_f32 v11, v16, v17
	v_cvt_pk_bf16_f32 v12, v18, v19
	v_cvt_pk_bf16_f32 v13, v20, v21
	v_lshl_add_u64 v[82:83], v[82:83], 0, s[100:101]
	global_store_dwordx4 v[82:83], v[10:13], off sc1
	v_pk_mul_f32 v[8:9], v[8:9], v[64:65]
	s_mov_b64 s[16:17], -1
	v_pk_mul_f32 v[10:11], v[2:3], v[76:77]
	v_pk_mul_f32 v[12:13], v[4:5], v[78:79]
	v_cvt_pk_bf16_f32 v2, v6, v7
	v_cvt_pk_bf16_f32 v3, v8, v9
	v_cvt_pk_bf16_f32 v4, v10, v11
	v_cvt_pk_bf16_f32 v5, v12, v13
	v_lshl_add_u64 v[74:75], v[74:75], 0, s[100:101]
	global_store_dwordx4 v[74:75], v[2:5], off sc1
	s_cbranch_vccnz .LBB0_283
	s_andn2_b64 vcc, exec, s[4:5]
	s_cbranch_vccnz .LBB0_282
	s_barrier
	s_branch .LBB0_282

.LBB0_327:
	v_lshl_or_b32 v166, s47, 8, v185
	v_lshl_add_u32 v168, s48, 8, v1
	v_ashrrev_i32_e32 v167, 31, v166
	v_lshlrev_b64 v[196:197], 1, v[166:167]
	v_ashrrev_i32_e32 v169, 31, v168
	v_or_b32_e32 v180, 16, v168
	v_lshl_add_u64 v[170:171], s[80:81], 0, v[196:197]
	v_lshlrev_b64 v[198:199], 11, v[168:169]
	v_ashrrev_i32_e32 v181, 31, v180
	v_or_b32_e32 v176, 32, v168
	v_lshl_add_u64 v[130:131], v[170:171], 0, v[198:199]
	v_lshlrev_b64 v[182:183], 11, v[180:181]
	v_ashrrev_i32_e32 v177, 31, v176
	v_or_b32_e32 v172, 48, v168
	global_load_dwordx4 v[188:191], v[130:131], off
	global_load_dwordx4 v[192:195], v[130:131], off offset:256
	v_lshl_add_u64 v[130:131], v[170:171], 0, v[182:183]
	v_lshlrev_b64 v[178:179], 11, v[176:177]
	v_ashrrev_i32_e32 v173, 31, v172
	global_load_dwordx4 v[150:153], v[130:131], off
	global_load_dwordx4 v[146:149], v[130:131], off offset:256
	v_lshl_add_u64 v[130:131], v[170:171], 0, v[178:179]
	v_lshlrev_b64 v[174:175], 11, v[172:173]
	global_load_dwordx4 v[142:145], v[130:131], off
	global_load_dwordx4 v[138:141], v[130:131], off offset:256
	v_lshl_add_u64 v[130:131], v[170:171], 0, v[174:175]
	global_load_dwordx4 v[134:137], v[130:131], off
	s_nop 0
	global_load_dwordx4 v[130:133], v[130:131], off offset:256
	v_lshl_add_u64 v[198:199], s[80:81], 0, v[198:199]
	v_lshl_add_u64 v[196:197], v[198:199], 0, v[196:197]
	s_lshl_b32 s24, s47, 2
	s_ashr_i32 s25, s24, 31
	s_waitcnt vmcnt(0)
	v_lshlrev_b32_e32 v198, 16, v188
	v_and_b32_e32 v199, 0xffff0000, v188
	v_lshlrev_b32_e32 v188, 16, v189
	v_and_b32_e32 v189, 0xffff0000, v189
	v_lshlrev_b32_e32 v200, 16, v190
	v_and_b32_e32 v201, 0xffff0000, v190
	v_lshlrev_b32_e32 v190, 16, v191
	v_and_b32_e32 v191, 0xffff0000, v191
	v_lshlrev_b32_e32 v202, 16, v192
	v_and_b32_e32 v203, 0xffff0000, v192
	v_lshlrev_b32_e32 v192, 16, v193
	v_and_b32_e32 v193, 0xffff0000, v193
	v_lshlrev_b32_e32 v204, 16, v194
	v_and_b32_e32 v205, 0xffff0000, v194
	v_lshlrev_b32_e32 v194, 16, v195
	v_and_b32_e32 v195, 0xffff0000, v195
	v_pk_add_f32 v[128:129], v[128:129], v[188:189]
	v_pk_add_f32 v[126:127], v[126:127], v[198:199]
	v_pk_add_f32 v[124:125], v[124:125], v[190:191]
	v_pk_add_f32 v[122:123], v[122:123], v[200:201]
	v_pk_add_f32 v[188:189], v[120:121], v[192:193]
	v_pk_add_f32 v[190:191], v[118:119], v[202:203]
	v_pk_add_f32 v[192:193], v[116:117], v[194:195]
	v_pk_add_f32 v[194:195], v[114:115], v[204:205]
	v_mul_f32_e32 v187, v127, v127
	v_mul_f32_e32 v198, v129, v129
	v_mul_f32_e32 v199, v123, v123
	v_mul_f32_e32 v200, v125, v125
	v_cvt_pk_bf16_f32 v116, v122, v123
	v_cvt_pk_bf16_f32 v117, v124, v125
	v_mul_f32_e32 v123, v191, v191
	v_mul_f32_e32 v125, v189, v189
	v_cvt_pk_bf16_f32 v114, v126, v127
	v_cvt_pk_bf16_f32 v115, v128, v129
	v_mul_f32_e32 v127, v195, v195
	v_fmac_f32_e32 v187, v126, v126
	v_fmac_f32_e32 v198, v128, v128
	v_fmac_f32_e32 v123, v190, v190
	v_fmac_f32_e32 v125, v188, v188
	v_mul_f32_e32 v129, v193, v193
	v_fmac_f32_e32 v199, v122, v122
	global_store_dwordx4 v[196:197], v[114:117], off sc1
	v_fmac_f32_e32 v127, v194, v194
	v_fmac_f32_e32 v200, v124, v124
	v_add_f32_e32 v114, v187, v198
	v_add_f32_e32 v115, v123, v125
	v_fmac_f32_e32 v129, v192, v192
	v_add_f32_e32 v114, v199, v114
	v_add_f32_e32 v115, v127, v115
	v_add_f32_e32 v114, v200, v114
	v_add_f32_e32 v115, v129, v115
	v_add_f32_e32 v114, v114, v115
	v_mov_b32_e32 v115, v114
	s_nop 1
	v_permlane16_swap_b32_e32 v114, v115
	v_add_f32_e32 v114, v114, v115
	v_mov_b32_e32 v115, v114
	v_cvt_pk_bf16_f32 v118, v190, v191
	v_cvt_pk_bf16_f32 v119, v188, v189
	v_cvt_pk_bf16_f32 v120, v194, v195
	v_cvt_pk_bf16_f32 v121, v192, v193
	v_permlane32_swap_b32_e32 v114, v115
	global_store_dwordx4 v[196:197], v[118:121], off offset:256 sc1
	s_and_saveexec_b64 s[26:27], s[2:3]
	s_cbranch_execz .LBB0_329
	v_lshlrev_b64 v[116:117], 6, v[168:169]
	v_lshl_add_u64 v[116:117], s[12:13], 0, v[116:117]
	v_lshl_add_u64 v[116:117], s[24:25], 2, v[116:117]
	s_lshl_b32 s78, s41, 2
	v_lshl_add_u64 v[116:117], v[116:117], 0, s[78:79]
	v_add_f32_e32 v114, v114, v115
	global_store_dword v[116:117], v114, off
.LBB0_329:
	s_or_b64 exec, exec, s[26:27]
	v_lshlrev_b32_e32 v114, 16, v150
	v_and_b32_e32 v115, 0xffff0000, v150
	v_lshlrev_b32_e32 v116, 16, v151
	v_and_b32_e32 v117, 0xffff0000, v151
	v_lshlrev_b32_e32 v118, 16, v152
	v_and_b32_e32 v119, 0xffff0000, v152
	v_lshlrev_b32_e32 v120, 16, v153
	v_and_b32_e32 v121, 0xffff0000, v153
	v_pk_add_f32 v[112:113], v[112:113], v[116:117]
	v_pk_add_f32 v[110:111], v[110:111], v[114:115]
	v_pk_add_f32 v[114:115], v[108:109], v[120:121]
	v_pk_add_f32 v[108:109], v[106:107], v[118:119]
	v_mul_f32_e32 v106, v111, v111
	v_mul_f32_e32 v107, v113, v113
	v_fmac_f32_e32 v106, v110, v110
	v_fmac_f32_e32 v107, v112, v112
	v_add_f32_e32 v106, v106, v107
	v_mul_f32_e32 v107, v109, v109
	v_fmac_f32_e32 v107, v108, v108
	v_add_f32_e32 v106, v107, v106
	v_mul_f32_e32 v107, v115, v115
	v_fmac_f32_e32 v107, v114, v114
	v_lshlrev_b32_e32 v122, 16, v146
	v_and_b32_e32 v123, 0xffff0000, v146
	v_lshlrev_b32_e32 v124, 16, v147
	v_and_b32_e32 v125, 0xffff0000, v147
	v_add_f32_e32 v116, v107, v106
	v_cvt_pk_bf16_f32 v106, v110, v111
	v_lshl_add_u64 v[110:111], s[80:81], 0, v[182:183]
	v_lshlrev_b32_e32 v126, 16, v148
	v_and_b32_e32 v127, 0xffff0000, v148
	v_lshlrev_b32_e32 v128, 16, v149
	v_and_b32_e32 v129, 0xffff0000, v149
	v_cvt_pk_bf16_f32 v107, v112, v113
	v_cvt_pk_bf16_f32 v108, v108, v109
	v_cvt_pk_bf16_f32 v109, v114, v115
	v_lshl_add_u64 v[110:111], v[166:167], 1, v[110:111]
	v_pk_add_f32 v[104:105], v[104:105], v[124:125]
	v_pk_add_f32 v[102:103], v[102:103], v[122:123]
	global_store_dwordx4 v[110:111], v[106:109], off sc1
	s_nop 1
	v_pk_add_f32 v[106:107], v[100:101], v[128:129]
	v_pk_add_f32 v[100:101], v[98:99], v[126:127]
	v_mul_f32_e32 v98, v103, v103
	v_mul_f32_e32 v99, v105, v105
	v_fmac_f32_e32 v98, v102, v102
	v_fmac_f32_e32 v99, v104, v104
	v_add_f32_e32 v98, v98, v99
	v_mul_f32_e32 v99, v101, v101
	v_fmac_f32_e32 v99, v100, v100
	v_add_f32_e32 v98, v99, v98
	v_mul_f32_e32 v99, v107, v107
	v_fmac_f32_e32 v99, v106, v106
	v_add_f32_e32 v98, v99, v98
	v_add_f32_e32 v108, v116, v98
	v_cvt_pk_bf16_f32 v98, v102, v103
	v_cvt_pk_bf16_f32 v99, v104, v105
	v_cvt_pk_bf16_f32 v100, v100, v101
	v_cvt_pk_bf16_f32 v101, v106, v107
	global_store_dwordx4 v[110:111], v[98:101], off offset:256 sc1
	s_nop 1
	v_mov_b32_e32 v98, v108
	s_nop 1
	v_permlane16_swap_b32_e32 v108, v98
	v_add_f32_e32 v98, v108, v98
	v_mov_b32_e32 v99, v98
	s_nop 1
	v_permlane32_swap_b32_e32 v98, v99
	s_and_saveexec_b64 s[26:27], s[2:3]
	s_cbranch_execz .LBB0_331
	v_lshlrev_b64 v[100:101], 6, v[180:181]
	v_lshl_add_u64 v[100:101], s[12:13], 0, v[100:101]
	v_lshl_add_u64 v[100:101], s[24:25], 2, v[100:101]
	s_lshl_b32 s78, s41, 2
	v_lshl_add_u64 v[100:101], v[100:101], 0, s[78:79]
	v_add_f32_e32 v98, v98, v99
	global_store_dword v[100:101], v98, off
.LBB0_331:
	s_or_b64 exec, exec, s[26:27]
	v_lshlrev_b32_e32 v98, 16, v142
	v_and_b32_e32 v99, 0xffff0000, v142
	v_lshlrev_b32_e32 v100, 16, v143
	v_and_b32_e32 v101, 0xffff0000, v143
	v_lshlrev_b32_e32 v102, 16, v144
	v_and_b32_e32 v103, 0xffff0000, v144
	v_lshlrev_b32_e32 v104, 16, v145
	v_and_b32_e32 v105, 0xffff0000, v145
	v_pk_add_f32 v[96:97], v[96:97], v[100:101]
	v_pk_add_f32 v[94:95], v[94:95], v[98:99]
	v_pk_add_f32 v[98:99], v[92:93], v[104:105]
	v_pk_add_f32 v[92:93], v[90:91], v[102:103]
	v_mul_f32_e32 v90, v95, v95
	v_mul_f32_e32 v91, v97, v97
	v_fmac_f32_e32 v90, v94, v94
	v_fmac_f32_e32 v91, v96, v96
	v_add_f32_e32 v90, v90, v91
	v_mul_f32_e32 v91, v93, v93
	v_fmac_f32_e32 v91, v92, v92
	v_add_f32_e32 v90, v91, v90
	v_mul_f32_e32 v91, v99, v99
	v_fmac_f32_e32 v91, v98, v98
	v_lshlrev_b32_e32 v106, 16, v138
	v_and_b32_e32 v107, 0xffff0000, v138
	v_lshlrev_b32_e32 v108, 16, v139
	v_and_b32_e32 v109, 0xffff0000, v139
	v_add_f32_e32 v100, v91, v90
	v_cvt_pk_bf16_f32 v90, v94, v95
	v_lshl_add_u64 v[94:95], s[80:81], 0, v[178:179]
	v_lshlrev_b32_e32 v110, 16, v140
	v_and_b32_e32 v111, 0xffff0000, v140
	v_lshlrev_b32_e32 v112, 16, v141
	v_and_b32_e32 v113, 0xffff0000, v141
	v_cvt_pk_bf16_f32 v91, v96, v97
	v_cvt_pk_bf16_f32 v92, v92, v93
	v_cvt_pk_bf16_f32 v93, v98, v99
	v_lshl_add_u64 v[94:95], v[166:167], 1, v[94:95]
	v_pk_add_f32 v[88:89], v[88:89], v[108:109]
	v_pk_add_f32 v[86:87], v[86:87], v[106:107]
	global_store_dwordx4 v[94:95], v[90:93], off sc1
	s_nop 1
	v_pk_add_f32 v[90:91], v[84:85], v[112:113]
	v_pk_add_f32 v[84:85], v[82:83], v[110:111]
	v_mul_f32_e32 v82, v87, v87
	v_mul_f32_e32 v83, v89, v89
	v_fmac_f32_e32 v82, v86, v86
	v_fmac_f32_e32 v83, v88, v88
	v_add_f32_e32 v82, v82, v83
	v_mul_f32_e32 v83, v85, v85
	v_fmac_f32_e32 v83, v84, v84
	v_add_f32_e32 v82, v83, v82
	v_mul_f32_e32 v83, v91, v91
	v_fmac_f32_e32 v83, v90, v90
	v_add_f32_e32 v82, v83, v82
	v_add_f32_e32 v92, v100, v82
	v_cvt_pk_bf16_f32 v82, v86, v87
	v_cvt_pk_bf16_f32 v83, v88, v89
	v_cvt_pk_bf16_f32 v84, v84, v85
	v_cvt_pk_bf16_f32 v85, v90, v91
	global_store_dwordx4 v[94:95], v[82:85], off offset:256 sc1
	s_nop 1
	v_mov_b32_e32 v82, v92
	s_nop 1
	v_permlane16_swap_b32_e32 v92, v82
	v_add_f32_e32 v82, v92, v82
	v_mov_b32_e32 v83, v82
	s_nop 1
	v_permlane32_swap_b32_e32 v82, v83
	s_and_saveexec_b64 s[26:27], s[2:3]
	s_cbranch_execz .LBB0_333
	v_lshlrev_b64 v[84:85], 6, v[176:177]
	v_lshl_add_u64 v[84:85], s[12:13], 0, v[84:85]
	v_lshl_add_u64 v[84:85], s[24:25], 2, v[84:85]
	s_lshl_b32 s78, s41, 2
	v_lshl_add_u64 v[84:85], v[84:85], 0, s[78:79]
	v_add_f32_e32 v82, v82, v83
	global_store_dword v[84:85], v82, off
.LBB0_333:
	s_or_b64 exec, exec, s[26:27]
	v_lshlrev_b32_e32 v82, 16, v134
	v_and_b32_e32 v83, 0xffff0000, v134
	v_lshlrev_b32_e32 v84, 16, v135
	v_and_b32_e32 v85, 0xffff0000, v135
	v_lshlrev_b32_e32 v86, 16, v136
	v_and_b32_e32 v87, 0xffff0000, v136
	v_lshlrev_b32_e32 v88, 16, v137
	v_and_b32_e32 v89, 0xffff0000, v137
	v_pk_add_f32 v[80:81], v[80:81], v[84:85]
	v_pk_add_f32 v[78:79], v[78:79], v[82:83]
	v_pk_add_f32 v[82:83], v[76:77], v[88:89]
	v_pk_add_f32 v[76:77], v[74:75], v[86:87]
	v_mul_f32_e32 v74, v79, v79
	v_mul_f32_e32 v75, v81, v81
	v_fmac_f32_e32 v74, v78, v78
	v_fmac_f32_e32 v75, v80, v80
	v_add_f32_e32 v74, v74, v75
	v_mul_f32_e32 v75, v77, v77
	v_fmac_f32_e32 v75, v76, v76
	v_add_f32_e32 v74, v75, v74
	v_mul_f32_e32 v75, v83, v83
	v_fmac_f32_e32 v75, v82, v82
	v_lshlrev_b32_e32 v90, 16, v130
	v_and_b32_e32 v91, 0xffff0000, v130
	v_lshlrev_b32_e32 v92, 16, v131
	v_and_b32_e32 v93, 0xffff0000, v131
	v_add_f32_e32 v84, v75, v74
	v_cvt_pk_bf16_f32 v74, v78, v79
	v_lshl_add_u64 v[78:79], s[80:81], 0, v[174:175]
	v_lshlrev_b32_e32 v94, 16, v132
	v_and_b32_e32 v95, 0xffff0000, v132
	v_lshlrev_b32_e32 v96, 16, v133
	v_and_b32_e32 v97, 0xffff0000, v133
	v_cvt_pk_bf16_f32 v75, v80, v81
	v_cvt_pk_bf16_f32 v76, v76, v77
	v_cvt_pk_bf16_f32 v77, v82, v83
	v_lshl_add_u64 v[78:79], v[166:167], 1, v[78:79]
	v_pk_add_f32 v[72:73], v[72:73], v[92:93]
	v_pk_add_f32 v[70:71], v[70:71], v[90:91]
	global_store_dwordx4 v[78:79], v[74:77], off sc1
	s_nop 1
	v_pk_add_f32 v[74:75], v[68:69], v[96:97]
	v_pk_add_f32 v[68:69], v[66:67], v[94:95]
	v_mul_f32_e32 v66, v71, v71
	v_mul_f32_e32 v67, v73, v73
	v_fmac_f32_e32 v66, v70, v70
	v_fmac_f32_e32 v67, v72, v72
	v_add_f32_e32 v66, v66, v67
	v_mul_f32_e32 v67, v69, v69
	v_fmac_f32_e32 v67, v68, v68
	v_add_f32_e32 v66, v67, v66
	v_mul_f32_e32 v67, v75, v75
	v_fmac_f32_e32 v67, v74, v74
	v_add_f32_e32 v66, v67, v66
	v_add_f32_e32 v76, v84, v66
	v_cvt_pk_bf16_f32 v66, v70, v71
	v_cvt_pk_bf16_f32 v67, v72, v73
	v_cvt_pk_bf16_f32 v68, v68, v69
	v_cvt_pk_bf16_f32 v69, v74, v75
	global_store_dwordx4 v[78:79], v[66:69], off offset:256 sc1
	s_nop 1
	v_mov_b32_e32 v66, v76
	s_nop 1
	v_permlane16_swap_b32_e32 v76, v66
	v_add_f32_e32 v66, v76, v66
	v_mov_b32_e32 v67, v66
	s_nop 1
	v_permlane32_swap_b32_e32 v66, v67
	s_and_saveexec_b64 s[26:27], s[2:3]
	s_cbranch_execz .LBB0_335
	v_lshlrev_b64 v[68:69], 6, v[172:173]
	v_lshl_add_u64 v[68:69], s[12:13], 0, v[68:69]
	v_lshl_add_u64 v[68:69], s[24:25], 2, v[68:69]
	s_lshl_b32 s78, s41, 2
	v_lshl_add_u64 v[68:69], v[68:69], 0, s[78:79]
	v_add_f32_e32 v66, v66, v67
	global_store_dword v[68:69], v66, off
.LBB0_335:
	s_or_b64 exec, exec, s[26:27]
	v_add_u32_e32 v102, 0x80, v168
	v_ashrrev_i32_e32 v103, 31, v102
	v_add_u32_e32 v98, 0x90, v168
	v_lshlrev_b64 v[112:113], 11, v[102:103]
	v_ashrrev_i32_e32 v99, 31, v98
	v_add_u32_e32 v94, 0xa0, v168
	v_lshl_add_u64 v[66:67], v[170:171], 0, v[112:113]
	v_lshlrev_b64 v[100:101], 11, v[98:99]
	v_ashrrev_i32_e32 v95, 31, v94
	v_add_u32_e32 v90, 0xb0, v168
	global_load_dwordx4 v[104:107], v[66:67], off
	global_load_dwordx4 v[108:111], v[66:67], off offset:256
	v_lshl_add_u64 v[66:67], v[170:171], 0, v[100:101]
	v_lshlrev_b64 v[96:97], 11, v[94:95]
	v_ashrrev_i32_e32 v91, 31, v90
	global_load_dwordx4 v[86:89], v[66:67], off
	global_load_dwordx4 v[82:85], v[66:67], off offset:256
	v_lshl_add_u64 v[66:67], v[170:171], 0, v[96:97]
	v_lshlrev_b64 v[92:93], 11, v[90:91]
	global_load_dwordx4 v[78:81], v[66:67], off
	global_load_dwordx4 v[74:77], v[66:67], off offset:256
	v_lshl_add_u64 v[66:67], v[170:171], 0, v[92:93]
	global_load_dwordx4 v[70:73], v[66:67], off
	s_nop 0
	global_load_dwordx4 v[66:69], v[66:67], off offset:256
	v_lshl_add_u64 v[112:113], s[80:81], 0, v[112:113]
	v_lshl_add_u64 v[112:113], v[166:167], 1, v[112:113]
	s_waitcnt vmcnt(0)
	v_lshlrev_b32_e32 v114, 16, v104
	v_and_b32_e32 v115, 0xffff0000, v104
	v_lshlrev_b32_e32 v104, 16, v105
	v_and_b32_e32 v105, 0xffff0000, v105
	v_lshlrev_b32_e32 v116, 16, v106
	v_and_b32_e32 v117, 0xffff0000, v106
	v_lshlrev_b32_e32 v106, 16, v107
	v_and_b32_e32 v107, 0xffff0000, v107
	v_lshlrev_b32_e32 v118, 16, v108
	v_and_b32_e32 v119, 0xffff0000, v108
	v_lshlrev_b32_e32 v108, 16, v109
	v_and_b32_e32 v109, 0xffff0000, v109
	v_lshlrev_b32_e32 v120, 16, v110
	v_and_b32_e32 v121, 0xffff0000, v110
	v_lshlrev_b32_e32 v110, 16, v111
	v_and_b32_e32 v111, 0xffff0000, v111
	v_pk_add_f32 v[64:65], v[64:65], v[104:105]
	v_pk_add_f32 v[62:63], v[62:63], v[114:115]
	v_pk_add_f32 v[60:61], v[60:61], v[106:107]
	v_pk_add_f32 v[58:59], v[58:59], v[116:117]
	v_pk_add_f32 v[104:105], v[56:57], v[108:109]
	v_pk_add_f32 v[106:107], v[54:55], v[118:119]
	v_pk_add_f32 v[108:109], v[52:53], v[110:111]
	v_pk_add_f32 v[110:111], v[50:51], v[120:121]
	v_mul_f32_e32 v114, v63, v63
	v_mul_f32_e32 v115, v65, v65
	v_mul_f32_e32 v116, v59, v59
	v_mul_f32_e32 v117, v61, v61
	v_cvt_pk_bf16_f32 v52, v58, v59
	v_cvt_pk_bf16_f32 v53, v60, v61
	v_mul_f32_e32 v59, v107, v107
	v_mul_f32_e32 v61, v105, v105
	v_cvt_pk_bf16_f32 v50, v62, v63
	v_cvt_pk_bf16_f32 v51, v64, v65
	v_mul_f32_e32 v63, v111, v111
	v_fmac_f32_e32 v114, v62, v62
	v_fmac_f32_e32 v115, v64, v64
	v_fmac_f32_e32 v59, v106, v106
	v_fmac_f32_e32 v61, v104, v104
	v_mul_f32_e32 v65, v109, v109
	v_fmac_f32_e32 v116, v58, v58
	global_store_dwordx4 v[112:113], v[50:53], off sc1
	v_fmac_f32_e32 v63, v110, v110
	v_fmac_f32_e32 v117, v60, v60
	v_add_f32_e32 v50, v114, v115
	v_add_f32_e32 v51, v59, v61
	v_fmac_f32_e32 v65, v108, v108
	v_add_f32_e32 v50, v116, v50
	v_add_f32_e32 v51, v63, v51
	v_add_f32_e32 v50, v117, v50
	v_add_f32_e32 v51, v65, v51
	v_add_f32_e32 v50, v50, v51
	v_mov_b32_e32 v51, v50
	s_nop 1
	v_permlane16_swap_b32_e32 v50, v51
	v_add_f32_e32 v50, v50, v51
	v_mov_b32_e32 v51, v50
	v_cvt_pk_bf16_f32 v54, v106, v107
	v_cvt_pk_bf16_f32 v55, v104, v105
	v_cvt_pk_bf16_f32 v56, v110, v111
	v_cvt_pk_bf16_f32 v57, v108, v109
	v_permlane32_swap_b32_e32 v50, v51
	global_store_dwordx4 v[112:113], v[54:57], off offset:256 sc1
	s_and_saveexec_b64 s[26:27], s[2:3]
	s_cbranch_execz .LBB0_337
	v_lshlrev_b64 v[52:53], 6, v[102:103]
	v_lshl_add_u64 v[52:53], s[12:13], 0, v[52:53]
	v_lshl_add_u64 v[52:53], s[24:25], 2, v[52:53]
	s_lshl_b32 s78, s41, 2
	v_lshl_add_u64 v[52:53], v[52:53], 0, s[78:79]
	v_add_f32_e32 v50, v50, v51
	global_store_dword v[52:53], v50, off
.LBB0_337:
	s_or_b64 exec, exec, s[26:27]
	v_lshlrev_b32_e32 v50, 16, v86
	v_and_b32_e32 v51, 0xffff0000, v86
	v_lshlrev_b32_e32 v52, 16, v87
	v_and_b32_e32 v53, 0xffff0000, v87
	v_lshlrev_b32_e32 v54, 16, v88
	v_and_b32_e32 v55, 0xffff0000, v88
	v_lshlrev_b32_e32 v56, 16, v89
	v_and_b32_e32 v57, 0xffff0000, v89
	v_pk_add_f32 v[48:49], v[48:49], v[52:53]
	v_pk_add_f32 v[46:47], v[46:47], v[50:51]
	v_pk_add_f32 v[50:51], v[44:45], v[56:57]
	v_pk_add_f32 v[44:45], v[42:43], v[54:55]
	v_mul_f32_e32 v42, v47, v47
	v_mul_f32_e32 v43, v49, v49
	v_fmac_f32_e32 v42, v46, v46
	v_fmac_f32_e32 v43, v48, v48
	v_add_f32_e32 v42, v42, v43
	v_mul_f32_e32 v43, v45, v45
	v_fmac_f32_e32 v43, v44, v44
	v_add_f32_e32 v42, v43, v42
	v_mul_f32_e32 v43, v51, v51
	v_fmac_f32_e32 v43, v50, v50
	v_lshlrev_b32_e32 v58, 16, v82
	v_and_b32_e32 v59, 0xffff0000, v82
	v_lshlrev_b32_e32 v60, 16, v83
	v_and_b32_e32 v61, 0xffff0000, v83
	v_add_f32_e32 v52, v43, v42
	v_cvt_pk_bf16_f32 v42, v46, v47
	v_lshl_add_u64 v[46:47], s[80:81], 0, v[100:101]
	v_lshlrev_b32_e32 v62, 16, v84
	v_and_b32_e32 v63, 0xffff0000, v84
	v_lshlrev_b32_e32 v64, 16, v85
	v_and_b32_e32 v65, 0xffff0000, v85
	v_cvt_pk_bf16_f32 v43, v48, v49
	v_cvt_pk_bf16_f32 v44, v44, v45
	v_cvt_pk_bf16_f32 v45, v50, v51
	v_lshl_add_u64 v[46:47], v[166:167], 1, v[46:47]
	v_pk_add_f32 v[40:41], v[40:41], v[60:61]
	v_pk_add_f32 v[38:39], v[38:39], v[58:59]
	global_store_dwordx4 v[46:47], v[42:45], off sc1
	s_nop 1
	v_pk_add_f32 v[42:43], v[36:37], v[64:65]
	v_pk_add_f32 v[36:37], v[34:35], v[62:63]
	v_mul_f32_e32 v34, v39, v39
	v_mul_f32_e32 v35, v41, v41
	v_fmac_f32_e32 v34, v38, v38
	v_fmac_f32_e32 v35, v40, v40
	v_add_f32_e32 v34, v34, v35
	v_mul_f32_e32 v35, v37, v37
	v_fmac_f32_e32 v35, v36, v36
	v_add_f32_e32 v34, v35, v34
	v_mul_f32_e32 v35, v43, v43
	v_fmac_f32_e32 v35, v42, v42
	v_add_f32_e32 v34, v35, v34
	v_add_f32_e32 v44, v52, v34
	v_cvt_pk_bf16_f32 v34, v38, v39
	v_cvt_pk_bf16_f32 v35, v40, v41
	v_cvt_pk_bf16_f32 v36, v36, v37
	v_cvt_pk_bf16_f32 v37, v42, v43
	global_store_dwordx4 v[46:47], v[34:37], off offset:256 sc1
	s_nop 1
	v_mov_b32_e32 v34, v44
	s_nop 1
	v_permlane16_swap_b32_e32 v44, v34
	v_add_f32_e32 v34, v44, v34
	v_mov_b32_e32 v35, v34
	s_nop 1
	v_permlane32_swap_b32_e32 v34, v35
	s_and_saveexec_b64 s[26:27], s[2:3]
	s_cbranch_execz .LBB0_339
	v_lshlrev_b64 v[36:37], 6, v[98:99]
	v_lshl_add_u64 v[36:37], s[12:13], 0, v[36:37]
	v_lshl_add_u64 v[36:37], s[24:25], 2, v[36:37]
	s_lshl_b32 s78, s41, 2
	v_lshl_add_u64 v[36:37], v[36:37], 0, s[78:79]
	v_add_f32_e32 v34, v34, v35
	global_store_dword v[36:37], v34, off
.LBB0_339:
	s_or_b64 exec, exec, s[26:27]
	v_lshlrev_b32_e32 v34, 16, v78
	v_and_b32_e32 v35, 0xffff0000, v78
	v_lshlrev_b32_e32 v36, 16, v79
	v_and_b32_e32 v37, 0xffff0000, v79
	v_lshlrev_b32_e32 v38, 16, v80
	v_and_b32_e32 v39, 0xffff0000, v80
	v_lshlrev_b32_e32 v40, 16, v81
	v_and_b32_e32 v41, 0xffff0000, v81
	v_pk_add_f32 v[32:33], v[32:33], v[36:37]
	v_pk_add_f32 v[30:31], v[30:31], v[34:35]
	v_pk_add_f32 v[34:35], v[28:29], v[40:41]
	v_pk_add_f32 v[28:29], v[26:27], v[38:39]
	v_mul_f32_e32 v26, v31, v31
	v_mul_f32_e32 v27, v33, v33
	v_fmac_f32_e32 v26, v30, v30
	v_fmac_f32_e32 v27, v32, v32
	v_add_f32_e32 v26, v26, v27
	v_mul_f32_e32 v27, v29, v29
	v_fmac_f32_e32 v27, v28, v28
	v_add_f32_e32 v26, v27, v26
	v_mul_f32_e32 v27, v35, v35
	v_fmac_f32_e32 v27, v34, v34
	v_lshlrev_b32_e32 v42, 16, v74
	v_and_b32_e32 v43, 0xffff0000, v74
	v_lshlrev_b32_e32 v44, 16, v75
	v_and_b32_e32 v45, 0xffff0000, v75
	v_add_f32_e32 v36, v27, v26
	v_cvt_pk_bf16_f32 v26, v30, v31
	v_lshl_add_u64 v[30:31], s[80:81], 0, v[96:97]
	v_lshlrev_b32_e32 v46, 16, v76
	v_and_b32_e32 v47, 0xffff0000, v76
	v_lshlrev_b32_e32 v48, 16, v77
	v_and_b32_e32 v49, 0xffff0000, v77
	v_cvt_pk_bf16_f32 v27, v32, v33
	v_cvt_pk_bf16_f32 v28, v28, v29
	v_cvt_pk_bf16_f32 v29, v34, v35
	v_lshl_add_u64 v[30:31], v[166:167], 1, v[30:31]
	v_pk_add_f32 v[24:25], v[24:25], v[44:45]
	v_pk_add_f32 v[22:23], v[22:23], v[42:43]
	global_store_dwordx4 v[30:31], v[26:29], off sc1
	s_nop 1
	v_pk_add_f32 v[26:27], v[20:21], v[48:49]
	v_pk_add_f32 v[20:21], v[18:19], v[46:47]
	v_mul_f32_e32 v18, v23, v23
	v_mul_f32_e32 v19, v25, v25
	v_fmac_f32_e32 v18, v22, v22
	v_fmac_f32_e32 v19, v24, v24
	v_add_f32_e32 v18, v18, v19
	v_mul_f32_e32 v19, v21, v21
	v_fmac_f32_e32 v19, v20, v20
	v_add_f32_e32 v18, v19, v18
	v_mul_f32_e32 v19, v27, v27
	v_fmac_f32_e32 v19, v26, v26
	v_add_f32_e32 v18, v19, v18
	v_add_f32_e32 v28, v36, v18
	v_cvt_pk_bf16_f32 v18, v22, v23
	v_cvt_pk_bf16_f32 v19, v24, v25
	v_cvt_pk_bf16_f32 v20, v20, v21
	v_cvt_pk_bf16_f32 v21, v26, v27
	global_store_dwordx4 v[30:31], v[18:21], off offset:256 sc1
	s_nop 1
	v_mov_b32_e32 v18, v28
	s_nop 1
	v_permlane16_swap_b32_e32 v28, v18
	v_add_f32_e32 v18, v28, v18
	v_mov_b32_e32 v19, v18
	s_nop 1
	v_permlane32_swap_b32_e32 v18, v19
	s_and_saveexec_b64 s[26:27], s[2:3]
	s_cbranch_execz .LBB0_341
	v_lshlrev_b64 v[20:21], 6, v[94:95]
	v_lshl_add_u64 v[20:21], s[12:13], 0, v[20:21]
	v_lshl_add_u64 v[20:21], s[24:25], 2, v[20:21]
	s_lshl_b32 s78, s41, 2
	v_lshl_add_u64 v[20:21], v[20:21], 0, s[78:79]
	v_add_f32_e32 v18, v18, v19
	global_store_dword v[20:21], v18, off
.LBB0_341:
	s_or_b64 exec, exec, s[26:27]
	v_lshlrev_b32_e32 v18, 16, v70
	v_and_b32_e32 v19, 0xffff0000, v70
	v_lshlrev_b32_e32 v20, 16, v71
	v_and_b32_e32 v21, 0xffff0000, v71
	v_lshlrev_b32_e32 v22, 16, v72
	v_and_b32_e32 v23, 0xffff0000, v72
	v_lshlrev_b32_e32 v24, 16, v73
	v_and_b32_e32 v25, 0xffff0000, v73
	v_pk_add_f32 v[16:17], v[16:17], v[20:21]
	v_pk_add_f32 v[14:15], v[14:15], v[18:19]
	v_pk_add_f32 v[18:19], v[12:13], v[24:25]
	v_pk_add_f32 v[12:13], v[10:11], v[22:23]
	v_mul_f32_e32 v10, v15, v15
	v_mul_f32_e32 v11, v17, v17
	v_fmac_f32_e32 v10, v14, v14
	v_fmac_f32_e32 v11, v16, v16
	v_add_f32_e32 v10, v10, v11
	v_mul_f32_e32 v11, v13, v13
	v_fmac_f32_e32 v11, v12, v12
	v_add_f32_e32 v10, v11, v10
	v_mul_f32_e32 v11, v19, v19
	v_fmac_f32_e32 v11, v18, v18
	v_lshlrev_b32_e32 v26, 16, v66
	v_and_b32_e32 v27, 0xffff0000, v66
	v_lshlrev_b32_e32 v28, 16, v67
	v_and_b32_e32 v29, 0xffff0000, v67
	v_add_f32_e32 v20, v11, v10
	v_cvt_pk_bf16_f32 v10, v14, v15
	v_lshl_add_u64 v[14:15], s[80:81], 0, v[92:93]
	v_lshlrev_b32_e32 v30, 16, v68
	v_and_b32_e32 v31, 0xffff0000, v68
	v_lshlrev_b32_e32 v32, 16, v69
	v_and_b32_e32 v33, 0xffff0000, v69
	v_cvt_pk_bf16_f32 v11, v16, v17
	v_cvt_pk_bf16_f32 v12, v12, v13
	v_cvt_pk_bf16_f32 v13, v18, v19
	v_lshl_add_u64 v[14:15], v[166:167], 1, v[14:15]
	v_pk_add_f32 v[8:9], v[8:9], v[28:29]
	v_pk_add_f32 v[6:7], v[6:7], v[26:27]
	global_store_dwordx4 v[14:15], v[10:13], off sc1
	s_nop 1
	v_pk_add_f32 v[10:11], v[4:5], v[32:33]
	v_pk_add_f32 v[4:5], v[2:3], v[30:31]
	v_mul_f32_e32 v2, v7, v7
	v_mul_f32_e32 v3, v9, v9
	v_fmac_f32_e32 v2, v6, v6
	v_fmac_f32_e32 v3, v8, v8
	v_add_f32_e32 v2, v2, v3
	v_mul_f32_e32 v3, v5, v5
	v_fmac_f32_e32 v3, v4, v4
	v_add_f32_e32 v2, v3, v2
	v_mul_f32_e32 v3, v11, v11
	v_fmac_f32_e32 v3, v10, v10
	v_add_f32_e32 v2, v3, v2
	v_add_f32_e32 v12, v20, v2
	v_cvt_pk_bf16_f32 v2, v6, v7
	v_cvt_pk_bf16_f32 v3, v8, v9
	v_cvt_pk_bf16_f32 v4, v4, v5
	v_cvt_pk_bf16_f32 v5, v10, v11
	global_store_dwordx4 v[14:15], v[2:5], off offset:256 sc1
	s_nop 1
	v_mov_b32_e32 v2, v12
	s_nop 1
	v_permlane16_swap_b32_e32 v12, v2
	v_add_f32_e32 v2, v12, v2
	v_mov_b32_e32 v3, v2
	s_nop 1
	v_permlane32_swap_b32_e32 v2, v3
	s_and_saveexec_b64 s[26:27], s[2:3]
	s_cbranch_execz .LBB0_343
	v_lshlrev_b64 v[4:5], 6, v[90:91]
	v_lshl_add_u64 v[4:5], s[12:13], 0, v[4:5]
	v_lshl_add_u64 v[4:5], s[24:25], 2, v[4:5]
	s_lshl_b32 s78, s41, 2
	v_lshl_add_u64 v[4:5], v[4:5], 0, s[78:79]
	v_add_f32_e32 v2, v2, v3
	global_store_dword v[4:5], v2, off

.LBB0_364:
	v_lshl_add_u32 v168, s37, 8, v1
	v_or_b32_e32 v164, 16, v168
	v_ashrrev_i32_e32 v169, 31, v168
	v_ashrrev_i32_e32 v165, 31, v164
	v_lshlrev_b64 v[144:145], 6, v[168:169]
	v_lshlrev_b64 v[146:147], 6, v[164:165]
	v_or_b32_e32 v160, 32, v168
	v_or_b32_e32 v156, 48, v168
	v_lshl_add_u64 v[144:145], v[138:139], 0, v[144:145]
	v_lshl_add_u64 v[146:147], v[138:139], 0, v[146:147]
	v_ashrrev_i32_e32 v161, 31, v160
	v_ashrrev_i32_e32 v157, 31, v156
	global_load_dwordx4 v[170:173], v[144:145], off
	global_load_dwordx4 v[174:177], v[146:147], off
	v_lshlrev_b64 v[144:145], 6, v[160:161]
	v_lshlrev_b64 v[146:147], 6, v[156:157]
	v_add_u32_e32 v152, 0x80, v168
	v_add_u32_e32 v148, 0x90, v168
	v_lshl_add_u64 v[144:145], v[138:139], 0, v[144:145]
	v_lshl_add_u64 v[146:147], v[138:139], 0, v[146:147]
	v_ashrrev_i32_e32 v153, 31, v152
	v_ashrrev_i32_e32 v149, 31, v148
	global_load_dwordx4 v[178:181], v[144:145], off
	global_load_dwordx4 v[182:185], v[146:147], off
	v_lshlrev_b64 v[144:145], 6, v[152:153]
	v_lshlrev_b64 v[146:147], 6, v[148:149]
	v_lshl_add_u64 v[144:145], v[138:139], 0, v[144:145]
	v_lshl_add_u64 v[146:147], v[138:139], 0, v[146:147]
	global_load_dwordx4 v[186:189], v[144:145], off
	global_load_dwordx4 v[190:193], v[146:147], off
	v_add_u32_e32 v146, 0xa0, v168
	v_ashrrev_i32_e32 v147, 31, v146
	v_lshlrev_b64 v[144:145], 6, v[146:147]
	v_lshl_add_u64 v[162:163], v[138:139], 0, v[144:145]
	v_add_u32_e32 v144, 0xb0, v168
	v_ashrrev_i32_e32 v145, 31, v144
	v_lshlrev_b64 v[166:167], 6, v[144:145]
	v_lshl_add_u64 v[166:167], v[138:139], 0, v[166:167]
	global_load_dwordx4 v[194:197], v[162:163], off
	global_load_dwordx4 v[198:201], v[166:167], off
	v_lshl_or_b32 v202, s36, 7, v155
	v_ashrrev_i32_e32 v203, 31, v202
	s_andn2_b64 vcc, exec, s[2:3]
	s_mov_b64 s[2:3], -1
	s_waitcnt vmcnt(0)
	v_add_f32_e32 v145, v170, v171
	v_add_f32_e32 v147, v172, v173
	v_add_f32_e32 v145, v145, v147
	v_add_f32_e32 v147, v174, v175
	v_add_f32_e32 v149, v176, v177
	v_add_f32_e32 v150, v178, v179
	v_add_f32_e32 v153, v180, v181
	v_mov_b32_e32 v161, v145
	v_add_f32_e32 v147, v147, v149
	v_add_f32_e32 v149, v150, v153
	v_permlane16_swap_b32_e32 v145, v161
	v_mov_b32_e32 v153, v147
	v_add_f32_e32 v154, v182, v183
	v_add_f32_e32 v157, v184, v185
	v_add_f32_e32 v145, v145, v161
	v_permlane16_swap_b32_e32 v147, v153
	v_add_f32_e32 v150, v154, v157
	v_mov_b32_e32 v154, v149
	v_mov_b32_e32 v161, v145
	v_add_f32_e32 v147, v147, v153
	v_permlane16_swap_b32_e32 v149, v154
	v_permlane32_swap_b32_e32 v145, v161
	v_mov_b32_e32 v153, v147
	v_add_f32_e32 v149, v149, v154
	v_add_f32_e32 v145, v145, v161
	v_permlane32_swap_b32_e32 v147, v153
	v_mov_b32_e32 v154, v149
	v_fmamk_f32 v145, v145, 0x3a800000, v235
	v_add_f32_e32 v147, v147, v153
	v_permlane32_swap_b32_e32 v149, v154
	v_rsq_f32_e32 v170, v145
	v_fmamk_f32 v145, v147, 0x3a800000, v235
	v_add_f32_e32 v158, v186, v187
	v_add_f32_e32 v149, v149, v154
	v_rsq_f32_e32 v172, v145
	v_add_f32_e32 v145, v188, v189
	v_fmamk_f32 v147, v149, 0x3a800000, v235
	v_add_f32_e32 v145, v158, v145
	v_rsq_f32_e32 v166, v147
	v_mov_b32_e32 v147, v145
	s_nop 1
	v_permlane16_swap_b32_e32 v145, v147
	v_add_f32_e32 v145, v145, v147
	v_mov_b32_e32 v147, v145
	s_nop 1
	v_permlane32_swap_b32_e32 v145, v147
	v_add_f32_e32 v145, v145, v147
	v_fmamk_f32 v145, v145, 0x3a800000, v235
	v_rsq_f32_e32 v158, v145
	v_add_f32_e32 v145, v190, v191
	v_add_f32_e32 v147, v192, v193
	v_add_f32_e32 v145, v145, v147
	v_mov_b32_e32 v147, v145
	s_nop 1
	v_permlane16_swap_b32_e32 v145, v147
	v_add_f32_e32 v145, v145, v147
	v_mov_b32_e32 v147, v145
	s_nop 1
	v_permlane32_swap_b32_e32 v145, v147
	v_add_f32_e32 v145, v145, v147
	v_fmamk_f32 v145, v145, 0x3a800000, v235
	v_rsq_f32_e32 v154, v145
	v_add_f32_e32 v145, v194, v195
	v_add_f32_e32 v147, v196, v197
	v_add_f32_e32 v145, v145, v147
	v_mov_b32_e32 v147, v145
	v_mov_b32_e32 v157, v150
	s_nop 0
	v_permlane16_swap_b32_e32 v145, v147
	v_permlane16_swap_b32_e32 v150, v157
	v_add_f32_e32 v145, v145, v147
	v_add_f32_e32 v150, v150, v157
	v_mov_b32_e32 v147, v145
	v_mov_b32_e32 v157, v150
	s_nop 0
	v_permlane32_swap_b32_e32 v145, v147
	v_permlane32_swap_b32_e32 v150, v157
	v_add_f32_e32 v145, v145, v147
	v_add_f32_e32 v150, v150, v157
	v_fmamk_f32 v145, v145, 0x3a800000, v235
	v_fmamk_f32 v149, v150, 0x3a800000, v235
	v_rsq_f32_e32 v150, v145
	v_add_f32_e32 v145, v198, v199
	v_add_f32_e32 v147, v200, v201
	v_add_f32_e32 v145, v145, v147
	v_mov_b32_e32 v147, v145
	s_nop 1
	v_permlane16_swap_b32_e32 v145, v147
	v_add_f32_e32 v145, v145, v147
	v_mov_b32_e32 v147, v145
	s_nop 1
	v_permlane32_swap_b32_e32 v145, v147
	v_pk_mul_f32 v[174:175], v[126:127], v[170:171] op_sel_hi:[1,0]
	v_add_f32_e32 v145, v145, v147
	v_mul_f32_e32 v126, 0xbfb8aa3b, v174
	v_exp_f32_e32 v127, v126
	v_fmamk_f32 v126, v145, 0x3a800000, v235
	v_mul_f32_e32 v145, 0xbfb8aa3b, v175
	v_exp_f32_e32 v145, v145
	v_add_f32_e32 v127, 1.0, v127
	v_rcp_f32_e32 v176, v127
	v_pk_mul_f32 v[128:129], v[128:129], v[170:171] op_sel_hi:[1,0]
	v_add_f32_e32 v127, 1.0, v145
	v_rcp_f32_e32 v177, v127
	v_mul_f32_e32 v127, 0xbfb8aa3b, v128
	v_exp_f32_e32 v127, v127
	v_mul_f32_e32 v145, 0xbfb8aa3b, v129
	v_exp_f32_e32 v145, v145
	v_pk_mul_f32 v[118:119], v[118:119], v[170:171] op_sel_hi:[1,0]
	v_add_f32_e32 v127, 1.0, v127
	v_pk_mul_f32 v[118:119], v[174:175], v[118:119]
	v_rcp_f32_e32 v174, v127
	v_add_f32_e32 v127, 1.0, v145
	v_pk_mul_f32 v[122:123], v[122:123], v[170:171] op_sel_hi:[1,0]
	v_pk_mul_f32 v[120:121], v[120:121], v[170:171] op_sel_hi:[1,0]
	v_pk_mul_f32 v[114:115], v[114:115], v[170:171] op_sel_hi:[1,0]
	v_rcp_f32_e32 v175, v127
	v_mul_f32_e32 v127, 0xbfb8aa3b, v122
	v_pk_mul_f32 v[120:121], v[128:129], v[120:121]
	v_mul_f32_e32 v128, 0xbfb8aa3b, v123
	v_pk_mul_f32 v[114:115], v[122:123], v[114:115]
	v_pk_mul_f32 v[122:123], v[124:125], v[170:171] op_sel_hi:[1,0]
	v_exp_f32_e32 v127, v127
	v_mul_f32_e32 v124, 0xbfb8aa3b, v122
	v_mul_f32_e32 v125, 0xbfb8aa3b, v123
	v_exp_f32_e32 v124, v124
	v_exp_f32_e32 v125, v125
	v_exp_f32_e32 v129, v128
	v_add_f32_e32 v127, 1.0, v127
	v_add_f32_e32 v124, 1.0, v124
	v_add_f32_e32 v125, 1.0, v125
	v_rcp_f32_e32 v128, v127
	v_add_f32_e32 v127, 1.0, v129
	v_rcp_f32_e32 v124, v124
	v_rcp_f32_e32 v125, v125
	v_rcp_f32_e32 v129, v127
	v_pk_mul_f32 v[116:117], v[116:117], v[170:171] op_sel_hi:[1,0]
	v_pk_mul_f32 v[118:119], v[118:119], v[176:177]
	v_pk_mul_f32 v[116:117], v[122:123], v[116:117]
	v_pk_mul_f32 v[114:115], v[114:115], v[128:129]
	v_pk_mul_f32 v[122:123], v[116:117], v[124:125]
	v_cvt_pk_bf16_f32 v116, v118, v119
	v_cvt_pk_bf16_f32 v119, v122, v123
	v_pk_mul_f32 v[122:123], v[110:111], v[172:173] op_sel_hi:[1,0]
	v_pk_mul_f32 v[120:121], v[120:121], v[174:175]
	v_cvt_pk_bf16_f32 v118, v114, v115
	v_mov_b64_e32 v[114:115], s[96:97]
	v_mul_f32_e32 v110, 0xbfb8aa3b, v122
	v_cvt_pk_bf16_f32 v117, v120, v121
	v_mad_i64_i32 v[120:121], s[14:15], v168, s69, v[114:115]
	v_exp_f32_e32 v124, v110
	v_lshlrev_b64 v[110:111], 1, v[202:203]
	v_lshl_add_u64 v[120:121], v[120:121], 0, v[110:111]
	global_store_dwordx4 v[120:121], v[116:119], off sc1
	v_pk_mul_f32 v[112:113], v[112:113], v[172:173] op_sel_hi:[1,0]
	v_pk_mul_f32 v[102:103], v[102:103], v[172:173] op_sel_hi:[1,0]
	v_mul_f32_e32 v117, 0xbfb8aa3b, v123
	v_exp_f32_e32 v117, v117
	v_add_f32_e32 v116, 1.0, v124
	v_mul_f32_e32 v118, 0xbfb8aa3b, v112
	v_rcp_f32_e32 v116, v116
	v_add_f32_e32 v117, 1.0, v117
	v_rcp_f32_e32 v117, v117
	v_exp_f32_e32 v118, v118
	v_pk_mul_f32 v[102:103], v[122:123], v[102:103]
	v_pk_mul_f32 v[106:107], v[106:107], v[172:173] op_sel_hi:[1,0]
	v_pk_mul_f32 v[104:105], v[104:105], v[172:173] op_sel_hi:[1,0]
	v_mul_f32_e32 v119, 0xbfb8aa3b, v113
	v_pk_mul_f32 v[102:103], v[102:103], v[116:117]
	v_add_f32_e32 v116, 1.0, v118
	v_mul_f32_e32 v118, 0xbfb8aa3b, v106
	v_pk_mul_f32 v[104:105], v[112:113], v[104:105]
	v_mul_f32_e32 v113, 0xbfb8aa3b, v107
	v_pk_mul_f32 v[98:99], v[98:99], v[172:173] op_sel_hi:[1,0]
	v_exp_f32_e32 v118, v118
	v_exp_f32_e32 v113, v113
	v_pk_mul_f32 v[98:99], v[106:107], v[98:99]
	v_pk_mul_f32 v[106:107], v[108:109], v[172:173] op_sel_hi:[1,0]
	v_exp_f32_e32 v119, v119
	v_mul_f32_e32 v108, 0xbfb8aa3b, v106
	v_mul_f32_e32 v109, 0xbfb8aa3b, v107
	v_exp_f32_e32 v108, v108
	v_exp_f32_e32 v109, v109
	v_add_f32_e32 v112, 1.0, v118
	v_add_f32_e32 v113, 1.0, v113
	v_rcp_f32_e32 v112, v112
	v_rcp_f32_e32 v113, v113
	v_add_f32_e32 v117, 1.0, v119
	v_add_f32_e32 v108, 1.0, v108
	v_add_f32_e32 v109, 1.0, v109
	v_rcp_f32_e32 v116, v116
	v_rcp_f32_e32 v117, v117
	v_rcp_f32_e32 v108, v108
	v_rcp_f32_e32 v109, v109
	v_pk_mul_f32 v[112:113], v[98:99], v[112:113]
	v_pk_mul_f32 v[98:99], v[100:101], v[172:173] op_sel_hi:[1,0]
	v_pk_mul_f32 v[94:95], v[94:95], v[166:167] op_sel_hi:[1,0]
	v_pk_mul_f32 v[98:99], v[106:107], v[98:99]
	v_pk_mul_f32 v[104:105], v[104:105], v[116:117]
	v_pk_mul_f32 v[106:107], v[98:99], v[108:109]
	v_cvt_pk_bf16_f32 v98, v102, v103
	v_mul_f32_e32 v102, 0xbfb8aa3b, v94
	v_cvt_pk_bf16_f32 v99, v104, v105
	v_exp_f32_e32 v104, v102
	v_mad_i64_i32 v[102:103], s[14:15], v164, s69, v[114:115]
	v_cvt_pk_bf16_f32 v100, v112, v113
	v_cvt_pk_bf16_f32 v101, v106, v107
	v_lshl_add_u64 v[102:103], v[102:103], 0, v[110:111]
	global_store_dwordx4 v[102:103], v[98:101], off sc1
	v_pk_mul_f32 v[86:87], v[86:87], v[166:167] op_sel_hi:[1,0]
	v_pk_mul_f32 v[90:91], v[90:91], v[166:167] op_sel_hi:[1,0]
	v_mul_f32_e32 v99, 0xbfb8aa3b, v95
	v_exp_f32_e32 v99, v99
	v_add_f32_e32 v98, 1.0, v104
	v_pk_mul_f32 v[86:87], v[94:95], v[86:87]
	v_rcp_f32_e32 v98, v98
	v_add_f32_e32 v94, 1.0, v99
	v_rcp_f32_e32 v99, v94
	v_pk_mul_f32 v[94:95], v[96:97], v[166:167] op_sel_hi:[1,0]
	v_pk_mul_f32 v[88:89], v[88:89], v[166:167] op_sel_hi:[1,0]
	v_mul_f32_e32 v97, 0xbfb8aa3b, v95
	v_pk_mul_f32 v[86:87], v[86:87], v[98:99]
	v_mul_f32_e32 v98, 0xbfb8aa3b, v90
	v_pk_mul_f32 v[88:89], v[94:95], v[88:89]
	v_mul_f32_e32 v95, 0xbfb8aa3b, v91
	v_pk_mul_f32 v[82:83], v[82:83], v[166:167] op_sel_hi:[1,0]
	v_exp_f32_e32 v98, v98
	v_exp_f32_e32 v95, v95
	v_pk_mul_f32 v[82:83], v[90:91], v[82:83]
	v_pk_mul_f32 v[90:91], v[92:93], v[166:167] op_sel_hi:[1,0]
	v_mul_f32_e32 v96, 0xbfb8aa3b, v94
	v_mul_f32_e32 v92, 0xbfb8aa3b, v90
	v_mul_f32_e32 v93, 0xbfb8aa3b, v91
	v_exp_f32_e32 v96, v96
	v_exp_f32_e32 v97, v97
	v_exp_f32_e32 v92, v92
	v_exp_f32_e32 v93, v93
	v_add_f32_e32 v94, 1.0, v98
	v_add_f32_e32 v95, 1.0, v95
	v_rcp_f32_e32 v94, v94
	v_rcp_f32_e32 v95, v95
	v_rsq_f32_e32 v162, v149
	v_add_f32_e32 v96, 1.0, v96
	v_add_f32_e32 v97, 1.0, v97
	v_add_f32_e32 v92, 1.0, v92
	v_add_f32_e32 v93, 1.0, v93
	v_rcp_f32_e32 v96, v96
	v_rcp_f32_e32 v97, v97
	v_rcp_f32_e32 v92, v92
	v_rcp_f32_e32 v93, v93
	v_pk_mul_f32 v[94:95], v[82:83], v[94:95]
	v_pk_mul_f32 v[82:83], v[84:85], v[166:167] op_sel_hi:[1,0]
	v_pk_mul_f32 v[78:79], v[78:79], v[162:163] op_sel_hi:[1,0]
	v_pk_mul_f32 v[82:83], v[90:91], v[82:83]
	v_pk_mul_f32 v[88:89], v[88:89], v[96:97]
	v_pk_mul_f32 v[90:91], v[82:83], v[92:93]
	v_cvt_pk_bf16_f32 v82, v86, v87
	v_mul_f32_e32 v86, 0xbfb8aa3b, v78
	v_cvt_pk_bf16_f32 v83, v88, v89
	v_exp_f32_e32 v88, v86
	v_mad_i64_i32 v[86:87], s[14:15], v160, s69, v[114:115]
	v_cvt_pk_bf16_f32 v84, v94, v95
	v_cvt_pk_bf16_f32 v85, v90, v91
	v_lshl_add_u64 v[86:87], v[86:87], 0, v[110:111]
	global_store_dwordx4 v[86:87], v[82:85], off sc1
	v_pk_mul_f32 v[70:71], v[70:71], v[162:163] op_sel_hi:[1,0]
	v_pk_mul_f32 v[74:75], v[74:75], v[162:163] op_sel_hi:[1,0]
	v_mul_f32_e32 v83, 0xbfb8aa3b, v79
	v_exp_f32_e32 v83, v83
	v_add_f32_e32 v82, 1.0, v88
	v_pk_mul_f32 v[70:71], v[78:79], v[70:71]
	v_rcp_f32_e32 v82, v82
	v_add_f32_e32 v78, 1.0, v83
	v_rcp_f32_e32 v83, v78
	v_pk_mul_f32 v[78:79], v[80:81], v[162:163] op_sel_hi:[1,0]
	v_pk_mul_f32 v[72:73], v[72:73], v[162:163] op_sel_hi:[1,0]
	v_mul_f32_e32 v81, 0xbfb8aa3b, v79
	v_pk_mul_f32 v[70:71], v[70:71], v[82:83]
	v_mul_f32_e32 v82, 0xbfb8aa3b, v74
	v_pk_mul_f32 v[72:73], v[78:79], v[72:73]
	v_mul_f32_e32 v79, 0xbfb8aa3b, v75
	v_pk_mul_f32 v[66:67], v[66:67], v[162:163] op_sel_hi:[1,0]
	v_exp_f32_e32 v82, v82
	v_exp_f32_e32 v79, v79
	v_pk_mul_f32 v[66:67], v[74:75], v[66:67]
	v_pk_mul_f32 v[74:75], v[76:77], v[162:163] op_sel_hi:[1,0]
	v_mul_f32_e32 v80, 0xbfb8aa3b, v78
	v_mul_f32_e32 v76, 0xbfb8aa3b, v74
	v_mul_f32_e32 v77, 0xbfb8aa3b, v75
	v_exp_f32_e32 v80, v80
	v_exp_f32_e32 v81, v81
	v_exp_f32_e32 v76, v76
	v_exp_f32_e32 v77, v77
	v_add_f32_e32 v78, 1.0, v82
	v_add_f32_e32 v79, 1.0, v79
	v_rcp_f32_e32 v78, v78
	v_rcp_f32_e32 v79, v79
	v_add_f32_e32 v80, 1.0, v80
	v_add_f32_e32 v81, 1.0, v81
	v_add_f32_e32 v76, 1.0, v76
	v_add_f32_e32 v77, 1.0, v77
	v_rcp_f32_e32 v80, v80
	v_rcp_f32_e32 v81, v81
	v_rcp_f32_e32 v76, v76
	v_rcp_f32_e32 v77, v77
	v_pk_mul_f32 v[78:79], v[66:67], v[78:79]
	v_pk_mul_f32 v[66:67], v[68:69], v[162:163] op_sel_hi:[1,0]
	v_pk_mul_f32 v[62:63], v[62:63], v[158:159] op_sel_hi:[1,0]
	v_pk_mul_f32 v[66:67], v[74:75], v[66:67]
	v_pk_mul_f32 v[72:73], v[72:73], v[80:81]
	v_pk_mul_f32 v[74:75], v[66:67], v[76:77]
	v_cvt_pk_bf16_f32 v66, v70, v71
	v_mul_f32_e32 v70, 0xbfb8aa3b, v62
	v_cvt_pk_bf16_f32 v67, v72, v73
	v_exp_f32_e32 v72, v70
	v_mad_i64_i32 v[70:71], s[14:15], v156, s69, v[114:115]
	v_cvt_pk_bf16_f32 v68, v78, v79
	v_cvt_pk_bf16_f32 v69, v74, v75
	v_lshl_add_u64 v[70:71], v[70:71], 0, v[110:111]
	global_store_dwordx4 v[70:71], v[66:69], off sc1
	v_pk_mul_f32 v[54:55], v[54:55], v[158:159] op_sel_hi:[1,0]
	v_pk_mul_f32 v[58:59], v[58:59], v[158:159] op_sel_hi:[1,0]
	v_mul_f32_e32 v67, 0xbfb8aa3b, v63
	v_exp_f32_e32 v67, v67
	v_add_f32_e32 v66, 1.0, v72
	v_pk_mul_f32 v[54:55], v[62:63], v[54:55]
	v_rcp_f32_e32 v66, v66
	v_add_f32_e32 v62, 1.0, v67
	v_rcp_f32_e32 v67, v62
	v_pk_mul_f32 v[62:63], v[64:65], v[158:159] op_sel_hi:[1,0]
	v_pk_mul_f32 v[56:57], v[56:57], v[158:159] op_sel_hi:[1,0]
	v_mul_f32_e32 v65, 0xbfb8aa3b, v63
	v_pk_mul_f32 v[54:55], v[54:55], v[66:67]
	v_mul_f32_e32 v66, 0xbfb8aa3b, v58
	v_pk_mul_f32 v[56:57], v[62:63], v[56:57]
	v_mul_f32_e32 v63, 0xbfb8aa3b, v59
	v_pk_mul_f32 v[50:51], v[50:51], v[158:159] op_sel_hi:[1,0]
	v_exp_f32_e32 v66, v66
	v_exp_f32_e32 v63, v63
	v_pk_mul_f32 v[50:51], v[58:59], v[50:51]
	v_pk_mul_f32 v[58:59], v[60:61], v[158:159] op_sel_hi:[1,0]
	v_mul_f32_e32 v64, 0xbfb8aa3b, v62
	v_mul_f32_e32 v60, 0xbfb8aa3b, v58
	v_mul_f32_e32 v61, 0xbfb8aa3b, v59
	v_exp_f32_e32 v64, v64
	v_exp_f32_e32 v65, v65
	v_exp_f32_e32 v60, v60
	v_exp_f32_e32 v61, v61
	v_add_f32_e32 v62, 1.0, v66
	v_add_f32_e32 v63, 1.0, v63
	v_rcp_f32_e32 v62, v62
	v_rcp_f32_e32 v63, v63
	v_add_f32_e32 v64, 1.0, v64
	v_add_f32_e32 v65, 1.0, v65
	v_add_f32_e32 v60, 1.0, v60
	v_add_f32_e32 v61, 1.0, v61
	v_rcp_f32_e32 v64, v64
	v_rcp_f32_e32 v65, v65
	v_rcp_f32_e32 v60, v60
	v_rcp_f32_e32 v61, v61
	v_pk_mul_f32 v[62:63], v[50:51], v[62:63]
	v_pk_mul_f32 v[50:51], v[52:53], v[158:159] op_sel_hi:[1,0]
	v_pk_mul_f32 v[46:47], v[46:47], v[154:155] op_sel_hi:[1,0]
	v_pk_mul_f32 v[50:51], v[58:59], v[50:51]
	v_pk_mul_f32 v[56:57], v[56:57], v[64:65]
	v_pk_mul_f32 v[58:59], v[50:51], v[60:61]
	v_cvt_pk_bf16_f32 v50, v54, v55
	v_mul_f32_e32 v54, 0xbfb8aa3b, v46
	v_cvt_pk_bf16_f32 v51, v56, v57
	v_exp_f32_e32 v56, v54
	v_mad_i64_i32 v[54:55], s[14:15], v152, s69, v[114:115]
	v_cvt_pk_bf16_f32 v52, v62, v63
	v_cvt_pk_bf16_f32 v53, v58, v59
	v_lshl_add_u64 v[54:55], v[54:55], 0, v[110:111]
	global_store_dwordx4 v[54:55], v[50:53], off sc1
	v_pk_mul_f32 v[38:39], v[38:39], v[154:155] op_sel_hi:[1,0]
	v_pk_mul_f32 v[42:43], v[42:43], v[154:155] op_sel_hi:[1,0]
	v_mul_f32_e32 v51, 0xbfb8aa3b, v47
	v_exp_f32_e32 v51, v51
	v_add_f32_e32 v50, 1.0, v56
	v_pk_mul_f32 v[38:39], v[46:47], v[38:39]
	v_rcp_f32_e32 v50, v50
	v_add_f32_e32 v46, 1.0, v51
	v_rcp_f32_e32 v51, v46
	v_pk_mul_f32 v[46:47], v[48:49], v[154:155] op_sel_hi:[1,0]
	v_pk_mul_f32 v[40:41], v[40:41], v[154:155] op_sel_hi:[1,0]
	v_mul_f32_e32 v49, 0xbfb8aa3b, v47
	v_pk_mul_f32 v[38:39], v[38:39], v[50:51]
	v_mul_f32_e32 v50, 0xbfb8aa3b, v42
	v_pk_mul_f32 v[40:41], v[46:47], v[40:41]
	v_mul_f32_e32 v47, 0xbfb8aa3b, v43
	v_pk_mul_f32 v[34:35], v[34:35], v[154:155] op_sel_hi:[1,0]
	v_exp_f32_e32 v50, v50
	v_exp_f32_e32 v47, v47
	v_pk_mul_f32 v[34:35], v[42:43], v[34:35]
	v_pk_mul_f32 v[42:43], v[44:45], v[154:155] op_sel_hi:[1,0]
	v_mul_f32_e32 v48, 0xbfb8aa3b, v46
	v_mul_f32_e32 v44, 0xbfb8aa3b, v42
	v_mul_f32_e32 v45, 0xbfb8aa3b, v43
	v_exp_f32_e32 v48, v48
	v_exp_f32_e32 v49, v49
	v_exp_f32_e32 v44, v44
	v_exp_f32_e32 v45, v45
	v_add_f32_e32 v46, 1.0, v50
	v_add_f32_e32 v47, 1.0, v47
	v_rcp_f32_e32 v46, v46
	v_rcp_f32_e32 v47, v47
	v_add_f32_e32 v48, 1.0, v48
	v_add_f32_e32 v49, 1.0, v49
	v_add_f32_e32 v44, 1.0, v44
	v_add_f32_e32 v45, 1.0, v45
	v_rcp_f32_e32 v48, v48
	v_rcp_f32_e32 v49, v49
	v_rcp_f32_e32 v44, v44
	v_rcp_f32_e32 v45, v45
	v_pk_mul_f32 v[46:47], v[34:35], v[46:47]
	v_pk_mul_f32 v[34:35], v[36:37], v[154:155] op_sel_hi:[1,0]
	v_pk_mul_f32 v[30:31], v[30:31], v[150:151] op_sel_hi:[1,0]
	v_pk_mul_f32 v[34:35], v[42:43], v[34:35]
	v_pk_mul_f32 v[40:41], v[40:41], v[48:49]
	v_pk_mul_f32 v[42:43], v[34:35], v[44:45]
	v_cvt_pk_bf16_f32 v34, v38, v39
	v_mul_f32_e32 v38, 0xbfb8aa3b, v30
	v_cvt_pk_bf16_f32 v35, v40, v41
	v_exp_f32_e32 v40, v38
	v_mad_i64_i32 v[38:39], s[14:15], v148, s69, v[114:115]
	v_cvt_pk_bf16_f32 v36, v46, v47
	v_cvt_pk_bf16_f32 v37, v42, v43
	v_lshl_add_u64 v[38:39], v[38:39], 0, v[110:111]
	global_store_dwordx4 v[38:39], v[34:37], off sc1
	v_pk_mul_f32 v[22:23], v[22:23], v[150:151] op_sel_hi:[1,0]
	v_pk_mul_f32 v[26:27], v[26:27], v[150:151] op_sel_hi:[1,0]
	v_mul_f32_e32 v35, 0xbfb8aa3b, v31
	v_exp_f32_e32 v35, v35
	v_add_f32_e32 v34, 1.0, v40
	v_pk_mul_f32 v[22:23], v[30:31], v[22:23]
	v_rcp_f32_e32 v34, v34
	v_add_f32_e32 v30, 1.0, v35
	v_rcp_f32_e32 v35, v30
	v_pk_mul_f32 v[30:31], v[32:33], v[150:151] op_sel_hi:[1,0]
	v_pk_mul_f32 v[24:25], v[24:25], v[150:151] op_sel_hi:[1,0]
	v_mul_f32_e32 v33, 0xbfb8aa3b, v31
	v_pk_mul_f32 v[22:23], v[22:23], v[34:35]
	v_mul_f32_e32 v34, 0xbfb8aa3b, v26
	v_pk_mul_f32 v[24:25], v[30:31], v[24:25]
	v_mul_f32_e32 v31, 0xbfb8aa3b, v27
	v_pk_mul_f32 v[18:19], v[18:19], v[150:151] op_sel_hi:[1,0]
	v_exp_f32_e32 v34, v34
	v_exp_f32_e32 v31, v31
	v_pk_mul_f32 v[18:19], v[26:27], v[18:19]
	v_pk_mul_f32 v[26:27], v[28:29], v[150:151] op_sel_hi:[1,0]
	v_mul_f32_e32 v32, 0xbfb8aa3b, v30
	v_mul_f32_e32 v28, 0xbfb8aa3b, v26
	v_mul_f32_e32 v29, 0xbfb8aa3b, v27
	v_exp_f32_e32 v32, v32
	v_exp_f32_e32 v33, v33
	v_exp_f32_e32 v28, v28
	v_exp_f32_e32 v29, v29
	v_add_f32_e32 v30, 1.0, v34
	v_add_f32_e32 v31, 1.0, v31
	v_rcp_f32_e32 v30, v30
	v_rcp_f32_e32 v31, v31
	v_rsq_f32_e32 v126, v126
	v_add_f32_e32 v32, 1.0, v32
	v_add_f32_e32 v33, 1.0, v33
	v_add_f32_e32 v28, 1.0, v28
	v_add_f32_e32 v29, 1.0, v29
	v_rcp_f32_e32 v32, v32
	v_rcp_f32_e32 v33, v33
	v_rcp_f32_e32 v28, v28
	v_rcp_f32_e32 v29, v29
	v_pk_mul_f32 v[30:31], v[18:19], v[30:31]
	v_pk_mul_f32 v[18:19], v[20:21], v[150:151] op_sel_hi:[1,0]
	v_pk_mul_f32 v[14:15], v[14:15], v[126:127] op_sel_hi:[1,0]
	v_pk_mul_f32 v[18:19], v[26:27], v[18:19]
	v_pk_mul_f32 v[24:25], v[24:25], v[32:33]
	v_pk_mul_f32 v[26:27], v[18:19], v[28:29]
	v_cvt_pk_bf16_f32 v18, v22, v23
	v_mul_f32_e32 v22, 0xbfb8aa3b, v14
	v_cvt_pk_bf16_f32 v19, v24, v25
	v_exp_f32_e32 v24, v22
	v_mad_i64_i32 v[22:23], s[14:15], v146, s69, v[114:115]
	v_cvt_pk_bf16_f32 v20, v30, v31
	v_cvt_pk_bf16_f32 v21, v26, v27
	v_lshl_add_u64 v[22:23], v[22:23], 0, v[110:111]
	global_store_dwordx4 v[22:23], v[18:21], off sc1
	v_pk_mul_f32 v[6:7], v[6:7], v[126:127] op_sel_hi:[1,0]
	v_pk_mul_f32 v[10:11], v[10:11], v[126:127] op_sel_hi:[1,0]
	v_mul_f32_e32 v19, 0xbfb8aa3b, v15
	v_exp_f32_e32 v19, v19
	v_add_f32_e32 v18, 1.0, v24
	v_pk_mul_f32 v[6:7], v[14:15], v[6:7]
	v_rcp_f32_e32 v18, v18
	v_add_f32_e32 v14, 1.0, v19
	v_rcp_f32_e32 v19, v14
	v_pk_mul_f32 v[14:15], v[16:17], v[126:127] op_sel_hi:[1,0]
	v_pk_mul_f32 v[8:9], v[8:9], v[126:127] op_sel_hi:[1,0]
	v_mul_f32_e32 v17, 0xbfb8aa3b, v15
	v_pk_mul_f32 v[6:7], v[6:7], v[18:19]
	v_mul_f32_e32 v18, 0xbfb8aa3b, v10
	v_pk_mul_f32 v[8:9], v[14:15], v[8:9]
	v_mul_f32_e32 v15, 0xbfb8aa3b, v11
	v_pk_mul_f32 v[2:3], v[2:3], v[126:127] op_sel_hi:[1,0]
	v_exp_f32_e32 v18, v18
	v_exp_f32_e32 v15, v15
	v_pk_mul_f32 v[2:3], v[10:11], v[2:3]
	v_pk_mul_f32 v[10:11], v[12:13], v[126:127] op_sel_hi:[1,0]
	v_mul_f32_e32 v16, 0xbfb8aa3b, v14
	v_mul_f32_e32 v12, 0xbfb8aa3b, v10
	v_mul_f32_e32 v13, 0xbfb8aa3b, v11
	v_exp_f32_e32 v16, v16
	v_exp_f32_e32 v17, v17
	v_exp_f32_e32 v12, v12
	v_exp_f32_e32 v13, v13
	v_add_f32_e32 v14, 1.0, v18
	v_add_f32_e32 v15, 1.0, v15
	v_rcp_f32_e32 v14, v14
	v_rcp_f32_e32 v15, v15
	v_add_f32_e32 v16, 1.0, v16
	v_add_f32_e32 v17, 1.0, v17
	v_add_f32_e32 v12, 1.0, v12
	v_add_f32_e32 v13, 1.0, v13
	v_rcp_f32_e32 v16, v16
	v_rcp_f32_e32 v17, v17
	v_rcp_f32_e32 v12, v12
	v_rcp_f32_e32 v13, v13
	v_pk_mul_f32 v[14:15], v[2:3], v[14:15]
	v_pk_mul_f32 v[2:3], v[4:5], v[126:127] op_sel_hi:[1,0]
	v_pk_mul_f32 v[8:9], v[8:9], v[16:17]
	v_pk_mul_f32 v[2:3], v[10:11], v[2:3]
	v_cvt_pk_bf16_f32 v4, v14, v15
	v_pk_mul_f32 v[10:11], v[2:3], v[12:13]
	v_cvt_pk_bf16_f32 v2, v6, v7
	v_mad_i64_i32 v[6:7], s[14:15], v144, s69, v[114:115]
	v_cvt_pk_bf16_f32 v3, v8, v9
	v_cvt_pk_bf16_f32 v5, v10, v11
	v_lshl_add_u64 v[6:7], v[6:7], 0, v[110:111]
	global_store_dwordx4 v[6:7], v[2:5], off sc1
	s_cbranch_vccnz .LBB0_357
	s_andn2_b64 vcc, exec, s[4:5]
	s_cbranch_vccnz .LBB0_356
	s_barrier
	s_branch .LBB0_356

.LBB0_398:
	s_waitcnt vmcnt(0)
	v_pk_add_f32 v[128:129], v[128:129], v[192:193]
	v_pk_add_f32 v[126:127], v[126:127], v[190:191]
	v_pk_add_f32 v[188:189], v[124:125], v[188:189]
	v_pk_add_f32 v[124:125], v[122:123], v[186:187]
	v_mul_f32_e32 v122, v127, v127
	v_mul_f32_e32 v123, v129, v129
	v_fmac_f32_e32 v122, v126, v126
	v_fmac_f32_e32 v123, v128, v128
	v_add_f32_e32 v122, v122, v123
	v_mul_f32_e32 v123, v125, v125
	v_fmac_f32_e32 v123, v124, v124
	v_add_f32_e32 v122, v122, v123
	v_mul_f32_e32 v123, v189, v189
	v_fmac_f32_e32 v123, v188, v188
	v_add_f32_e32 v186, v123, v122
	v_cvt_pk_bf16_f32 v122, v126, v127
	v_lshl_add_u64 v[126:127], s[80:81], 0, v[230:231]
	v_cvt_pk_bf16_f32 v123, v128, v129
	v_cvt_pk_bf16_f32 v124, v124, v125
	v_cvt_pk_bf16_f32 v125, v188, v189
	v_lshl_add_u64 v[126:127], v[214:215], 1, v[126:127]
	v_pk_add_f32 v[120:121], v[120:121], v[184:185]
	v_pk_add_f32 v[118:119], v[118:119], v[182:183]
	global_store_dwordx4 v[126:127], v[122:125], off sc1
	s_lshl_b32 s24, s43, 2
	s_ashr_i32 s25, s24, 31
	v_pk_add_f32 v[122:123], v[116:117], v[180:181]
	v_pk_add_f32 v[116:117], v[114:115], v[178:179]
	v_mul_f32_e32 v114, v119, v119
	v_mul_f32_e32 v115, v121, v121
	v_fmac_f32_e32 v114, v118, v118
	v_fmac_f32_e32 v115, v120, v120
	v_add_f32_e32 v114, v114, v115
	v_mul_f32_e32 v115, v117, v117
	v_fmac_f32_e32 v115, v116, v116
	v_add_f32_e32 v114, v114, v115
	v_mul_f32_e32 v115, v123, v123
	v_fmac_f32_e32 v115, v122, v122
	v_add_f32_e32 v114, v115, v114
	v_add_f32_e32 v124, v114, v186
	v_cvt_pk_bf16_f32 v114, v118, v119
	v_cvt_pk_bf16_f32 v115, v120, v121
	v_cvt_pk_bf16_f32 v116, v116, v117
	v_cvt_pk_bf16_f32 v117, v122, v123
	global_store_dwordx4 v[126:127], v[114:117], off offset:256 sc1
	s_nop 1
	v_mov_b32_e32 v114, v124
	s_nop 1
	v_permlane16_swap_b32_e32 v124, v114
	v_add_f32_e32 v114, v124, v114
	v_mov_b32_e32 v115, v114
	s_nop 1
	v_permlane32_swap_b32_e32 v114, v115
	s_and_saveexec_b64 s[26:27], s[2:3]
	s_cbranch_execz .LBB0_400
	v_lshlrev_b64 v[116:117], 6, v[220:221]
	v_lshl_add_u64 v[116:117], s[12:13], 0, v[116:117]
	v_lshl_add_u64 v[116:117], s[24:25], 2, v[116:117]
	s_lshl_b32 s78, s37, 2
	v_lshl_add_u64 v[116:117], v[116:117], 0, s[78:79]
	v_add_f32_e32 v114, v114, v115
	global_store_dword v[116:117], v114, off
.LBB0_400:
	s_or_b64 exec, exec, s[26:27]
	v_pk_add_f32 v[112:113], v[112:113], v[176:177]
	v_pk_add_f32 v[110:111], v[110:111], v[174:175]
	v_pk_add_f32 v[116:117], v[108:109], v[172:173]
	v_pk_add_f32 v[108:109], v[106:107], v[170:171]
	v_mul_f32_e32 v106, v111, v111
	v_mul_f32_e32 v107, v113, v113
	v_fmac_f32_e32 v106, v110, v110
	v_fmac_f32_e32 v107, v112, v112
	v_add_f32_e32 v106, v106, v107
	v_mul_f32_e32 v107, v109, v109
	v_fmac_f32_e32 v107, v108, v108
	v_ashrrev_i32_e32 v227, 31, v226
	v_add_f32_e32 v106, v106, v107
	v_mul_f32_e32 v107, v117, v117
	v_lshlrev_b64 v[114:115], 11, v[226:227]
	v_fmac_f32_e32 v107, v116, v116
	v_add_f32_e32 v118, v107, v106
	v_cvt_pk_bf16_f32 v106, v110, v111
	v_lshl_add_u64 v[110:111], s[80:81], 0, v[114:115]
	v_cvt_pk_bf16_f32 v107, v112, v113
	v_cvt_pk_bf16_f32 v108, v108, v109
	v_cvt_pk_bf16_f32 v109, v116, v117
	v_lshl_add_u64 v[110:111], v[214:215], 1, v[110:111]
	v_pk_add_f32 v[104:105], v[104:105], v[168:169]
	v_pk_add_f32 v[102:103], v[102:103], v[166:167]
	global_store_dwordx4 v[110:111], v[106:109], off sc1
	s_nop 1
	v_pk_add_f32 v[106:107], v[100:101], v[164:165]
	v_pk_add_f32 v[100:101], v[98:99], v[162:163]
	v_mul_f32_e32 v98, v103, v103
	v_mul_f32_e32 v99, v105, v105
	v_fmac_f32_e32 v98, v102, v102
	v_fmac_f32_e32 v99, v104, v104
	v_add_f32_e32 v98, v98, v99
	v_mul_f32_e32 v99, v101, v101
	v_fmac_f32_e32 v99, v100, v100
	v_add_f32_e32 v98, v98, v99
	v_mul_f32_e32 v99, v107, v107
	v_fmac_f32_e32 v99, v106, v106
	v_add_f32_e32 v98, v99, v98
	v_add_f32_e32 v108, v98, v118
	v_cvt_pk_bf16_f32 v98, v102, v103
	v_cvt_pk_bf16_f32 v99, v104, v105
	v_cvt_pk_bf16_f32 v100, v100, v101
	v_cvt_pk_bf16_f32 v101, v106, v107
	global_store_dwordx4 v[110:111], v[98:101], off offset:256 sc1
	s_nop 1
	v_mov_b32_e32 v98, v108
	s_nop 1
	v_permlane16_swap_b32_e32 v108, v98
	v_add_f32_e32 v98, v108, v98
	v_mov_b32_e32 v99, v98
	s_nop 1
	v_permlane32_swap_b32_e32 v98, v99
	s_and_saveexec_b64 s[26:27], s[2:3]
	s_cbranch_execz .LBB0_402
	v_lshlrev_b64 v[100:101], 6, v[226:227]
	v_lshl_add_u64 v[100:101], s[12:13], 0, v[100:101]
	v_lshl_add_u64 v[100:101], s[24:25], 2, v[100:101]
	s_lshl_b32 s78, s37, 2
	v_lshl_add_u64 v[100:101], v[100:101], 0, s[78:79]
	v_add_f32_e32 v98, v98, v99
	global_store_dword v[100:101], v98, off
.LBB0_402:
	s_or_b64 exec, exec, s[26:27]
	v_pk_add_f32 v[96:97], v[96:97], v[160:161]
	v_pk_add_f32 v[94:95], v[94:95], v[158:159]
	v_pk_add_f32 v[100:101], v[92:93], v[156:157]
	v_pk_add_f32 v[92:93], v[90:91], v[154:155]
	v_mul_f32_e32 v90, v95, v95
	v_mul_f32_e32 v91, v97, v97
	v_fmac_f32_e32 v90, v94, v94
	v_fmac_f32_e32 v91, v96, v96
	v_add_f32_e32 v90, v90, v91
	v_mul_f32_e32 v91, v93, v93
	v_fmac_f32_e32 v91, v92, v92
	v_ashrrev_i32_e32 v225, 31, v224
	v_add_f32_e32 v90, v90, v91
	v_mul_f32_e32 v91, v101, v101
	v_lshlrev_b64 v[98:99], 11, v[224:225]
	v_fmac_f32_e32 v91, v100, v100
	v_add_f32_e32 v102, v91, v90
	v_cvt_pk_bf16_f32 v90, v94, v95
	v_lshl_add_u64 v[94:95], s[80:81], 0, v[98:99]
	v_cvt_pk_bf16_f32 v91, v96, v97
	v_cvt_pk_bf16_f32 v92, v92, v93
	v_cvt_pk_bf16_f32 v93, v100, v101
	v_lshl_add_u64 v[94:95], v[214:215], 1, v[94:95]
	v_pk_add_f32 v[88:89], v[88:89], v[152:153]
	v_pk_add_f32 v[86:87], v[86:87], v[150:151]
	global_store_dwordx4 v[94:95], v[90:93], off sc1
	s_nop 1
	v_pk_add_f32 v[90:91], v[84:85], v[148:149]
	v_pk_add_f32 v[84:85], v[82:83], v[146:147]
	v_mul_f32_e32 v82, v87, v87
	v_mul_f32_e32 v83, v89, v89
	v_fmac_f32_e32 v82, v86, v86
	v_fmac_f32_e32 v83, v88, v88
	v_add_f32_e32 v82, v82, v83
	v_mul_f32_e32 v83, v85, v85
	v_fmac_f32_e32 v83, v84, v84
	v_add_f32_e32 v82, v82, v83
	v_mul_f32_e32 v83, v91, v91
	v_fmac_f32_e32 v83, v90, v90
	v_add_f32_e32 v82, v83, v82
	v_add_f32_e32 v92, v82, v102
	v_cvt_pk_bf16_f32 v82, v86, v87
	v_cvt_pk_bf16_f32 v83, v88, v89
	v_cvt_pk_bf16_f32 v84, v84, v85
	v_cvt_pk_bf16_f32 v85, v90, v91
	global_store_dwordx4 v[94:95], v[82:85], off offset:256 sc1
	s_nop 1
	v_mov_b32_e32 v82, v92
	s_nop 1
	v_permlane16_swap_b32_e32 v92, v82
	v_add_f32_e32 v82, v92, v82
	v_mov_b32_e32 v83, v82
	s_nop 1
	v_permlane32_swap_b32_e32 v82, v83
	s_and_saveexec_b64 s[26:27], s[2:3]
	s_cbranch_execz .LBB0_404
	v_lshlrev_b64 v[84:85], 6, v[224:225]
	v_lshl_add_u64 v[84:85], s[12:13], 0, v[84:85]
	v_lshl_add_u64 v[84:85], s[24:25], 2, v[84:85]
	s_lshl_b32 s78, s37, 2
	v_lshl_add_u64 v[84:85], v[84:85], 0, s[78:79]
	v_add_f32_e32 v82, v82, v83
	global_store_dword v[84:85], v82, off
.LBB0_404:
	s_or_b64 exec, exec, s[26:27]
	v_pk_add_f32 v[80:81], v[80:81], v[144:145]
	v_pk_add_f32 v[78:79], v[78:79], v[142:143]
	v_pk_add_f32 v[84:85], v[76:77], v[140:141]
	v_pk_add_f32 v[76:77], v[74:75], v[138:139]
	v_mul_f32_e32 v74, v79, v79
	v_mul_f32_e32 v75, v81, v81
	v_fmac_f32_e32 v74, v78, v78
	v_fmac_f32_e32 v75, v80, v80
	v_add_f32_e32 v74, v74, v75
	v_mul_f32_e32 v75, v77, v77
	v_fmac_f32_e32 v75, v76, v76
	v_ashrrev_i32_e32 v223, 31, v222
	v_add_f32_e32 v74, v74, v75
	v_mul_f32_e32 v75, v85, v85
	v_lshlrev_b64 v[82:83], 11, v[222:223]
	v_fmac_f32_e32 v75, v84, v84
	v_add_f32_e32 v86, v75, v74
	v_cvt_pk_bf16_f32 v74, v78, v79
	v_lshl_add_u64 v[78:79], s[80:81], 0, v[82:83]
	v_cvt_pk_bf16_f32 v75, v80, v81
	v_cvt_pk_bf16_f32 v76, v76, v77
	v_cvt_pk_bf16_f32 v77, v84, v85
	v_lshl_add_u64 v[78:79], v[214:215], 1, v[78:79]
	v_pk_add_f32 v[72:73], v[72:73], v[136:137]
	v_pk_add_f32 v[70:71], v[70:71], v[134:135]
	global_store_dwordx4 v[78:79], v[74:77], off sc1
	s_nop 1
	v_pk_add_f32 v[74:75], v[68:69], v[132:133]
	v_pk_add_f32 v[68:69], v[66:67], v[130:131]
	v_mul_f32_e32 v66, v71, v71
	v_mul_f32_e32 v67, v73, v73
	v_fmac_f32_e32 v66, v70, v70
	v_fmac_f32_e32 v67, v72, v72
	v_add_f32_e32 v66, v66, v67
	v_mul_f32_e32 v67, v69, v69
	v_fmac_f32_e32 v67, v68, v68
	v_add_f32_e32 v66, v66, v67
	v_mul_f32_e32 v67, v75, v75
	v_fmac_f32_e32 v67, v74, v74
	v_add_f32_e32 v66, v67, v66
	v_add_f32_e32 v76, v66, v86
	v_cvt_pk_bf16_f32 v66, v70, v71
	v_cvt_pk_bf16_f32 v67, v72, v73
	v_cvt_pk_bf16_f32 v68, v68, v69
	v_cvt_pk_bf16_f32 v69, v74, v75
	global_store_dwordx4 v[78:79], v[66:69], off offset:256 sc1
	s_nop 1
	v_mov_b32_e32 v66, v76
	s_nop 1
	v_permlane16_swap_b32_e32 v76, v66
	v_add_f32_e32 v66, v76, v66
	v_mov_b32_e32 v67, v66
	s_nop 1
	v_permlane32_swap_b32_e32 v66, v67
	s_and_saveexec_b64 s[26:27], s[2:3]
	s_cbranch_execz .LBB0_406
	v_lshlrev_b64 v[68:69], 6, v[222:223]
	v_lshl_add_u64 v[68:69], s[12:13], 0, v[68:69]
	v_lshl_add_u64 v[68:69], s[24:25], 2, v[68:69]
	s_lshl_b32 s78, s37, 2
	v_lshl_add_u64 v[68:69], v[68:69], 0, s[78:79]
	v_add_f32_e32 v66, v66, v67
	global_store_dword v[68:69], v66, off

.LBB0_409:
	s_waitcnt vmcnt(14)
	v_pk_add_f32 v[64:65], v[64:65], v[128:129]
	v_pk_add_f32 v[62:63], v[62:63], v[126:127]
	v_pk_add_f32 v[124:125], v[60:61], v[124:125]
	v_pk_add_f32 v[60:61], v[58:59], v[122:123]
	v_mul_f32_e32 v58, v63, v63
	v_mul_f32_e32 v59, v65, v65
	v_fmac_f32_e32 v58, v62, v62
	v_fmac_f32_e32 v59, v64, v64
	v_add_f32_e32 v58, v58, v59
	v_mul_f32_e32 v59, v61, v61
	v_fmac_f32_e32 v59, v60, v60
	v_add_f32_e32 v58, v58, v59
	v_mul_f32_e32 v59, v125, v125
	v_fmac_f32_e32 v59, v124, v124
	v_add_f32_e32 v122, v59, v58
	v_cvt_pk_bf16_f32 v58, v62, v63
	v_lshl_add_u64 v[62:63], s[80:81], 0, v[140:141]
	v_cvt_pk_bf16_f32 v59, v64, v65
	v_cvt_pk_bf16_f32 v60, v60, v61
	v_cvt_pk_bf16_f32 v61, v124, v125
	v_lshl_add_u64 v[62:63], v[214:215], 1, v[62:63]
	s_waitcnt vmcnt(12)
	v_pk_add_f32 v[56:57], v[56:57], v[120:121]
	v_pk_add_f32 v[54:55], v[54:55], v[118:119]
	global_store_dwordx4 v[62:63], v[58:61], off sc1
	s_nop 1
	v_pk_add_f32 v[58:59], v[52:53], v[116:117]
	v_pk_add_f32 v[52:53], v[50:51], v[114:115]
	v_mul_f32_e32 v50, v55, v55
	v_mul_f32_e32 v51, v57, v57
	v_fmac_f32_e32 v50, v54, v54
	v_fmac_f32_e32 v51, v56, v56
	v_add_f32_e32 v50, v50, v51
	v_mul_f32_e32 v51, v53, v53
	v_fmac_f32_e32 v51, v52, v52
	v_add_f32_e32 v50, v50, v51
	v_mul_f32_e32 v51, v59, v59
	v_fmac_f32_e32 v51, v58, v58
	v_add_f32_e32 v50, v51, v50
	v_add_f32_e32 v60, v50, v122
	v_cvt_pk_bf16_f32 v50, v54, v55
	v_cvt_pk_bf16_f32 v51, v56, v57
	v_cvt_pk_bf16_f32 v52, v52, v53
	v_cvt_pk_bf16_f32 v53, v58, v59
	global_store_dwordx4 v[62:63], v[50:53], off offset:256 sc1
	s_nop 1
	v_mov_b32_e32 v50, v60
	s_nop 1
	v_permlane16_swap_b32_e32 v60, v50
	v_add_f32_e32 v50, v60, v50
	v_mov_b32_e32 v51, v50
	s_nop 1
	v_permlane32_swap_b32_e32 v50, v51
	s_and_saveexec_b64 s[6:7], s[2:3]
	s_cbranch_execz .LBB0_411
	v_lshlrev_b64 v[52:53], 6, v[136:137]
	v_lshl_add_u64 v[52:53], s[12:13], 0, v[52:53]
	v_lshl_add_u64 v[52:53], s[24:25], 2, v[52:53]
	s_lshl_b32 s78, s37, 2
	v_lshl_add_u64 v[52:53], v[52:53], 0, s[78:79]
	v_add_f32_e32 v50, v50, v51
	global_store_dword v[52:53], v50, off
.LBB0_411:
	s_or_b64 exec, exec, s[6:7]
	s_waitcnt vmcnt(12)
	v_pk_add_f32 v[48:49], v[48:49], v[112:113]
	v_pk_add_f32 v[46:47], v[46:47], v[110:111]
	v_pk_add_f32 v[52:53], v[44:45], v[108:109]
	v_pk_add_f32 v[44:45], v[42:43], v[106:107]
	v_mul_f32_e32 v42, v47, v47
	v_mul_f32_e32 v43, v49, v49
	v_fmac_f32_e32 v42, v46, v46
	v_fmac_f32_e32 v43, v48, v48
	v_add_f32_e32 v42, v42, v43
	v_mul_f32_e32 v43, v45, v45
	v_fmac_f32_e32 v43, v44, v44
	v_ashrrev_i32_e32 v135, 31, v134
	v_add_f32_e32 v42, v42, v43
	v_mul_f32_e32 v43, v53, v53
	v_lshlrev_b64 v[50:51], 11, v[134:135]
	v_fmac_f32_e32 v43, v52, v52
	v_add_f32_e32 v54, v43, v42
	v_cvt_pk_bf16_f32 v42, v46, v47
	v_lshl_add_u64 v[46:47], s[80:81], 0, v[50:51]
	v_cvt_pk_bf16_f32 v43, v48, v49
	v_cvt_pk_bf16_f32 v44, v44, v45
	v_cvt_pk_bf16_f32 v45, v52, v53
	v_lshl_add_u64 v[46:47], v[214:215], 1, v[46:47]
	s_waitcnt vmcnt(10)
	v_pk_add_f32 v[40:41], v[40:41], v[104:105]
	v_pk_add_f32 v[38:39], v[38:39], v[102:103]
	global_store_dwordx4 v[46:47], v[42:45], off sc1
	s_nop 1
	v_pk_add_f32 v[42:43], v[36:37], v[100:101]
	v_pk_add_f32 v[36:37], v[34:35], v[98:99]
	v_mul_f32_e32 v34, v39, v39
	v_mul_f32_e32 v35, v41, v41
	v_fmac_f32_e32 v34, v38, v38
	v_fmac_f32_e32 v35, v40, v40
	v_add_f32_e32 v34, v34, v35
	v_mul_f32_e32 v35, v37, v37
	v_fmac_f32_e32 v35, v36, v36
	v_add_f32_e32 v34, v34, v35
	v_mul_f32_e32 v35, v43, v43
	v_fmac_f32_e32 v35, v42, v42
	v_add_f32_e32 v34, v35, v34
	v_add_f32_e32 v44, v34, v54
	v_cvt_pk_bf16_f32 v34, v38, v39
	v_cvt_pk_bf16_f32 v35, v40, v41
	v_cvt_pk_bf16_f32 v36, v36, v37
	v_cvt_pk_bf16_f32 v37, v42, v43
	global_store_dwordx4 v[46:47], v[34:37], off offset:256 sc1
	s_nop 1
	v_mov_b32_e32 v34, v44
	s_nop 1
	v_permlane16_swap_b32_e32 v44, v34
	v_add_f32_e32 v34, v44, v34
	v_mov_b32_e32 v35, v34
	s_nop 1
	v_permlane32_swap_b32_e32 v34, v35
	s_and_saveexec_b64 s[6:7], s[2:3]
	s_cbranch_execz .LBB0_413
	v_lshlrev_b64 v[36:37], 6, v[134:135]
	v_lshl_add_u64 v[36:37], s[12:13], 0, v[36:37]
	v_lshl_add_u64 v[36:37], s[24:25], 2, v[36:37]
	s_lshl_b32 s78, s37, 2
	v_lshl_add_u64 v[36:37], v[36:37], 0, s[78:79]
	v_add_f32_e32 v34, v34, v35
	global_store_dword v[36:37], v34, off
.LBB0_413:
	s_or_b64 exec, exec, s[6:7]
	s_waitcnt vmcnt(10)
	v_pk_add_f32 v[32:33], v[32:33], v[96:97]
	v_pk_add_f32 v[30:31], v[30:31], v[94:95]
	v_pk_add_f32 v[36:37], v[28:29], v[92:93]
	v_pk_add_f32 v[28:29], v[26:27], v[90:91]
	v_mul_f32_e32 v26, v31, v31
	v_mul_f32_e32 v27, v33, v33
	v_fmac_f32_e32 v26, v30, v30
	v_fmac_f32_e32 v27, v32, v32
	v_add_f32_e32 v26, v26, v27
	v_mul_f32_e32 v27, v29, v29
	v_fmac_f32_e32 v27, v28, v28
	v_ashrrev_i32_e32 v133, 31, v132
	v_add_f32_e32 v26, v26, v27
	v_mul_f32_e32 v27, v37, v37
	v_lshlrev_b64 v[34:35], 11, v[132:133]
	v_fmac_f32_e32 v27, v36, v36
	v_add_f32_e32 v38, v27, v26
	v_cvt_pk_bf16_f32 v26, v30, v31
	v_lshl_add_u64 v[30:31], s[80:81], 0, v[34:35]
	v_cvt_pk_bf16_f32 v27, v32, v33
	v_cvt_pk_bf16_f32 v28, v28, v29
	v_cvt_pk_bf16_f32 v29, v36, v37
	v_lshl_add_u64 v[30:31], v[214:215], 1, v[30:31]
	s_waitcnt vmcnt(8)
	v_pk_add_f32 v[24:25], v[24:25], v[88:89]
	v_pk_add_f32 v[22:23], v[22:23], v[86:87]
	global_store_dwordx4 v[30:31], v[26:29], off sc1
	s_nop 1
	v_pk_add_f32 v[26:27], v[20:21], v[84:85]
	v_pk_add_f32 v[20:21], v[18:19], v[82:83]
	v_mul_f32_e32 v18, v23, v23
	v_mul_f32_e32 v19, v25, v25
	v_fmac_f32_e32 v18, v22, v22
	v_fmac_f32_e32 v19, v24, v24
	v_add_f32_e32 v18, v18, v19
	v_mul_f32_e32 v19, v21, v21
	v_fmac_f32_e32 v19, v20, v20
	v_add_f32_e32 v18, v18, v19
	v_mul_f32_e32 v19, v27, v27
	v_fmac_f32_e32 v19, v26, v26
	v_add_f32_e32 v18, v19, v18
	v_add_f32_e32 v28, v18, v38
	v_cvt_pk_bf16_f32 v18, v22, v23
	v_cvt_pk_bf16_f32 v19, v24, v25
	v_cvt_pk_bf16_f32 v20, v20, v21
	v_cvt_pk_bf16_f32 v21, v26, v27
	global_store_dwordx4 v[30:31], v[18:21], off offset:256 sc1
	s_nop 1
	v_mov_b32_e32 v18, v28
	s_nop 1
	v_permlane16_swap_b32_e32 v28, v18
	v_add_f32_e32 v18, v28, v18
	v_mov_b32_e32 v19, v18
	s_nop 1
	v_permlane32_swap_b32_e32 v18, v19
	s_and_saveexec_b64 s[6:7], s[2:3]
	s_cbranch_execz .LBB0_415
	v_lshlrev_b64 v[20:21], 6, v[132:133]
	v_lshl_add_u64 v[20:21], s[12:13], 0, v[20:21]
	v_lshl_add_u64 v[20:21], s[24:25], 2, v[20:21]
	s_lshl_b32 s78, s37, 2
	v_lshl_add_u64 v[20:21], v[20:21], 0, s[78:79]
	v_add_f32_e32 v18, v18, v19
	global_store_dword v[20:21], v18, off
.LBB0_415:
	s_or_b64 exec, exec, s[6:7]
	s_waitcnt vmcnt(8)
	v_pk_add_f32 v[16:17], v[16:17], v[80:81]
	v_pk_add_f32 v[14:15], v[14:15], v[78:79]
	v_pk_add_f32 v[20:21], v[12:13], v[76:77]
	v_pk_add_f32 v[12:13], v[10:11], v[74:75]
	v_mul_f32_e32 v10, v15, v15
	v_mul_f32_e32 v11, v17, v17
	v_fmac_f32_e32 v10, v14, v14
	v_fmac_f32_e32 v11, v16, v16
	v_add_f32_e32 v10, v10, v11
	v_mul_f32_e32 v11, v13, v13
	v_fmac_f32_e32 v11, v12, v12
	v_ashrrev_i32_e32 v131, 31, v130
	v_add_f32_e32 v10, v10, v11
	v_mul_f32_e32 v11, v21, v21
	v_lshlrev_b64 v[18:19], 11, v[130:131]
	v_fmac_f32_e32 v11, v20, v20
	v_add_f32_e32 v22, v11, v10
	v_cvt_pk_bf16_f32 v10, v14, v15
	v_lshl_add_u64 v[14:15], s[80:81], 0, v[18:19]
	v_cvt_pk_bf16_f32 v11, v16, v17
	v_cvt_pk_bf16_f32 v12, v12, v13
	v_cvt_pk_bf16_f32 v13, v20, v21
	v_lshl_add_u64 v[14:15], v[214:215], 1, v[14:15]
	s_waitcnt vmcnt(6)
	v_pk_add_f32 v[8:9], v[8:9], v[72:73]
	v_pk_add_f32 v[6:7], v[6:7], v[70:71]
	global_store_dwordx4 v[14:15], v[10:13], off sc1
	s_nop 1
	v_pk_add_f32 v[10:11], v[4:5], v[68:69]
	v_pk_add_f32 v[4:5], v[2:3], v[66:67]
	v_mul_f32_e32 v2, v7, v7
	v_mul_f32_e32 v3, v9, v9
	v_fmac_f32_e32 v2, v6, v6
	v_fmac_f32_e32 v3, v8, v8
	v_add_f32_e32 v2, v2, v3
	v_mul_f32_e32 v3, v5, v5
	v_fmac_f32_e32 v3, v4, v4
	v_add_f32_e32 v2, v2, v3
	v_mul_f32_e32 v3, v11, v11
	v_fmac_f32_e32 v3, v10, v10
	v_add_f32_e32 v2, v3, v2
	v_add_f32_e32 v12, v2, v22
	v_cvt_pk_bf16_f32 v2, v6, v7
	v_cvt_pk_bf16_f32 v3, v8, v9
	v_cvt_pk_bf16_f32 v4, v4, v5
	v_cvt_pk_bf16_f32 v5, v10, v11
	global_store_dwordx4 v[14:15], v[2:5], off offset:256 sc1
	s_nop 1
	v_mov_b32_e32 v2, v12
	s_nop 1
	v_permlane16_swap_b32_e32 v12, v2
	v_add_f32_e32 v2, v12, v2
	v_mov_b32_e32 v3, v2
	s_nop 1
	v_permlane32_swap_b32_e32 v2, v3
	s_and_saveexec_b64 s[6:7], s[2:3]
	s_cbranch_execz .LBB0_417
	v_lshlrev_b64 v[4:5], 6, v[130:131]
	v_lshl_add_u64 v[4:5], s[12:13], 0, v[4:5]
	v_lshl_add_u64 v[4:5], s[24:25], 2, v[4:5]
	s_lshl_b32 s78, s37, 2
	v_lshl_add_u64 v[4:5], v[4:5], 0, s[78:79]
	v_add_f32_e32 v2, v2, v3
	global_store_dword v[4:5], v2, off

.LBB0_525:
	v_and_b32_e32 v154, 15, v204
	v_and_b32_e32 v194, 3, v154
	v_and_b32_e32 v195, 4, v154
	v_lshl_or_b32 v194, v195, 1, v194
	v_and_b32_e32 v195, 8, v154
	v_lshrrev_b32_e32 v195, 1, v195
	v_or_b32_e32 v194, v194, v195
	s_cmp_lt_i32 s33, 4
	s_cselect_b64 vcc, -1, 0
	v_cndmask_b32_e32 v154, v194, v154, vcc
	v_lshlrev_b32_e32 v154, 4, v154
	v_and_b32_e32 v194, 31, v206
	v_lshl_add_u32 v154, v194, 6, v154
	v_lshrrev_b32_e32 v154, 1, v154
	v_mov_b64_e32 v[194:195], 0
	s_waitcnt lgkmcnt(3)
	s_waitcnt lgkmcnt(2)
	v_ashrrev_i32_e32 v155, 31, v154
	v_cvt_pk_bf16_f32 v158, v158, v159
	v_cvt_pk_bf16_f32 v159, v160, v161
	v_cvt_pk_bf16_f32 v160, v156, v157
	v_lshl_add_u64 v[156:157], s[98:99], 0, v[194:195]
	v_cvt_pk_bf16_f32 v161, v182, v183
	v_lshl_add_u64 v[156:157], v[154:155], 1, v[156:157]
	v_pk_mul_f32 v[152:153], v[152:153], v[180:181]
	s_and_b64 vcc, exec, s[6:7]
	v_pk_mul_f32 v[150:151], v[150:151], v[178:179]
	global_store_dwordx4 v[156:157], v[158:161], off sc1
	s_cbranch_vccnz .LBB0_529
	s_nop 0
	v_and_b32_e32 v159, 64, v238
	v_xor_b32_e32 v158, 16, v238
	v_add_u32_e32 v159, 64, v159
	v_cmp_lt_i32_e32 vcc, v158, v159
	s_nop 1
	v_cndmask_b32_e32 v158, v238, v158, vcc
	v_lshlrev_b32_e32 v160, 2, v158
	ds_bpermute_b32 v158, v160, v150
	ds_bpermute_b32 v159, v160, v151
	ds_bpermute_b32 v161, v160, v152
	ds_bpermute_b32 v160, v160, v153
	s_and_saveexec_b64 s[24:25], s[2:3]
	s_cbranch_execz .LBB0_528
	s_waitcnt lgkmcnt(2)
	v_pk_mul_f32 v[158:159], v[170:171], v[158:159]
	v_mov_b32_e32 v182, v83
	v_mov_b32_e32 v183, v85
	v_mov_b32_e32 v180, v82
	v_mov_b32_e32 v181, v84
	v_pk_mul_f32 v[158:159], v[182:183], v[158:159]
	v_mul_f32_e32 v152, v152, v78
	v_pk_fma_f32 v[150:151], v[150:151], v[180:181], v[158:159]
	s_waitcnt lgkmcnt(1)
	v_mul_f32_e32 v158, v170, v161
	s_waitcnt lgkmcnt(0)
	v_mul_f32_e32 v161, v170, v160
	v_mov_b32_e32 v180, v153
	v_mov_b32_e32 v181, v81
	v_mov_b32_e32 v160, v80
	v_pk_mul_f32 v[160:161], v[180:181], v[160:161]
	v_mul_f32_e32 v158, v79, v158
	v_mov_b32_e32 v153, v160
	v_mov_b32_e32 v159, v161
	v_pk_add_f32 v[152:153], v[152:153], v[158:159]

.LBB0_533:
	s_waitcnt lgkmcnt(3)
	v_mul_f32_e32 v146, v209, v215
	v_cvt_pk_bf16_f32 v150, v150, v151
	v_cvt_pk_bf16_f32 v151, v152, v153
	v_cvt_pk_bf16_f32 v152, v148, v149
	v_cvt_pk_bf16_f32 v153, v158, v159
	s_waitcnt lgkmcnt(2)
	v_pk_mul_f32 v[144:145], v[144:145], v[146:147] op_sel_hi:[1,0]
	s_and_b64 vcc, exec, s[6:7]
	v_pk_mul_f32 v[142:143], v[142:143], v[146:147] op_sel_hi:[1,0]
	v_lshl_add_u64 v[156:157], v[156:157], 0, s[100:101]
	global_store_dwordx4 v[156:157], v[150:153], off sc1
	s_cbranch_vccnz .LBB0_537
	v_and_b32_e32 v148, 64, v238
	v_xor_b32_e32 v147, 16, v238
	v_add_u32_e32 v148, 64, v148
	v_cmp_lt_i32_e32 vcc, v147, v148
	s_nop 1
	v_cndmask_b32_e32 v147, v238, v147, vcc
	v_lshlrev_b32_e32 v147, 2, v147
	ds_bpermute_b32 v148, v147, v142
	ds_bpermute_b32 v149, v147, v143
	ds_bpermute_b32 v150, v147, v144
	ds_bpermute_b32 v147, v147, v145
	s_and_saveexec_b64 s[24:25], s[2:3]
	s_cbranch_execz .LBB0_536
	s_waitcnt lgkmcnt(2)
	v_pk_mul_f32 v[148:149], v[170:171], v[148:149]
	v_mov_b32_e32 v156, v55
	v_mov_b32_e32 v157, v57
	v_mov_b32_e32 v152, v54
	v_mov_b32_e32 v153, v56
	v_pk_mul_f32 v[148:149], v[156:157], v[148:149]
	s_waitcnt lgkmcnt(0)
	v_mul_f32_e32 v151, v170, v147
	v_pk_fma_f32 v[142:143], v[142:143], v[152:153], v[148:149]
	v_mul_f32_e32 v148, v170, v150
	v_mov_b32_e32 v152, v145
	v_mov_b32_e32 v153, v53
	v_mov_b32_e32 v150, v52
	v_pk_mul_f32 v[150:151], v[152:153], v[150:151]
	v_mul_f32_e32 v144, v144, v50
	v_mul_f32_e32 v148, v51, v148
	v_mov_b32_e32 v145, v150
	v_mov_b32_e32 v149, v151
	v_pk_add_f32 v[144:145], v[144:145], v[148:149]

.LBB0_541:
	s_waitcnt lgkmcnt(3)
	v_or_b32_e32 v150, 16, v204
	v_add_u32_e32 v150, s26, v150
	s_waitcnt lgkmcnt(2)
	v_ashrrev_i32_e32 v151, 31, v150
	v_mov_b64_e32 v[150:151], 0x100
	v_cvt_pk_bf16_f32 v142, v142, v143
	v_cvt_pk_bf16_f32 v143, v144, v145
	v_cvt_pk_bf16_f32 v144, v138, v139
	v_lshl_add_u64 v[138:139], s[98:99], 0, v[150:151]
	v_cvt_pk_bf16_f32 v145, v140, v141
	v_lshl_add_u64 v[138:139], v[154:155], 1, v[138:139]
	v_pk_mul_f32 v[136:137], v[136:137], v[148:149]
	s_and_b64 vcc, exec, s[6:7]
	v_pk_mul_f32 v[134:135], v[134:135], v[146:147]
	global_store_dwordx4 v[138:139], v[142:145], off sc1
	s_cbranch_vccnz .LBB0_545
	v_and_b32_e32 v141, 64, v238
	v_xor_b32_e32 v140, 16, v238
	v_add_u32_e32 v141, 64, v141
	v_cmp_lt_i32_e32 vcc, v140, v141
	s_nop 1
	v_cndmask_b32_e32 v140, v238, v140, vcc
	v_lshlrev_b32_e32 v142, 2, v140
	ds_bpermute_b32 v140, v142, v134
	ds_bpermute_b32 v141, v142, v135
	ds_bpermute_b32 v143, v142, v136
	ds_bpermute_b32 v142, v142, v137
	s_and_saveexec_b64 s[24:25], s[2:3]
	s_cbranch_execz .LBB0_544
	s_waitcnt lgkmcnt(2)
	v_pk_mul_f32 v[140:141], v[170:171], v[140:141]
	v_mov_b32_e32 v148, v55
	v_mov_b32_e32 v149, v57
	v_mov_b32_e32 v144, v54
	v_mov_b32_e32 v145, v56
	v_pk_mul_f32 v[140:141], v[148:149], v[140:141]
	v_mul_f32_e32 v136, v136, v50
	v_pk_fma_f32 v[134:135], v[134:135], v[144:145], v[140:141]
	s_waitcnt lgkmcnt(1)
	v_mul_f32_e32 v140, v170, v143
	s_waitcnt lgkmcnt(0)
	v_mul_f32_e32 v143, v170, v142
	v_mov_b32_e32 v144, v137
	v_mov_b32_e32 v145, v53
	v_mov_b32_e32 v142, v52
	v_pk_mul_f32 v[142:143], v[144:145], v[142:143]
	v_mul_f32_e32 v140, v51, v140
	v_mov_b32_e32 v137, v142
	v_mov_b32_e32 v141, v143
	v_pk_add_f32 v[136:137], v[136:137], v[140:141]

.LBB0_549:
	v_cvt_pk_bf16_f32 v134, v134, v135
	v_cvt_pk_bf16_f32 v135, v136, v137
	v_cvt_pk_bf16_f32 v136, v130, v131
	v_cvt_pk_bf16_f32 v137, v132, v133
	s_and_b64 vcc, exec, s[6:7]
	v_lshl_add_u64 v[138:139], v[138:139], 0, s[100:101]
	global_store_dwordx4 v[138:139], v[134:137], off sc1
	s_cbranch_vccnz .LBB0_551
	s_add_i32 s24, s26, s43
	s_and_b32 s24, s24, 0xfc0
	v_or_b32_e32 v38, s24, v188
	v_or_b32_e32 v39, 32, v38
	v_lshlrev_b32_e32 v40, s30, v39
	v_and_b32_e32 v40, 0xfff, v40
	v_lshrrev_b32_e32 v39, s37, v39
	v_add_lshl_u32 v39, v40, v39, 6
	v_or_b32_e32 v38, 48, v38
	global_load_dwordx4 v[66:69], v39, s[0:1] offset:48
	global_load_dwordx4 v[70:73], v39, s[0:1] offset:32
	global_load_dwordx4 v[78:81], v39, s[0:1] offset:16
	global_load_dwordx4 v[82:85], v39, s[0:1]
	v_lshlrev_b32_e32 v39, s30, v38
	v_and_b32_e32 v39, 0xfff, v39
	v_lshrrev_b32_e32 v38, s37, v38
	v_add_lshl_u32 v54, v39, v38, 6
	global_load_dwordx4 v[38:41], v54, s[0:1] offset:48
	global_load_dwordx4 v[42:45], v54, s[0:1] offset:32
	global_load_dwordx4 v[50:53], v54, s[0:1] offset:16
	s_nop 0
	global_load_dwordx4 v[54:57], v54, s[0:1]
	s_waitcnt vmcnt(0)

.LBB0_559:
	s_waitcnt lgkmcnt(3)
	v_or_b32_e32 v134, 32, v204
	v_add_u32_e32 v134, s26, v134
	s_waitcnt lgkmcnt(2)
	v_ashrrev_i32_e32 v135, 31, v134
	v_mov_b64_e32 v[134:135], 0x1000
	v_cvt_pk_bf16_f32 v126, v126, v127
	v_cvt_pk_bf16_f32 v127, v128, v129
	v_cvt_pk_bf16_f32 v128, v122, v123
	v_lshl_add_u64 v[122:123], s[98:99], 0, v[134:135]
	v_cvt_pk_bf16_f32 v129, v124, v125
	v_lshl_add_u64 v[122:123], v[154:155], 1, v[122:123]
	v_pk_mul_f32 v[120:121], v[120:121], v[132:133]
	s_and_b64 vcc, exec, s[6:7]
	v_pk_mul_f32 v[118:119], v[118:119], v[130:131]
	global_store_dwordx4 v[122:123], v[126:129], off sc1
	s_cbranch_vccnz .LBB0_563
	v_and_b32_e32 v125, 64, v238
	v_xor_b32_e32 v124, 16, v238
	v_add_u32_e32 v125, 64, v125
	v_cmp_lt_i32_e32 vcc, v124, v125
	s_nop 1
	v_cndmask_b32_e32 v124, v238, v124, vcc
	v_lshlrev_b32_e32 v126, 2, v124
	ds_bpermute_b32 v124, v126, v118
	ds_bpermute_b32 v125, v126, v119
	ds_bpermute_b32 v127, v126, v120
	ds_bpermute_b32 v126, v126, v121
	s_and_saveexec_b64 s[24:25], s[2:3]
	s_cbranch_execz .LBB0_562
	s_waitcnt lgkmcnt(2)
	v_pk_mul_f32 v[124:125], v[170:171], v[124:125]
	v_mov_b32_e32 v132, v83
	v_mov_b32_e32 v133, v85
	v_mov_b32_e32 v128, v82
	v_mov_b32_e32 v129, v84
	v_pk_mul_f32 v[124:125], v[132:133], v[124:125]
	v_mul_f32_e32 v120, v120, v78
	v_pk_fma_f32 v[118:119], v[118:119], v[128:129], v[124:125]
	s_waitcnt lgkmcnt(1)
	v_mul_f32_e32 v124, v170, v127
	s_waitcnt lgkmcnt(0)
	v_mul_f32_e32 v127, v170, v126
	v_mov_b32_e32 v128, v121
	v_mov_b32_e32 v129, v81
	v_mov_b32_e32 v126, v80
	v_pk_mul_f32 v[126:127], v[128:129], v[126:127]
	v_mul_f32_e32 v124, v79, v124
	v_mov_b32_e32 v121, v126
	v_mov_b32_e32 v125, v127
	v_pk_add_f32 v[120:121], v[120:121], v[124:125]

.LBB0_567:
	s_waitcnt lgkmcnt(3)
	v_mul_f32_e32 v114, v209, v213
	v_cvt_pk_bf16_f32 v118, v118, v119
	v_cvt_pk_bf16_f32 v119, v120, v121
	v_cvt_pk_bf16_f32 v120, v116, v117
	v_cvt_pk_bf16_f32 v121, v124, v125
	s_waitcnt lgkmcnt(2)
	v_pk_mul_f32 v[112:113], v[112:113], v[114:115] op_sel_hi:[1,0]
	s_and_b64 vcc, exec, s[6:7]
	v_pk_mul_f32 v[110:111], v[110:111], v[114:115] op_sel_hi:[1,0]
	v_lshl_add_u64 v[122:123], v[122:123], 0, s[100:101]
	global_store_dwordx4 v[122:123], v[118:121], off sc1
	s_cbranch_vccnz .LBB0_571
	v_and_b32_e32 v116, 64, v238
	v_xor_b32_e32 v115, 16, v238
	v_add_u32_e32 v116, 64, v116
	v_cmp_lt_i32_e32 vcc, v115, v116
	s_nop 1
	v_cndmask_b32_e32 v115, v238, v115, vcc
	v_lshlrev_b32_e32 v115, 2, v115
	ds_bpermute_b32 v116, v115, v110
	ds_bpermute_b32 v117, v115, v111
	ds_bpermute_b32 v118, v115, v112
	ds_bpermute_b32 v115, v115, v113
	s_and_saveexec_b64 s[24:25], s[2:3]
	s_cbranch_execz .LBB0_570
	s_waitcnt lgkmcnt(2)
	v_pk_mul_f32 v[116:117], v[170:171], v[116:117]
	v_mov_b32_e32 v122, v55
	v_mov_b32_e32 v123, v57
	v_mov_b32_e32 v120, v54
	v_mov_b32_e32 v121, v56
	v_pk_mul_f32 v[116:117], v[122:123], v[116:117]
	s_waitcnt lgkmcnt(0)
	v_mul_f32_e32 v119, v170, v115
	v_pk_fma_f32 v[110:111], v[110:111], v[120:121], v[116:117]
	v_mul_f32_e32 v116, v170, v118
	v_mov_b32_e32 v120, v113
	v_mov_b32_e32 v121, v53
	v_mov_b32_e32 v118, v52
	v_pk_mul_f32 v[118:119], v[120:121], v[118:119]
	v_mul_f32_e32 v112, v112, v50
	v_mul_f32_e32 v116, v51, v116
	v_mov_b32_e32 v113, v118
	v_mov_b32_e32 v117, v119
	v_pk_add_f32 v[112:113], v[112:113], v[116:117]

.LBB0_575:
	s_waitcnt lgkmcnt(3)
	v_or_b32_e32 v118, 48, v204
	v_add_u32_e32 v118, s26, v118
	s_waitcnt lgkmcnt(2)
	v_ashrrev_i32_e32 v119, 31, v118
	v_mov_b64_e32 v[118:119], 0x1100
	v_cvt_pk_bf16_f32 v110, v110, v111
	v_cvt_pk_bf16_f32 v111, v112, v113
	v_cvt_pk_bf16_f32 v112, v106, v107
	v_lshl_add_u64 v[106:107], s[98:99], 0, v[118:119]
	v_cvt_pk_bf16_f32 v113, v108, v109
	v_lshl_add_u64 v[106:107], v[154:155], 1, v[106:107]
	v_pk_mul_f32 v[104:105], v[104:105], v[116:117]
	s_and_b64 vcc, exec, s[6:7]
	v_pk_mul_f32 v[102:103], v[102:103], v[114:115]
	global_store_dwordx4 v[106:107], v[110:113], off sc1
	s_cbranch_vccnz .LBB0_579
	v_and_b32_e32 v109, 64, v238
	v_xor_b32_e32 v108, 16, v238
	v_add_u32_e32 v109, 64, v109
	v_cmp_lt_i32_e32 vcc, v108, v109
	s_nop 1
	v_cndmask_b32_e32 v108, v238, v108, vcc
	v_lshlrev_b32_e32 v110, 2, v108
	ds_bpermute_b32 v108, v110, v102
	ds_bpermute_b32 v109, v110, v103
	ds_bpermute_b32 v111, v110, v104
	ds_bpermute_b32 v110, v110, v105
	s_and_saveexec_b64 s[24:25], s[2:3]
	s_cbranch_execz .LBB0_578
	s_waitcnt lgkmcnt(2)
	v_pk_mul_f32 v[108:109], v[170:171], v[108:109]
	v_mov_b32_e32 v116, v55
	v_mov_b32_e32 v117, v57
	v_mov_b32_e32 v112, v54
	v_mov_b32_e32 v113, v56
	v_pk_mul_f32 v[108:109], v[116:117], v[108:109]
	v_mul_f32_e32 v104, v104, v50
	v_pk_fma_f32 v[102:103], v[102:103], v[112:113], v[108:109]
	s_waitcnt lgkmcnt(1)
	v_mul_f32_e32 v108, v170, v111
	s_waitcnt lgkmcnt(0)
	v_mul_f32_e32 v111, v170, v110
	v_mov_b32_e32 v112, v105
	v_mov_b32_e32 v113, v53
	v_mov_b32_e32 v110, v52
	v_pk_mul_f32 v[110:111], v[112:113], v[110:111]
	v_mul_f32_e32 v108, v51, v108
	v_mov_b32_e32 v105, v110
	v_mov_b32_e32 v109, v111
	v_pk_add_f32 v[104:105], v[104:105], v[108:109]

.LBB0_583:
	v_cvt_pk_bf16_f32 v102, v102, v103
	v_cvt_pk_bf16_f32 v103, v104, v105
	v_cvt_pk_bf16_f32 v104, v98, v99
	v_cvt_pk_bf16_f32 v105, v100, v101
	s_and_b64 vcc, exec, s[6:7]
	v_lshl_add_u64 v[106:107], v[106:107], 0, s[100:101]
	global_store_dwordx4 v[106:107], v[102:105], off sc1
	s_cbranch_vccnz .LBB0_585
	s_add_i32 s24, s26, s47
	s_and_b32 s24, s24, 0xfc0
	v_or_b32_e32 v38, s24, v188
	v_lshlrev_b32_e32 v39, s30, v38
	v_and_b32_e32 v39, 0xfff, v39
	v_lshrrev_b32_e32 v40, s37, v38
	v_add_lshl_u32 v39, v39, v40, 6
	v_or_b32_e32 v38, 16, v38
	global_load_dwordx4 v[66:69], v39, s[0:1] offset:48
	global_load_dwordx4 v[70:73], v39, s[0:1] offset:32
	global_load_dwordx4 v[78:81], v39, s[0:1] offset:16
	global_load_dwordx4 v[82:85], v39, s[0:1]
	v_lshlrev_b32_e32 v39, s30, v38
	v_and_b32_e32 v39, 0xfff, v39
	v_lshrrev_b32_e32 v38, s37, v38
	v_add_lshl_u32 v54, v39, v38, 6
	global_load_dwordx4 v[38:41], v54, s[0:1] offset:48
	global_load_dwordx4 v[42:45], v54, s[0:1] offset:32
	global_load_dwordx4 v[50:53], v54, s[0:1] offset:16
	s_nop 0
	global_load_dwordx4 v[54:57], v54, s[0:1]
	s_waitcnt vmcnt(0)

.LBB0_593:
	s_waitcnt lgkmcnt(3)
	v_add_u32_e32 v102, 0x80, v176
	s_waitcnt lgkmcnt(2)
	v_ashrrev_i32_e32 v103, 31, v102
	v_mov_b64_e32 v[102:103], 0x4000
	v_cvt_pk_bf16_f32 v94, v94, v95
	v_cvt_pk_bf16_f32 v95, v96, v97
	v_cvt_pk_bf16_f32 v96, v90, v91
	v_lshl_add_u64 v[90:91], s[98:99], 0, v[102:103]
	v_cvt_pk_bf16_f32 v97, v92, v93
	v_lshl_add_u64 v[90:91], v[154:155], 1, v[90:91]
	v_pk_mul_f32 v[88:89], v[88:89], v[100:101]
	s_and_b64 vcc, exec, s[6:7]
	v_pk_mul_f32 v[86:87], v[86:87], v[98:99]
	global_store_dwordx4 v[90:91], v[94:97], off sc1
	s_cbranch_vccnz .LBB0_597
	v_and_b32_e32 v93, 64, v238
	v_xor_b32_e32 v92, 16, v238
	v_add_u32_e32 v93, 64, v93
	v_cmp_lt_i32_e32 vcc, v92, v93
	s_nop 1
	v_cndmask_b32_e32 v92, v238, v92, vcc
	v_lshlrev_b32_e32 v94, 2, v92
	ds_bpermute_b32 v92, v94, v86
	ds_bpermute_b32 v93, v94, v87
	ds_bpermute_b32 v95, v94, v88
	ds_bpermute_b32 v94, v94, v89
	s_and_saveexec_b64 s[24:25], s[2:3]
	s_cbranch_execz .LBB0_596
	s_waitcnt lgkmcnt(2)
	v_pk_mul_f32 v[92:93], v[170:171], v[92:93]
	v_mov_b32_e32 v100, v83
	v_mov_b32_e32 v101, v85
	v_mov_b32_e32 v96, v82
	v_mov_b32_e32 v97, v84
	v_pk_mul_f32 v[92:93], v[100:101], v[92:93]
	v_mul_f32_e32 v88, v88, v78
	v_pk_fma_f32 v[86:87], v[86:87], v[96:97], v[92:93]
	s_waitcnt lgkmcnt(1)
	v_mul_f32_e32 v92, v170, v95
	s_waitcnt lgkmcnt(0)
	v_mul_f32_e32 v95, v170, v94
	v_mov_b32_e32 v96, v89
	v_mov_b32_e32 v97, v81
	v_mov_b32_e32 v94, v80
	v_pk_mul_f32 v[94:95], v[96:97], v[94:95]
	v_mul_f32_e32 v92, v79, v92
	v_mov_b32_e32 v89, v94
	v_mov_b32_e32 v93, v95
	v_pk_add_f32 v[88:89], v[88:89], v[92:93]

.LBB0_601:
	s_waitcnt lgkmcnt(3)
	v_mul_f32_e32 v74, v209, v211
	v_cvt_pk_bf16_f32 v86, v86, v87
	v_cvt_pk_bf16_f32 v87, v88, v89
	v_cvt_pk_bf16_f32 v88, v76, v77
	v_cvt_pk_bf16_f32 v89, v92, v93
	s_waitcnt lgkmcnt(2)
	v_pk_mul_f32 v[64:65], v[64:65], v[74:75] op_sel_hi:[1,0]
	s_and_b64 vcc, exec, s[6:7]
	v_pk_mul_f32 v[62:63], v[62:63], v[74:75] op_sel_hi:[1,0]
	v_lshl_add_u64 v[90:91], v[90:91], 0, s[100:101]
	global_store_dwordx4 v[90:91], v[86:89], off sc1
	s_cbranch_vccnz .LBB0_605
	v_and_b32_e32 v76, 64, v238
	v_xor_b32_e32 v75, 16, v238
	v_add_u32_e32 v76, 64, v76
	v_cmp_lt_i32_e32 vcc, v75, v76
	s_nop 1
	v_cndmask_b32_e32 v75, v238, v75, vcc
	v_lshlrev_b32_e32 v75, 2, v75
	ds_bpermute_b32 v76, v75, v62
	ds_bpermute_b32 v77, v75, v63
	ds_bpermute_b32 v86, v75, v64
	ds_bpermute_b32 v75, v75, v65
	s_and_saveexec_b64 s[24:25], s[2:3]
	s_cbranch_execz .LBB0_604
	s_waitcnt lgkmcnt(2)
	v_pk_mul_f32 v[76:77], v[170:171], v[76:77]
	v_mov_b32_e32 v90, v55
	v_mov_b32_e32 v91, v57
	v_mov_b32_e32 v88, v54
	v_mov_b32_e32 v89, v56
	v_pk_mul_f32 v[76:77], v[90:91], v[76:77]
	s_waitcnt lgkmcnt(0)
	v_mul_f32_e32 v87, v170, v75
	v_pk_fma_f32 v[62:63], v[62:63], v[88:89], v[76:77]
	v_mul_f32_e32 v76, v170, v86
	v_mov_b32_e32 v88, v65
	v_mov_b32_e32 v89, v53
	v_mov_b32_e32 v86, v52
	v_pk_mul_f32 v[86:87], v[88:89], v[86:87]
	v_mul_f32_e32 v64, v64, v50
	v_mul_f32_e32 v76, v51, v76
	v_mov_b32_e32 v65, v86
	v_mov_b32_e32 v77, v87
	v_pk_add_f32 v[64:65], v[64:65], v[76:77]

.LBB0_609:
	s_waitcnt lgkmcnt(3)
	v_add_u32_e32 v86, 0x90, v176
	s_waitcnt lgkmcnt(2)
	v_ashrrev_i32_e32 v87, 31, v86
	v_mov_b64_e32 v[86:87], 0x4100
	v_cvt_pk_bf16_f32 v62, v62, v63
	v_cvt_pk_bf16_f32 v63, v64, v65
	v_cvt_pk_bf16_f32 v64, v58, v59
	v_lshl_add_u64 v[58:59], s[98:99], 0, v[86:87]
	v_cvt_pk_bf16_f32 v65, v60, v61
	v_lshl_add_u64 v[58:59], v[154:155], 1, v[58:59]
	v_pk_mul_f32 v[48:49], v[48:49], v[76:77]
	s_and_b64 vcc, exec, s[6:7]
	v_pk_mul_f32 v[46:47], v[46:47], v[74:75]
	global_store_dwordx4 v[58:59], v[62:65], off sc1
	s_cbranch_vccnz .LBB0_613
	v_and_b32_e32 v61, 64, v238
	v_xor_b32_e32 v60, 16, v238
	v_add_u32_e32 v61, 64, v61
	v_cmp_lt_i32_e32 vcc, v60, v61
	s_nop 1
	v_cndmask_b32_e32 v60, v238, v60, vcc
	v_lshlrev_b32_e32 v62, 2, v60
	ds_bpermute_b32 v60, v62, v46
	ds_bpermute_b32 v61, v62, v47
	ds_bpermute_b32 v63, v62, v48
	ds_bpermute_b32 v62, v62, v49
	s_and_saveexec_b64 s[24:25], s[2:3]
	s_cbranch_execz .LBB0_612
	s_waitcnt lgkmcnt(2)
	v_pk_mul_f32 v[60:61], v[170:171], v[60:61]
	v_mov_b32_e32 v76, v55
	v_mov_b32_e32 v77, v57
	v_mov_b32_e32 v64, v54
	v_mov_b32_e32 v65, v56
	v_pk_mul_f32 v[60:61], v[76:77], v[60:61]
	v_mul_f32_e32 v48, v48, v50
	v_pk_fma_f32 v[46:47], v[46:47], v[64:65], v[60:61]
	s_waitcnt lgkmcnt(1)
	v_mul_f32_e32 v60, v170, v63
	s_waitcnt lgkmcnt(0)
	v_mul_f32_e32 v63, v170, v62
	v_mov_b32_e32 v64, v49
	v_mov_b32_e32 v65, v53
	v_mov_b32_e32 v62, v52
	v_pk_mul_f32 v[62:63], v[64:65], v[62:63]
	v_mul_f32_e32 v60, v51, v60
	v_mov_b32_e32 v49, v62
	v_mov_b32_e32 v61, v63
	v_pk_add_f32 v[48:49], v[48:49], v[60:61]

.LBB0_617:
	v_cvt_pk_bf16_f32 v46, v46, v47
	v_cvt_pk_bf16_f32 v47, v48, v49
	v_cvt_pk_bf16_f32 v48, v34, v35
	v_cvt_pk_bf16_f32 v49, v36, v37
	s_and_b64 vcc, exec, s[6:7]
	v_lshl_add_u64 v[58:59], v[58:59], 0, s[100:101]
	global_store_dwordx4 v[58:59], v[46:49], off sc1
	s_cbranch_vccnz .LBB0_619
	s_add_i32 s26, s26, s47
	s_and_b32 s24, s26, 0xfc0
	v_or_b32_e32 v34, s24, v188
	v_or_b32_e32 v35, 32, v34
	v_lshlrev_b32_e32 v36, s30, v35
	v_and_b32_e32 v36, 0xfff, v36
	v_lshrrev_b32_e32 v35, s37, v35
	v_add_lshl_u32 v35, v36, v35, 6
	v_or_b32_e32 v34, 48, v34
	global_load_dwordx4 v[66:69], v35, s[0:1] offset:48
	global_load_dwordx4 v[70:73], v35, s[0:1] offset:32
	global_load_dwordx4 v[78:81], v35, s[0:1] offset:16
	global_load_dwordx4 v[82:85], v35, s[0:1]
	v_lshlrev_b32_e32 v35, s30, v34
	v_and_b32_e32 v35, 0xfff, v35
	v_lshrrev_b32_e32 v34, s37, v34
	v_add_lshl_u32 v34, v35, v34, 6
	global_load_dwordx4 v[38:41], v34, s[0:1] offset:48
	global_load_dwordx4 v[42:45], v34, s[0:1] offset:32
	global_load_dwordx4 v[50:53], v34, s[0:1] offset:16
	global_load_dwordx4 v[54:57], v34, s[0:1]
	s_waitcnt vmcnt(0)

.LBB0_627:
	s_waitcnt lgkmcnt(3)
	v_add_u32_e32 v46, 0xa0, v176
	s_waitcnt lgkmcnt(2)
	v_ashrrev_i32_e32 v47, 31, v46
	v_mov_b64_e32 v[46:47], 0x5000
	v_cvt_pk_bf16_f32 v30, v30, v31
	v_cvt_pk_bf16_f32 v31, v32, v33
	v_cvt_pk_bf16_f32 v32, v26, v27
	v_lshl_add_u64 v[26:27], s[98:99], 0, v[46:47]
	v_cvt_pk_bf16_f32 v33, v28, v29
	v_lshl_add_u64 v[26:27], v[154:155], 1, v[26:27]
	v_pk_mul_f32 v[24:25], v[24:25], v[36:37]
	s_and_b64 vcc, exec, s[6:7]
	v_pk_mul_f32 v[22:23], v[22:23], v[34:35]
	global_store_dwordx4 v[26:27], v[30:33], off sc1
	s_cbranch_vccnz .LBB0_631
	v_and_b32_e32 v29, 64, v238
	v_xor_b32_e32 v28, 16, v238
	v_add_u32_e32 v29, 64, v29
	v_cmp_lt_i32_e32 vcc, v28, v29
	s_nop 1
	v_cndmask_b32_e32 v28, v238, v28, vcc
	v_lshlrev_b32_e32 v30, 2, v28
	ds_bpermute_b32 v28, v30, v22
	ds_bpermute_b32 v29, v30, v23
	ds_bpermute_b32 v31, v30, v24
	ds_bpermute_b32 v30, v30, v25
	s_and_saveexec_b64 s[24:25], s[2:3]
	s_cbranch_execz .LBB0_630
	v_mov_b32_e32 v33, v84
	s_waitcnt lgkmcnt(2)
	v_pk_mul_f32 v[28:29], v[170:171], v[28:29]
	v_mov_b32_e32 v84, v83
	v_mov_b32_e32 v32, v82
	v_pk_mul_f32 v[28:29], v[84:85], v[28:29]
	v_mul_f32_e32 v24, v24, v78
	v_pk_fma_f32 v[22:23], v[22:23], v[32:33], v[28:29]
	s_waitcnt lgkmcnt(0)
	v_mul_f32_e32 v29, v170, v30
	v_mul_f32_e32 v28, v170, v31
	v_mov_b32_e32 v30, v25
	v_mov_b32_e32 v31, v81
	v_mov_b32_e32 v81, v29
	v_pk_mul_f32 v[30:31], v[30:31], v[80:81]
	v_mul_f32_e32 v28, v79, v28
	v_mov_b32_e32 v25, v30
	v_mov_b32_e32 v29, v31
	v_pk_add_f32 v[24:25], v[24:25], v[28:29]

.LBB0_635:
	s_waitcnt lgkmcnt(3)
	v_mul_f32_e32 v18, v209, v208
	v_cvt_pk_bf16_f32 v22, v22, v23
	v_cvt_pk_bf16_f32 v23, v24, v25
	v_cvt_pk_bf16_f32 v24, v20, v21
	v_cvt_pk_bf16_f32 v25, v28, v29
	s_waitcnt lgkmcnt(2)
	v_pk_mul_f32 v[16:17], v[16:17], v[18:19] op_sel_hi:[1,0]
	s_and_b64 vcc, exec, s[6:7]
	v_pk_mul_f32 v[14:15], v[14:15], v[18:19] op_sel_hi:[1,0]
	v_lshl_add_u64 v[26:27], v[26:27], 0, s[100:101]
	global_store_dwordx4 v[26:27], v[22:25], off sc1
	s_cbranch_vccnz .LBB0_639
	v_and_b32_e32 v20, 64, v238
	v_xor_b32_e32 v19, 16, v238
	v_add_u32_e32 v20, 64, v20
	v_cmp_lt_i32_e32 vcc, v19, v20
	s_nop 1
	v_cndmask_b32_e32 v19, v238, v19, vcc
	v_lshlrev_b32_e32 v19, 2, v19
	ds_bpermute_b32 v20, v19, v14
	ds_bpermute_b32 v21, v19, v15
	ds_bpermute_b32 v22, v19, v16
	ds_bpermute_b32 v19, v19, v17
	s_and_saveexec_b64 s[24:25], s[2:3]
	s_cbranch_execz .LBB0_638
	s_waitcnt lgkmcnt(2)
	v_pk_mul_f32 v[20:21], v[170:171], v[20:21]
	v_mov_b32_e32 v26, v55
	v_mov_b32_e32 v27, v57
	v_mov_b32_e32 v24, v54
	v_mov_b32_e32 v25, v56
	v_pk_mul_f32 v[20:21], v[26:27], v[20:21]
	s_waitcnt lgkmcnt(0)
	v_mul_f32_e32 v23, v170, v19
	v_pk_fma_f32 v[14:15], v[14:15], v[24:25], v[20:21]
	v_mul_f32_e32 v20, v170, v22
	v_mov_b32_e32 v24, v17
	v_mov_b32_e32 v25, v53
	v_mov_b32_e32 v22, v52
	v_pk_mul_f32 v[22:23], v[24:25], v[22:23]
	v_mul_f32_e32 v16, v16, v50
	v_mul_f32_e32 v20, v51, v20
	v_mov_b32_e32 v17, v22
	v_mov_b32_e32 v21, v23
	v_pk_add_f32 v[16:17], v[16:17], v[20:21]

.LBB0_643:
	s_waitcnt lgkmcnt(3)
	v_add_u32_e32 v22, 0xb0, v176
	s_waitcnt lgkmcnt(2)
	v_ashrrev_i32_e32 v23, 31, v22
	v_mov_b64_e32 v[22:23], 0x5100
	v_cvt_pk_bf16_f32 v14, v14, v15
	v_cvt_pk_bf16_f32 v15, v16, v17
	v_cvt_pk_bf16_f32 v16, v10, v11
	v_lshl_add_u64 v[10:11], s[98:99], 0, v[22:23]
	v_cvt_pk_bf16_f32 v17, v12, v13
	v_lshl_add_u64 v[10:11], v[154:155], 1, v[10:11]
	v_pk_mul_f32 v[8:9], v[8:9], v[20:21]
	s_and_b64 vcc, exec, s[6:7]
	v_pk_mul_f32 v[6:7], v[6:7], v[18:19]
	global_store_dwordx4 v[10:11], v[14:17], off sc1
	s_cbranch_vccnz .LBB0_647
	v_and_b32_e32 v13, 64, v238
	v_xor_b32_e32 v12, 16, v238
	v_add_u32_e32 v13, 64, v13
	v_cmp_lt_i32_e32 vcc, v12, v13
	s_nop 1
	v_cndmask_b32_e32 v12, v238, v12, vcc
	v_lshlrev_b32_e32 v14, 2, v12
	ds_bpermute_b32 v12, v14, v6
	ds_bpermute_b32 v13, v14, v7
	ds_bpermute_b32 v15, v14, v8
	ds_bpermute_b32 v14, v14, v9
	s_and_saveexec_b64 s[24:25], s[2:3]
	s_cbranch_execz .LBB0_646
	v_mov_b32_e32 v17, v56
	s_waitcnt lgkmcnt(2)
	v_pk_mul_f32 v[12:13], v[170:171], v[12:13]
	v_mov_b32_e32 v56, v55
	v_mov_b32_e32 v16, v54
	v_pk_mul_f32 v[12:13], v[56:57], v[12:13]
	v_mul_f32_e32 v8, v8, v50
	v_pk_fma_f32 v[6:7], v[6:7], v[16:17], v[12:13]
	s_waitcnt lgkmcnt(0)
	v_mul_f32_e32 v13, v170, v14
	v_mul_f32_e32 v12, v170, v15
	v_mov_b32_e32 v14, v9
	v_mov_b32_e32 v15, v53
	v_mov_b32_e32 v53, v13
	v_pk_mul_f32 v[14:15], v[14:15], v[52:53]
	v_mul_f32_e32 v12, v51, v12
	v_mov_b32_e32 v9, v14
	v_mov_b32_e32 v13, v15
	v_pk_add_f32 v[8:9], v[8:9], v[12:13]

.LBB0_651:
	v_cvt_pk_bf16_f32 v6, v6, v7
	v_cvt_pk_bf16_f32 v7, v8, v9
	v_cvt_pk_bf16_f32 v8, v2, v3
	v_cvt_pk_bf16_f32 v9, v4, v5
	s_and_b64 vcc, exec, s[4:5]
	s_mov_b64 s[4:5], -1
	v_lshl_add_u64 v[10:11], v[10:11], 0, s[100:101]
	global_store_dwordx4 v[10:11], v[6:9], off sc1
	s_cbranch_vccnz .LBB0_502
	s_andn2_b64 vcc, exec, s[14:15]
	s_cbranch_vccnz .LBB0_501
	s_barrier
	s_branch .LBB0_501

.LBB0_677:
	s_lshr_b32 s98, s39, 4
	s_lshl_b32 s98, s98, 4
	s_lshl_b32 s99, s40, 2
	s_add_i32 s98, s98, s99
	s_lshr_b32 s99, s71, 2
	s_add_i32 s98, s98, s99
	s_lshl_b32 s98, s98, 19
	s_and_b32 s99, s39, 15
	s_lshl_b32 s99, s99, 15
	s_add_i32 s98, s98, s99
	s_add_u32 s98, s0, s98
	s_addc_u32 s99, s1, 0
	s_mov_b32 s100, 0x4000
	s_mov_b32 s101, 0
	s_lshl_b32 s4, s39, 8
	v_or_b32_e32 v122, s4, v154
	v_ashrrev_i32_e32 v123, 31, v122
	v_lshl_add_u64 v[148:149], v[122:123], 2, s[8:9]
	global_load_dwordx4 v[122:125], v[148:149], off offset:16
	global_load_dwordx4 v[134:137], v[148:149], off
	s_lshl_b32 s5, s39, 6
	v_bitop3_b32 v155, s4, v241, v154 bitop3:0xc8
	s_lshl_b32 s4, s40, 8
	s_and_b32 s5, s5, 0xfffffc00
	s_add_i32 s5, s5, s4
	v_add_u32_e32 v150, s5, v152
	v_ashrrev_i32_e32 v151, 31, v150
	v_mov_b64_e32 v[156:157], 0
	v_lshl_add_u64 v[156:157], s[98:99], 0, v[156:157]
	s_mov_b64 s[4:5], -1
	s_and_b64 vcc, exec, s[2:3]
	s_waitcnt vmcnt(0)
	v_pk_mul_f32 v[158:159], v[128:129], v[124:125]
	v_pk_mul_f32 v[132:133], v[132:133], v[136:137]
	v_pk_mul_f32 v[130:131], v[130:131], v[134:135]
	v_pk_mul_f32 v[160:161], v[126:127], v[122:123]
	v_and_b32_e32 v126, 0xffffffe0, v154
	v_lshlrev_b32_e32 v126, 7, v126
	v_and_b32_e32 v127, 31, v154
	v_lshl_add_u32 v126, v127, 6, v126
	v_and_b32_e32 v127, 15, v152
	v_lshl_add_u32 v126, v127, 4, v126
	v_mov_b32_e32 v127, v0
	v_lshl_add_u64 v[128:129], v[156:157], 0, v[126:127]
	v_cvt_pk_bf16_f32 v130, v130, v131
	v_cvt_pk_bf16_f32 v131, v132, v133
	v_cvt_pk_bf16_f32 v132, v160, v161
	v_cvt_pk_bf16_f32 v133, v158, v159
	global_store_dwordx4 v[128:129], v[130:133], off sc1
	v_pk_mul_f32 v[120:121], v[120:121], v[136:137]
	v_pk_mul_f32 v[118:119], v[118:119], v[134:135]
	v_or_b32_e32 v130, 16, v150
	v_ashrrev_i32_e32 v131, 31, v130
	v_mov_b64_e32 v[130:131], 0x100
	v_lshl_add_u64 v[130:131], s[98:99], 0, v[130:131]
	v_pk_mul_f32 v[132:133], v[116:117], v[124:125]
	v_pk_mul_f32 v[156:157], v[114:115], v[122:123]
	v_lshl_add_u64 v[114:115], v[130:131], 0, v[126:127]
	v_cvt_pk_bf16_f32 v116, v118, v119
	v_cvt_pk_bf16_f32 v117, v120, v121
	v_cvt_pk_bf16_f32 v118, v156, v157
	v_cvt_pk_bf16_f32 v119, v132, v133
	global_store_dwordx4 v[114:115], v[116:119], off sc1
	v_pk_mul_f32 v[112:113], v[112:113], v[136:137]
	v_pk_mul_f32 v[110:111], v[110:111], v[134:135]
	v_or_b32_e32 v116, 32, v150
	v_ashrrev_i32_e32 v117, 31, v116
	v_mov_b64_e32 v[116:117], 0x800
	v_lshl_add_u64 v[116:117], s[98:99], 0, v[116:117]
	v_pk_mul_f32 v[118:119], v[108:109], v[124:125]
	v_pk_mul_f32 v[120:121], v[106:107], v[122:123]
	v_lshl_add_u64 v[106:107], v[116:117], 0, v[126:127]
	v_cvt_pk_bf16_f32 v108, v110, v111
	v_cvt_pk_bf16_f32 v109, v112, v113
	v_cvt_pk_bf16_f32 v110, v120, v121
	v_cvt_pk_bf16_f32 v111, v118, v119
	global_store_dwordx4 v[106:107], v[108:111], off sc1
	v_pk_mul_f32 v[104:105], v[104:105], v[136:137]
	v_pk_mul_f32 v[102:103], v[102:103], v[134:135]
	v_or_b32_e32 v108, 48, v150
	v_ashrrev_i32_e32 v109, 31, v108
	v_mov_b64_e32 v[108:109], 0x900
	v_lshl_add_u64 v[108:109], s[98:99], 0, v[108:109]
	v_pk_mul_f32 v[110:111], v[100:101], v[124:125]
	v_pk_mul_f32 v[112:113], v[98:99], v[122:123]
	v_lshl_add_u64 v[98:99], v[108:109], 0, v[126:127]
	v_cvt_pk_bf16_f32 v100, v102, v103
	v_cvt_pk_bf16_f32 v101, v104, v105
	v_cvt_pk_bf16_f32 v102, v112, v113
	v_cvt_pk_bf16_f32 v103, v110, v111
	global_store_dwordx4 v[98:99], v[100:103], off sc1
	v_pk_mul_f32 v[96:97], v[96:97], v[136:137]
	v_pk_mul_f32 v[94:95], v[94:95], v[134:135]
	v_add_u32_e32 v100, 0x80, v150
	v_ashrrev_i32_e32 v101, 31, v100
	v_mov_b64_e32 v[100:101], 0x100000
	v_lshl_add_u64 v[100:101], s[98:99], 0, v[100:101]
	v_pk_mul_f32 v[102:103], v[92:93], v[124:125]
	v_pk_mul_f32 v[104:105], v[90:91], v[122:123]
	v_lshl_add_u64 v[90:91], v[100:101], 0, v[126:127]
	v_cvt_pk_bf16_f32 v92, v94, v95
	v_cvt_pk_bf16_f32 v93, v96, v97
	v_cvt_pk_bf16_f32 v94, v104, v105
	v_cvt_pk_bf16_f32 v95, v102, v103
	global_store_dwordx4 v[90:91], v[92:95], off sc1
	v_pk_mul_f32 v[88:89], v[88:89], v[136:137]
	v_pk_mul_f32 v[86:87], v[86:87], v[134:135]
	v_add_u32_e32 v92, 0x90, v150
	v_ashrrev_i32_e32 v93, 31, v92
	v_mov_b64_e32 v[92:93], 0x100100
	v_lshl_add_u64 v[92:93], s[98:99], 0, v[92:93]
	v_pk_mul_f32 v[94:95], v[84:85], v[124:125]
	v_pk_mul_f32 v[96:97], v[82:83], v[122:123]
	v_lshl_add_u64 v[82:83], v[92:93], 0, v[126:127]
	v_cvt_pk_bf16_f32 v84, v86, v87
	v_cvt_pk_bf16_f32 v85, v88, v89
	v_cvt_pk_bf16_f32 v86, v96, v97
	v_cvt_pk_bf16_f32 v87, v94, v95
	global_store_dwordx4 v[82:83], v[84:87], off sc1
	v_pk_mul_f32 v[80:81], v[80:81], v[136:137]
	v_pk_mul_f32 v[78:79], v[78:79], v[134:135]
	v_add_u32_e32 v84, 0xa0, v150
	v_ashrrev_i32_e32 v85, 31, v84
	v_pk_mul_f32 v[72:73], v[72:73], v[124:125]
	v_mov_b64_e32 v[84:85], 0x100800
	v_cvt_pk_bf16_f32 v78, v78, v79
	v_cvt_pk_bf16_f32 v79, v80, v81
	v_cvt_pk_bf16_f32 v81, v72, v73
	v_add_u32_e32 v72, 0xb0, v150
	v_lshl_add_u64 v[84:85], s[98:99], 0, v[84:85]
	v_pk_mul_f32 v[86:87], v[70:71], v[122:123]
	v_ashrrev_i32_e32 v73, 31, v72
	v_lshl_add_u64 v[70:71], v[84:85], 0, v[126:127]
	v_cvt_pk_bf16_f32 v80, v86, v87
	v_mov_b64_e32 v[72:73], 0x100900
	global_store_dwordx4 v[70:71], v[78:81], off sc1
	v_lshl_add_u64 v[72:73], s[98:99], 0, v[72:73]
	v_pk_mul_f32 v[64:65], v[64:65], v[136:137]
	v_pk_mul_f32 v[62:63], v[62:63], v[134:135]
	v_pk_mul_f32 v[78:79], v[60:61], v[124:125]
	v_pk_mul_f32 v[60:61], v[58:59], v[122:123]
	v_lshl_add_u64 v[72:73], v[72:73], 0, v[126:127]
	v_cvt_pk_bf16_f32 v58, v62, v63
	v_cvt_pk_bf16_f32 v59, v64, v65
	v_cvt_pk_bf16_f32 v60, v60, v61
	v_cvt_pk_bf16_f32 v61, v78, v79
	global_store_dwordx4 v[72:73], v[58:61], off sc1
	global_load_dwordx4 v[58:61], v[148:149], off offset:528
	s_nop 0
	global_load_dwordx4 v[62:65], v[148:149], off offset:512
	s_waitcnt vmcnt(1)
	v_pk_mul_f32 v[78:79], v[68:69], v[60:61]
	s_waitcnt vmcnt(0)
	v_pk_mul_f32 v[76:77], v[76:77], v[64:65]
	v_pk_mul_f32 v[74:75], v[74:75], v[62:63]
	v_pk_mul_f32 v[68:69], v[66:67], v[58:59]
	v_cvt_pk_bf16_f32 v66, v74, v75
	v_cvt_pk_bf16_f32 v67, v76, v77
	v_cvt_pk_bf16_f32 v68, v68, v69
	v_cvt_pk_bf16_f32 v69, v78, v79
	v_lshl_add_u64 v[128:129], v[128:129], 0, s[100:101]
	global_store_dwordx4 v[128:129], v[66:69], off sc1
	v_pk_mul_f32 v[56:57], v[56:57], v[64:65]
	v_pk_mul_f32 v[54:55], v[54:55], v[62:63]
	v_pk_mul_f32 v[66:67], v[52:53], v[60:61]
	v_pk_mul_f32 v[52:53], v[50:51], v[58:59]
	v_cvt_pk_bf16_f32 v50, v54, v55
	v_cvt_pk_bf16_f32 v51, v56, v57
	v_cvt_pk_bf16_f32 v52, v52, v53
	v_cvt_pk_bf16_f32 v53, v66, v67
	v_lshl_add_u64 v[114:115], v[114:115], 0, s[100:101]
	global_store_dwordx4 v[114:115], v[50:53], off sc1
	v_pk_mul_f32 v[48:49], v[48:49], v[64:65]
	v_pk_mul_f32 v[46:47], v[46:47], v[62:63]
	v_pk_mul_f32 v[50:51], v[44:45], v[60:61]
	v_pk_mul_f32 v[44:45], v[42:43], v[58:59]
	v_cvt_pk_bf16_f32 v42, v46, v47
	v_cvt_pk_bf16_f32 v43, v48, v49
	v_cvt_pk_bf16_f32 v44, v44, v45
	v_cvt_pk_bf16_f32 v45, v50, v51
	v_lshl_add_u64 v[106:107], v[106:107], 0, s[100:101]
	global_store_dwordx4 v[106:107], v[42:45], off sc1
	v_pk_mul_f32 v[40:41], v[40:41], v[64:65]
	v_pk_mul_f32 v[38:39], v[38:39], v[62:63]
	v_pk_mul_f32 v[42:43], v[36:37], v[60:61]
	v_pk_mul_f32 v[36:37], v[34:35], v[58:59]
	v_cvt_pk_bf16_f32 v34, v38, v39
	v_cvt_pk_bf16_f32 v35, v40, v41
	v_cvt_pk_bf16_f32 v36, v36, v37
	v_cvt_pk_bf16_f32 v37, v42, v43
	v_lshl_add_u64 v[98:99], v[98:99], 0, s[100:101]
	global_store_dwordx4 v[98:99], v[34:37], off sc1
	v_pk_mul_f32 v[32:33], v[32:33], v[64:65]
	v_pk_mul_f32 v[30:31], v[30:31], v[62:63]
	v_pk_mul_f32 v[34:35], v[28:29], v[60:61]
	v_pk_mul_f32 v[28:29], v[26:27], v[58:59]
	v_cvt_pk_bf16_f32 v26, v30, v31
	v_cvt_pk_bf16_f32 v27, v32, v33
	v_cvt_pk_bf16_f32 v28, v28, v29
	v_cvt_pk_bf16_f32 v29, v34, v35
	v_lshl_add_u64 v[90:91], v[90:91], 0, s[100:101]
	global_store_dwordx4 v[90:91], v[26:29], off sc1
	v_pk_mul_f32 v[24:25], v[24:25], v[64:65]
	v_pk_mul_f32 v[22:23], v[22:23], v[62:63]
	v_pk_mul_f32 v[26:27], v[20:21], v[60:61]
	v_pk_mul_f32 v[20:21], v[18:19], v[58:59]
	v_cvt_pk_bf16_f32 v18, v22, v23
	v_cvt_pk_bf16_f32 v19, v24, v25
	v_cvt_pk_bf16_f32 v20, v20, v21
	v_cvt_pk_bf16_f32 v21, v26, v27
	v_lshl_add_u64 v[82:83], v[82:83], 0, s[100:101]
	global_store_dwordx4 v[82:83], v[18:21], off sc1
	v_pk_mul_f32 v[16:17], v[16:17], v[64:65]
	v_pk_mul_f32 v[14:15], v[14:15], v[62:63]
	v_pk_mul_f32 v[18:19], v[12:13], v[60:61]
	v_pk_mul_f32 v[12:13], v[10:11], v[58:59]
	v_cvt_pk_bf16_f32 v10, v14, v15
	v_cvt_pk_bf16_f32 v11, v16, v17
	v_cvt_pk_bf16_f32 v12, v12, v13
	v_cvt_pk_bf16_f32 v13, v18, v19
	v_lshl_add_u64 v[70:71], v[70:71], 0, s[100:101]
	global_store_dwordx4 v[70:71], v[10:13], off sc1
	v_pk_mul_f32 v[8:9], v[8:9], v[64:65]
	v_pk_mul_f32 v[6:7], v[6:7], v[62:63]
	v_pk_mul_f32 v[10:11], v[4:5], v[60:61]
	v_pk_mul_f32 v[4:5], v[2:3], v[58:59]
	v_cvt_pk_bf16_f32 v2, v6, v7
	v_cvt_pk_bf16_f32 v3, v8, v9
	v_cvt_pk_bf16_f32 v4, v4, v5
	v_cvt_pk_bf16_f32 v5, v10, v11
	v_lshl_add_u64 v[72:73], v[72:73], 0, s[100:101]
	global_store_dwordx4 v[72:73], v[2:5], off sc1
	s_cbranch_vccnz .LBB0_664
	s_andn2_b64 vcc, exec, s[6:7]
	s_cbranch_vccnz .LBB0_663
	s_barrier
	s_branch .LBB0_663
